# store cache policy: all phase-output global stores agent-scope write-through (sc1) so the grid barrier's L2 writeback finds no dirty lines
# baseline (speedup 1.0000x reference)
; __global__ void __launch_bounds__(512, 2) mk_fwd(Params p) {
;     ...
;         for (int i = blockIdx.x * 512 + threadIdx.x; i < 192 * 32; i += gridDim.x * 512) {
;             const int pos = i >> 5, f = i & 31; const float pv = (float)(pos < 128 ? pos : pos - 128);
;             float sn_, cs_; sincos_acc(pv * INV_FREQ[f], sn_, cs_); RCOS0[i] = cs_; RSIN0[i] = sn_;
;         }
.LBB0_10:
	s_or_b64 exec, exec, s[24:25]
	v_ashrrev_i32_e32 v3, 31, v2
	v_cvt_f32_f64_e32 v28, v[24:25]
	v_lshlrev_b64 v[24:25], 2, v[2:3]
	v_add_u32_e32 v2, s27, v2
	v_cmp_lt_i32_e32 vcc, s29, v2
	v_cvt_f32_f64_e32 v29, v[26:27]
	v_lshl_add_u64 v[26:27], s[10:11], 0, v[24:25]
	v_lshl_add_u64 v[24:25], s[12:13], 0, v[24:25]
	s_or_b64 s[14:15], vcc, s[14:15]
	global_store_dword v[26:27], v29, off sc1
	global_store_dword v[24:25], v28, off sc1
	s_andn2_b64 exec, exec, s[14:15]
	s_cbranch_execz .LBB0_14

; __device__ __forceinline__ float bflo(unsigned w) { return __uint_as_float(w << 16); }
; __device__ __forceinline__ float bfhi(unsigned w) { return __uint_as_float(w & 0xffff0000u); }
; __device__ __forceinline__ void gate_row(int m, int lane, const bf16_t* __restrict__ YA, const bf16_t* __restrict__ YB, const float* __restrict__ LSE, const bf16_t* __restrict__ PROJ, ...
;     v4u a[2], b0[2], b1[2], b2[2], ga[2], gb[2]; float l0[2], l1[2], l2[2];
; #pragma unroll
;     for (int j = 0; j < 2; ++j) { const int c = lane + 64 * j, hh = c >> 4;
;         a[j] = *(const v4u*)(YA + (size_t)m * DA + 8 * c);
;         b0[j] = *(const v4u*)(YB + ((size_t)0 * M + m) * DB + 8 * c); b1[j] = *(const v4u*)(YB + ((size_t)1 * M + m) * DB + 8 * c); b2[j] = *(const v4u*)(YB + ((size_t)2 * M + m) * DB + 8 * c);
;         l0[j] = LSE[((size_t)0 * M + m) * 8 + hh]; l1[j] = LSE[((size_t)1 * M + m) * 8 + hh]; l2[j] = LSE[((size_t)2 * M + m) * 8 + hh];
;         ga[j] = *(const v4u*)(PROJ + ((size_t)(H_GA + (c >> 4)) * M + m) * HD + 8 * (c & 15)); gb[j] = *(const v4u*)(PROJ + ((size_t)(H_GB + (c >> 4)) * M + m) * HD + 8 * (c & 15)); }
;     float ya[2][8], yb[2][8]; float ssa = 0.f, ssb = 0.f;
; #pragma unroll
;     for (int j = 0; j < 2; ++j) {
;         ya[j][0] = bflo(a[j].x); ya[j][1] = bfhi(a[j].x); ya[j][2] = bflo(a[j].y); ya[j][3] = bfhi(a[j].y); ya[j][4] = bflo(a[j].z); ya[j][5] = bfhi(a[j].z); ya[j][6] = bflo(a[j].w); ya[j][7] = bfhi(a[j].w);
;         const float mx = fmaxf(l0[j], fmaxf(l1[j], l2[j])); const float e0 = __builtin_amdgcn_exp2f(l0[j] - mx), e1 = __builtin_amdgcn_exp2f(l1[j] - mx), e2 = __builtin_amdgcn_exp2f(l2[j] - mx);
;         const float inv = __builtin_amdgcn_rcpf(e0 + e1 + e2); const float w0 = e0 * inv, w1 = e1 * inv, w2 = e2 * inv;
;         yb[j][0] = w0 * bflo(b0[j].x) + w1 * bflo(b1[j].x) + w2 * bflo(b2[j].x); yb[j][1] = w0 * bfhi(b0[j].x) + w1 * bfhi(b1[j].x) + w2 * bfhi(b2[j].x);
;         yb[j][2] = w0 * bflo(b0[j].y) + w1 * bflo(b1[j].y) + w2 * bflo(b2[j].y); yb[j][3] = w0 * bfhi(b0[j].y) + w1 * bfhi(b1[j].y) + w2 * bfhi(b2[j].y);
;         yb[j][4] = w0 * bflo(b0[j].z) + w1 * bflo(b1[j].z) + w2 * bflo(b2[j].z); yb[j][5] = w0 * bfhi(b0[j].z) + w1 * bfhi(b1[j].z) + w2 * bfhi(b2[j].z);
.LBB0_41:
	v_lshl_add_u64 v[2:3], v[64:65], 0, s[28:29]
	v_add_co_u32_e32 v4, vcc, 0x19800000, v2
	s_mov_b32 s0, 0x21800000
	s_nop 0
	v_addc_co_u32_e32 v5, vcc, 0, v3, vcc
	v_add_co_u32_e32 v6, vcc, 0x1b800000, v2
	global_load_dwordx4 v[10:13], v[4:5], off
	s_nop 0
	v_addc_co_u32_e32 v7, vcc, 0, v3, vcc
	v_add_co_u32_e32 v8, vcc, 0x1d800000, v2
	global_load_dwordx4 v[38:41], v[6:7], off
	s_nop 0
	v_addc_co_u32_e32 v9, vcc, 0, v3, vcc
	v_add_co_u32_e32 v26, vcc, 0x1f800000, v2
	global_load_dwordx4 v[42:45], v[8:9], off
	s_nop 0
	v_addc_co_u32_e32 v27, vcc, 0, v3, vcc
	v_lshl_add_u64 v[2:3], v[72:73], 0, s[28:29]
	v_add_co_u32_e32 v14, vcc, 0x21800000, v2
	global_load_dwordx4 v[46:49], v[26:27], off
	s_nop 0
	v_addc_co_u32_e32 v15, vcc, 0, v3, vcc
	global_load_dword v76, v[14:15], off
	v_add_co_u32_e32 v14, vcc, 0x21880000, v2
	s_add_i32 s44, s26, s3
	s_nop 0
	v_addc_co_u32_e32 v15, vcc, 0, v3, vcc
	v_add_co_u32_e32 v2, vcc, 0x21900000, v2
	global_load_dword v78, v[14:15], off
	s_nop 0
	v_addc_co_u32_e32 v3, vcc, 0, v3, vcc
	global_load_dword v79, v[2:3], off
	v_lshl_add_u64 v[2:3], v[70:71], 0, s[28:29]
	v_add_co_u32_e32 v14, vcc, s33, v2
	s_cmpk_gt_i32 s44, 0x3fff
	s_nop 0
	v_addc_co_u32_e32 v15, vcc, 0, v3, vcc
	v_add_co_u32_e32 v2, vcc, 0x17800000, v2
	global_load_dwordx4 v[22:25], v[14:15], off
	s_nop 0
	v_addc_co_u32_e32 v3, vcc, 0, v3, vcc
	global_load_dwordx4 v[14:17], v[2:3], off
	s_nop 0
	global_load_dwordx4 v[2:5], v[4:5], off offset:1024
	s_nop 0
	global_load_dwordx4 v[18:21], v[6:7], off offset:1024
	global_load_dwordx4 v[34:37], v[8:9], off offset:1024
	global_load_dwordx4 v[30:33], v[26:27], off offset:1024
	v_lshl_add_u64 v[6:7], v[74:75], 0, s[28:29]
	v_add_co_u32_e32 v8, vcc, s0, v6
	s_mov_b32 s0, 0x21880000
	s_nop 0
	v_addc_co_u32_e32 v9, vcc, 0, v7, vcc
	global_load_dword v82, v[8:9], off
	v_add_co_u32_e32 v8, vcc, s0, v6
	s_mov_b32 s0, 0x21900000
	s_nop 0
	v_addc_co_u32_e32 v9, vcc, 0, v7, vcc
	v_add_co_u32_e32 v6, vcc, s0, v6
	global_load_dword v83, v[8:9], off
	s_nop 0
	v_addc_co_u32_e32 v7, vcc, 0, v7, vcc
	global_load_dword v87, v[6:7], off
	v_lshl_add_u64 v[26:27], v[68:69], 0, s[28:29]
	v_add_co_u32_e32 v6, vcc, s33, v26
	s_mov_b32 s0, 0x17800000
	s_nop 0
	v_addc_co_u32_e32 v7, vcc, 0, v27, vcc
	v_add_co_u32_e32 v26, vcc, s0, v26
	global_load_dwordx4 v[6:9], v[6:7], off
	s_nop 0
	v_addc_co_u32_e32 v27, vcc, 0, v27, vcc
	global_load_dwordx4 v[26:29], v[26:27], off
	s_waitcnt vmcnt(0)
	v_and_b32_e32 v93, 0xffff0000, v13
	v_lshlrev_b32_e32 v131, 16, v10
	v_and_b32_e32 v133, 0xffff0000, v10
	v_lshlrev_b32_e32 v109, 16, v11
	v_and_b32_e32 v123, 0xffff0000, v11
	v_lshlrev_b32_e32 v103, 16, v12
	s_waitcnt vmcnt(15)
	v_lshlrev_b32_e32 v84, 16, v43
	v_and_b32_e32 v85, 0xffff0000, v43
	v_lshlrev_b32_e32 v89, 16, v44
	v_and_b32_e32 v44, 0xffff0000, v44
	v_lshlrev_b32_e32 v90, 16, v45
	s_waitcnt vmcnt(11)
	v_max3_f32 v80, v76, v78, v79
	v_sub_f32_e32 v76, v76, v80
	v_exp_f32_e32 v77, v76
	v_sub_f32_e32 v76, v78, v80
	v_exp_f32_e32 v81, v76
	v_sub_f32_e32 v76, v79, v80
	v_exp_f32_e32 v76, v76
	v_lshlrev_b32_e32 v79, 16, v42
	v_add_f32_e32 v78, v77, v81
	v_and_b32_e32 v80, 0xffff0000, v42
	v_add_f32_e32 v78, v76, v78
	v_rcp_f32_e32 v78, v78
	s_waitcnt vmcnt(8)
	v_lshlrev_b32_e32 v111, 16, v3
	v_and_b32_e32 v119, 0xffff0000, v3
	v_lshlrev_b32_e32 v129, 16, v2
	v_pk_mul_f32 v[42:43], v[76:77], v[78:79] op_sel_hi:[1,0]
	v_lshlrev_b32_e32 v77, 16, v38
	v_lshlrev_b32_e32 v76, 16, v46
	v_mul_f32_e32 v88, v81, v78
	v_pk_mul_f32 v[76:77], v[42:43], v[76:77]
	v_and_b32_e32 v78, 0xffff0000, v46
	v_fma_f32 v77, v88, v79, v77
	v_and_b32_e32 v79, 0xffff0000, v38
	v_pk_mul_f32 v[78:79], v[42:43], v[78:79]
	v_lshlrev_b32_e32 v81, 16, v39
	v_fma_f32 v38, v88, v80, v79
	v_lshlrev_b32_e32 v80, 16, v47
	v_pk_mul_f32 v[80:81], v[42:43], v[80:81]
	v_add_f32_e32 v79, v78, v38
	v_fma_f32 v38, v88, v84, v81
	v_add_f32_e32 v86, v80, v38
	v_and_b32_e32 v39, 0xffff0000, v39
	v_and_b32_e32 v38, 0xffff0000, v47
	v_pk_mul_f32 v[38:39], v[42:43], v[38:39]
	s_waitcnt vmcnt(6)
	v_lshlrev_b32_e32 v46, 16, v35
	v_fma_f32 v39, v88, v85, v39
	v_add_f32_e32 v85, v38, v39
	v_lshlrev_b32_e32 v39, 16, v40
	v_lshlrev_b32_e32 v38, 16, v48
	v_pk_mul_f32 v[38:39], v[42:43], v[38:39]
	v_add_f32_e32 v77, v76, v77
	v_fma_f32 v39, v88, v89, v39
	v_add_f32_e32 v84, v38, v39
	v_and_b32_e32 v39, 0xffff0000, v40
	v_and_b32_e32 v38, 0xffff0000, v48
	v_pk_mul_f32 v[38:39], v[42:43], v[38:39]
	v_and_b32_e32 v40, 0xffff0000, v45
	v_fma_f32 v39, v88, v44, v39
	v_add_f32_e32 v47, v38, v39
	v_lshlrev_b32_e32 v39, 16, v41
	v_lshlrev_b32_e32 v38, 16, v49
	v_pk_mul_f32 v[38:39], v[42:43], v[38:39]
	v_lshlrev_b32_e32 v44, 16, v34
	v_fma_f32 v39, v88, v90, v39
	v_add_f32_e32 v92, v38, v39
	v_and_b32_e32 v39, 0xffff0000, v41
	v_and_b32_e32 v38, 0xffff0000, v49
	v_pk_mul_f32 v[38:39], v[42:43], v[38:39]
	v_and_b32_e32 v45, 0xffff0000, v34
	v_fma_f32 v39, v88, v40, v39
	v_add_f32_e32 v43, v38, v39
	s_waitcnt vmcnt(2)
; __device__ __forceinline__ void gate_row(int m, int lane, const bf16_t* __restrict__ YA, const bf16_t* __restrict__ YB, const float* __restrict__ LSE, const bf16_t* __restrict__ PROJ, ...
;     ...
;         const float mx = fmaxf(l0[j], fmaxf(l1[j], l2[j])); const float e0 = __builtin_amdgcn_exp2f(l0[j] - mx), e1 = __builtin_amdgcn_exp2f(l1[j] - mx), e2 = __builtin_amdgcn_exp2f(l2[j] - mx);
;         const float inv = __builtin_amdgcn_rcpf(e0 + e1 + e2); const float w0 = e0 * inv, w1 = e1 * inv, w2 = e2 * inv;
;         yb[j][0] = w0 * bflo(b0[j].x) + w1 * bflo(b1[j].x) + w2 * bflo(b2[j].x); yb[j][1] = w0 * bfhi(b0[j].x) + w1 * bfhi(b1[j].x) + w2 * bfhi(b2[j].x);
;         yb[j][2] = w0 * bflo(b0[j].y) + w1 * bflo(b1[j].y) + w2 * bflo(b2[j].y); yb[j][3] = w0 * bfhi(b0[j].y) + w1 * bfhi(b1[j].y) + w2 * bfhi(b2[j].y);
;         yb[j][4] = w0 * bflo(b0[j].z) + w1 * bflo(b1[j].z) + w2 * bflo(b2[j].z); yb[j][5] = w0 * bfhi(b0[j].z) + w1 * bfhi(b1[j].z) + w2 * bfhi(b2[j].z);
;         yb[j][6] = w0 * bflo(b0[j].w) + w1 * bflo(b1[j].w) + w2 * bflo(b2[j].w); yb[j][7] = w0 * bfhi(b0[j].w) + w1 * bfhi(b1[j].w) + w2 * bfhi(b2[j].w);
; #pragma unroll
;         for (int i = 0; i < 8; ++i) { ssa += ya[j][i] * ya[j][i]; ssb += yb[j][i] * yb[j][i]; } }
;     const float ra = 1.0f / sqrtf(wave_sum(ssa) * (1.0f / DA) + EPS), rb = 1.0f / sqrtf(wave_sum(ssb) * (1.0f / DB) + EPS);
; #pragma unroll
;     for (int j = 0; j < 2; ++j) { const int c = lane + 64 * j;
;         const float gaf[8] = {bflo(ga[j].x), bfhi(ga[j].x), bflo(ga[j].y), bfhi(ga[j].y), bflo(ga[j].z), bfhi(ga[j].z), bflo(ga[j].w), bfhi(ga[j].w)};
;         const float gbf[8] = {bflo(gb[j].x), bfhi(gb[j].x), bflo(gb[j].y), bfhi(gb[j].y), bflo(gb[j].z), bfhi(gb[j].z), bflo(gb[j].w), bfhi(gb[j].w)};
;         const f32x4 wa0 = *(const f32x4*)(wa + 8 * c), wa1 = *(const f32x4*)(wa + 8 * c + 4), wb0 = *(const f32x4*)(wb + 8 * c), wb1 = *(const f32x4*)(wb + 8 * c + 4);
;         float za[8], zb[8];
; #pragma unroll
;         for (int i = 0; i < 8; ++i) { const float wai = i < 4 ? wa0[i & 3] : wa1[i & 3], wbi = i < 4 ? wb0[i & 3] : wb1[i & 3];
;             const float sa = gaf[i] * __builtin_amdgcn_rcpf(1.0f + __builtin_amdgcn_exp2f(-1.4426950408889634f * gaf[i])), sb = gbf[i] * __builtin_amdgcn_rcpf(1.0f + __builtin_amdgcn_exp2f(-1.4426950408889634f * gbf[i]));
	v_max3_f32 v38, v82, v83, v87
	v_sub_f32_e32 v39, v82, v38
	v_sub_f32_e32 v40, v83, v38
	v_exp_f32_e32 v39, v39
	v_exp_f32_e32 v41, v40
	v_sub_f32_e32 v38, v87, v38
	v_exp_f32_e32 v38, v38
	v_and_b32_e32 v48, 0xffff0000, v35
	v_add_f32_e32 v40, v39, v41
	v_mul_f32_e32 v42, v79, v79
	v_add_f32_e32 v40, v38, v40
	v_rcp_f32_e32 v40, v40
	v_fmac_f32_e32 v42, v77, v77
	v_fmac_f32_e32 v42, v86, v86
	v_fmac_f32_e32 v42, v85, v85
	v_mul_f32_e32 v41, v41, v40
	v_pk_mul_f32 v[34:35], v[38:39], v[40:41] op_sel_hi:[1,0]
	v_lshlrev_b32_e32 v39, 16, v18
	v_lshlrev_b32_e32 v38, 16, v30
	v_pk_mul_f32 v[38:39], v[34:35], v[38:39]
	v_lshlrev_b32_e32 v49, 16, v36
	v_fma_f32 v39, v41, v44, v39
	v_add_f32_e32 v87, v38, v39
	v_and_b32_e32 v39, 0xffff0000, v18
	v_and_b32_e32 v38, 0xffff0000, v30
	v_pk_mul_f32 v[38:39], v[34:35], v[38:39]
	v_fmac_f32_e32 v42, v84, v84
	v_fma_f32 v18, v41, v45, v39
	v_add_f32_e32 v99, v38, v18
	v_lshlrev_b32_e32 v39, 16, v19
	v_lshlrev_b32_e32 v38, 16, v31
	v_pk_mul_f32 v[38:39], v[34:35], v[38:39]
	v_and_b32_e32 v19, 0xffff0000, v19
	v_fma_f32 v18, v41, v46, v39
	v_add_f32_e32 v91, v38, v18
	v_and_b32_e32 v18, 0xffff0000, v31
	v_pk_mul_f32 v[18:19], v[34:35], v[18:19]
	v_fmac_f32_e32 v42, v47, v47
	v_fma_f32 v19, v41, v48, v19
	v_add_f32_e32 v90, v18, v19
	v_lshlrev_b32_e32 v19, 16, v20
	v_lshlrev_b32_e32 v18, 16, v32
	v_pk_mul_f32 v[18:19], v[34:35], v[18:19]
	v_fmac_f32_e32 v42, v92, v92
	v_fma_f32 v19, v41, v49, v19
	v_add_f32_e32 v88, v18, v19
	v_and_b32_e32 v19, 0xffff0000, v20
	v_and_b32_e32 v18, 0xffff0000, v32
	v_and_b32_e32 v36, 0xffff0000, v36
	v_pk_mul_f32 v[18:19], v[34:35], v[18:19]
	v_fmac_f32_e32 v42, v43, v43
	v_fma_f32 v19, v41, v36, v19
	v_add_f32_e32 v89, v18, v19
	v_lshlrev_b32_e32 v19, 16, v21
	v_lshlrev_b32_e32 v18, 16, v33
	v_fmac_f32_e32 v42, v87, v87
	v_lshlrev_b32_e32 v76, 16, v37
	v_pk_mul_f32 v[18:19], v[34:35], v[18:19]
	v_fmac_f32_e32 v42, v99, v99
	v_fma_f32 v19, v41, v76, v19
	v_fmac_f32_e32 v42, v91, v91
	v_add_f32_e32 v94, v18, v19
	v_and_b32_e32 v19, 0xffff0000, v21
	v_and_b32_e32 v18, 0xffff0000, v33
	v_fmac_f32_e32 v42, v90, v90
	v_and_b32_e32 v20, 0xffff0000, v37
	v_pk_mul_f32 v[18:19], v[34:35], v[18:19]
	v_fmac_f32_e32 v42, v88, v88
	v_fma_f32 v19, v41, v20, v19
	v_fmac_f32_e32 v42, v89, v89
	v_add_f32_e32 v150, v18, v19
	v_fmac_f32_e32 v42, v94, v94
	v_fmac_f32_e32 v42, v150, v150
	v_and_b32_e32 v38, 0xffff0000, v5
	v_lshlrev_b32_e32 v39, 16, v5
	ds_bpermute_b32 v5, v140, v42
	v_lshlrev_b32_e32 v82, 16, v14
	v_and_b32_e32 v80, 0xffff0000, v14
	v_lshlrev_b32_e32 v78, 16, v15
	v_and_b32_e32 v76, 0xffff0000, v15
	s_waitcnt lgkmcnt(0)
	v_add_f32_e32 v5, v42, v5
	ds_bpermute_b32 v18, v141, v5
	v_lshlrev_b32_e32 v48, 16, v16
	v_and_b32_e32 v46, 0xffff0000, v16
	v_lshlrev_b32_e32 v44, 16, v17
	v_and_b32_e32 v42, 0xffff0000, v17
	s_waitcnt lgkmcnt(0)
	v_add_f32_e32 v5, v5, v18
	ds_bpermute_b32 v18, v142, v5
	s_waitcnt vmcnt(1)
	v_and_b32_e32 v118, 0xffff0000, v7
	v_mul_f32_e32 v3, 0xbfb8aa3b, v118
	v_exp_f32_e32 v3, v3
	v_and_b32_e32 v136, 0xffff0000, v6
	s_waitcnt lgkmcnt(0)
	v_add_f32_e32 v5, v5, v18
	ds_bpermute_b32 v18, v143, v5
	v_and_b32_e32 v137, 0xffff0000, v2
	v_mul_f32_e32 v2, 0xbfb8aa3b, v136
	v_exp_f32_e32 v2, v2
	v_lshlrev_b32_e32 v102, 16, v24
	s_waitcnt lgkmcnt(0)
	v_add_f32_e32 v5, v5, v18
	ds_bpermute_b32 v18, v144, v5
	v_lshlrev_b32_e32 v110, 16, v7
	v_add_f32_e32 v3, 1.0, v3
	v_rcp_f32_e32 v124, v3
	v_mul_f32_e32 v3, 0xbfb8aa3b, v110
	s_waitcnt lgkmcnt(0)
	v_add_f32_e32 v5, v5, v18
	ds_bpermute_b32 v18, v145, v5
	v_exp_f32_e32 v3, v3
	v_add_f32_e32 v2, 1.0, v2
	v_rcp_f32_e32 v138, v2
	v_mul_f32_e32 v2, v131, v131
	s_waitcnt lgkmcnt(0)
	v_add_f32_e32 v5, v5, v18
	v_fmamk_f32 v5, v5, 0x3a800000, v215
	v_cmp_gt_f32_e32 vcc, s33, v5
	v_mul_f32_e32 v18, 0x4f800000, v5
	v_fmac_f32_e32 v2, v133, v133
	v_cndmask_b32_e32 v5, v5, v18, vcc
	v_sqrt_f32_e32 v18, v5
	v_fmac_f32_e32 v2, v109, v109
	v_lshlrev_b32_e32 v108, 16, v23
	v_and_b32_e32 v122, 0xffff0000, v23
	v_add_u32_e32 v19, -1, v18
	v_fma_f32 v20, -v19, v18, v5
	v_cmp_ge_f32_e64 s[0:1], 0, v20
	v_add_u32_e32 v20, 1, v18
	v_lshlrev_b32_e32 v130, 16, v22
	v_cndmask_b32_e64 v19, v18, v19, s[0:1]
	v_fma_f32 v18, -v20, v18, v5
	v_cmp_lt_f32_e64 s[0:1], 0, v18
	v_and_b32_e32 v132, 0xffff0000, v22
	v_add_f32_e32 v3, 1.0, v3
	v_cndmask_b32_e64 v18, v19, v20, s[0:1]
	v_mul_f32_e32 v19, 0x37800000, v18
	v_cndmask_b32_e32 v18, v18, v19, vcc
	v_cmp_class_f32_e32 vcc, v5, v216
	v_fmac_f32_e32 v2, v123, v123
	v_rcp_f32_e32 v120, v3
	v_cndmask_b32_e32 v5, v18, v5, vcc
	v_div_scale_f32 v18, s[0:1], v5, v5, 1.0
	v_rcp_f32_e32 v19, v18
	v_fmac_f32_e32 v2, v103, v103
	v_pk_mul_f32 v[40:41], v[38:39], v[38:39]
	v_lshlrev_b32_e32 v128, 16, v6
	v_fma_f32 v20, -v18, v19, 1.0
	v_fmac_f32_e32 v19, v20, v19
	v_div_scale_f32 v20, vcc, 1.0, v5, 1.0
	v_mul_f32_e32 v21, v20, v19
	v_fma_f32 v30, -v18, v21, v20
	v_fmac_f32_e32 v21, v30, v19
	v_fma_f32 v18, -v18, v21, v20
	v_div_fmas_f32 v18, v18, v19, v21
	v_div_fixup_f32 v151, v18, v5, 1.0
	global_load_dwordx4 v[14:17], v[58:59], off offset:16
	global_load_dwordx4 v[18:21], v[58:59], off
	global_load_dwordx4 v[30:33], v[60:61], off offset:16
	global_load_dwordx4 v[34:37], v[60:61], off
	v_mul_f32_e32 v81, v79, v151
	v_mul_f32_e32 v83, v77, v151
	v_mul_f32_e32 v77, v85, v151
	v_mul_f32_e32 v47, v47, v151
	v_mul_f32_e32 v49, v84, v151
	v_lshlrev_b32_e32 v84, 16, v25
	v_mul_f32_e32 v79, v86, v151
	v_lshlrev_b32_e32 v85, 16, v13
	v_mul_f32_e32 v13, 0xbfb8aa3b, v102
	v_exp_f32_e32 v13, v13
	v_mul_f32_e32 v5, 0xbfb8aa3b, v82
	v_exp_f32_e32 v5, v5
	v_mul_f32_e32 v43, v43, v151
	v_add_f32_e32 v13, 1.0, v13
	v_rcp_f32_e32 v104, v13
	v_and_b32_e32 v13, 0xffff0000, v12
	v_add_f32_e32 v5, 1.0, v5
	v_fmac_f32_e32 v2, v13, v13
	v_rcp_f32_e32 v96, v5
	v_fmac_f32_e32 v2, v85, v85
	v_fmac_f32_e32 v2, v93, v93
	v_fmac_f32_e32 v2, v129, v129
	v_fmac_f32_e32 v2, v137, v137
	v_fmac_f32_e32 v2, v111, v111
	v_fmac_f32_e32 v2, v119, v119
	v_mul_f32_e32 v95, v90, v151
	v_and_b32_e32 v12, 0xffff0000, v24
	v_mul_f32_e32 v24, 0xbfb8aa3b, v12
	v_mul_f32_e32 v11, 0xbfb8aa3b, v122
	v_exp_f32_e32 v24, v24
	v_exp_f32_e32 v11, v11
	v_mul_f32_e32 v10, 0xbfb8aa3b, v132
	v_exp_f32_e32 v10, v10
	v_add_f32_e32 v24, 1.0, v24
	v_add_f32_e32 v11, 1.0, v11
	v_rcp_f32_e32 v106, v24
	v_mul_f32_e32 v24, 0xbfb8aa3b, v108
	v_rcp_f32_e32 v126, v11
	v_mul_f32_e32 v11, 0xbfb8aa3b, v130
	v_exp_f32_e32 v24, v24
	v_exp_f32_e32 v11, v11
	v_mul_f32_e32 v45, v92, v151
	v_add_f32_e32 v10, 1.0, v10
	v_add_f32_e32 v24, 1.0, v24
	v_add_f32_e32 v11, 1.0, v11
	v_rcp_f32_e32 v112, v24
	v_rcp_f32_e32 v24, v11
	v_rcp_f32_e32 v134, v10
	v_and_b32_e32 v92, 0xffff0000, v25
	v_mul_f32_e32 v10, 0xbfb8aa3b, v92
	v_exp_f32_e32 v10, v10
	v_mul_f32_e32 v115, v87, v151
	v_mul_f32_e32 v117, v99, v151
	v_mul_f32_e32 v91, v91, v151
	v_add_f32_e32 v10, 1.0, v10
	v_rcp_f32_e32 v10, v10
	s_waitcnt vmcnt(0)
; __device__ __forceinline__ unsigned pk2(float lo, float hi) { unsigned r; asm("v_cvt_pk_bf16_f32 %0, %1, %2" : "=v"(r) : "v"(lo), "v"(hi)); return r; }
; __device__ __forceinline__ float bflo(unsigned w) { return __uint_as_float(w << 16); }
; __device__ __forceinline__ float bfhi(unsigned w) { return __uint_as_float(w & 0xffff0000u); }
; __device__ __forceinline__ void gate_row(int m, int lane, const bf16_t* __restrict__ YA, const bf16_t* __restrict__ YB, const float* __restrict__ LSE, const bf16_t* __restrict__ PROJ, ...
;     ...
;     for (int j = 0; j < 2; ++j) { const int c = lane + 64 * j;
;         const float gaf[8] = {bflo(ga[j].x), bfhi(ga[j].x), bflo(ga[j].y), bfhi(ga[j].y), bflo(ga[j].z), bfhi(ga[j].z), bflo(ga[j].w), bfhi(ga[j].w)};
;         const float gbf[8] = {bflo(gb[j].x), bfhi(gb[j].x), bflo(gb[j].y), bfhi(gb[j].y), bflo(gb[j].z), bfhi(gb[j].z), bflo(gb[j].w), bfhi(gb[j].w)};
;         const f32x4 wa0 = *(const f32x4*)(wa + 8 * c), wa1 = *(const f32x4*)(wa + 8 * c + 4), wb0 = *(const f32x4*)(wb + 8 * c), wb1 = *(const f32x4*)(wb + 8 * c + 4);
;         float za[8], zb[8];
; #pragma unroll
;         for (int i = 0; i < 8; ++i) { const float wai = i < 4 ? wa0[i & 3] : wa1[i & 3], wbi = i < 4 ? wb0[i & 3] : wb1[i & 3];
;             const float sa = gaf[i] * __builtin_amdgcn_rcpf(1.0f + __builtin_amdgcn_exp2f(-1.4426950408889634f * gaf[i])), sb = gbf[i] * __builtin_amdgcn_rcpf(1.0f + __builtin_amdgcn_exp2f(-1.4426950408889634f * gbf[i]));
;             za[i] = ya[j][i] * ra * wai * sa; zb[i] = yb[j][i] * rb * wbi * sb; }
;         v4u oa, ob; oa.x = pk2(za[0], za[1]); oa.y = pk2(za[2], za[3]); oa.z = pk2(za[4], za[5]); oa.w = pk2(za[6], za[7]);
;         ob.x = pk2(zb[0], zb[1]); ob.y = pk2(zb[2], zb[3]); ob.z = pk2(zb[4], zb[5]); ob.w = pk2(zb[6], zb[7]);
;         *(v4u*)(H + (size_t)m * DM + 8 * c) = oa; *(v4u*)(H + (size_t)m * DM + DA + 8 * c) = ob; }
	v_mov_b32_e32 v97, v34
	v_mul_f32_e32 v34, 0xbfb8aa3b, v80
	v_exp_f32_e32 v34, v34
	v_pk_mul_f32 v[82:83], v[96:97], v[82:83]
	v_and_b32_e32 v97, 0xffff0000, v4
	v_mul_f32_e32 v5, v82, v83
	v_add_f32_e32 v34, 1.0, v34
	v_rcp_f32_e32 v34, v34
	v_mul_f32_e32 v83, v89, v151
	v_lshlrev_b32_e32 v89, 16, v4
	v_fmac_f32_e32 v2, v89, v89
	v_pk_mul_f32 v[34:35], v[34:35], v[80:81]
	v_mov_b32_e32 v81, v36
	v_mul_f32_e32 v35, v34, v35
	v_mul_f32_e32 v34, 0xbfb8aa3b, v78
	v_exp_f32_e32 v34, v34
	v_fmac_f32_e32 v2, v97, v97
	v_add_f32_e32 v2, v41, v2
	v_add_f32_e32 v2, v40, v2
	v_add_f32_e32 v34, 1.0, v34
	v_rcp_f32_e32 v80, v34
	v_mul_f32_e32 v34, 0xbfb8aa3b, v76
	v_exp_f32_e32 v34, v34
	v_and_b32_e32 v96, 0xffff0000, v8
	v_mul_f32_e32 v4, 0xbfb8aa3b, v96
	v_exp_f32_e32 v4, v4
	v_add_f32_e32 v34, 1.0, v34
	v_rcp_f32_e32 v36, v34
	v_pk_mul_f32 v[78:79], v[80:81], v[78:79]
	v_mul_f32_e32 v81, v88, v151
	v_lshlrev_b32_e32 v88, 16, v8
	v_pk_mul_f32 v[36:37], v[36:37], v[76:77]
	v_mov_b32_e32 v77, v30
	v_mul_f32_e32 v30, 0xbfb8aa3b, v46
	v_exp_f32_e32 v30, v30
	v_add_f32_e32 v4, 1.0, v4
	v_rcp_f32_e32 v100, v4
	v_mul_f32_e32 v4, 0xbfb8aa3b, v88
	v_add_f32_e32 v30, 1.0, v30
	v_rcp_f32_e32 v30, v30
	v_exp_f32_e32 v4, v4
	v_mul_f32_e32 v34, 0xbfb8aa3b, v48
	v_exp_f32_e32 v34, v34
	v_pk_mul_f32 v[30:31], v[30:31], v[46:47]
	v_mov_b32_e32 v47, v32
	v_mul_f32_e32 v31, v30, v31
	v_mul_f32_e32 v30, 0xbfb8aa3b, v44
	v_exp_f32_e32 v30, v30
	v_mul_f32_e32 v37, v36, v37
	v_and_b32_e32 v36, 0xffff0000, v27
	v_add_f32_e32 v4, 1.0, v4
	v_add_f32_e32 v30, 1.0, v30
	v_rcp_f32_e32 v46, v30
	v_mul_f32_e32 v30, 0xbfb8aa3b, v84
	v_exp_f32_e32 v30, v30
	v_rcp_f32_e32 v98, v4
	v_mul_f32_e32 v4, 0xbfb8aa3b, v36
	v_add_f32_e32 v34, 1.0, v34
	v_add_f32_e32 v30, 1.0, v30
	v_rcp_f32_e32 v86, v30
	v_mul_f32_e32 v30, 0xbfb8aa3b, v42
	v_exp_f32_e32 v30, v30
	v_exp_f32_e32 v4, v4
	v_rcp_f32_e32 v76, v34
	v_lshlrev_b32_e32 v34, 16, v27
	v_add_f32_e32 v30, 1.0, v30
	v_rcp_f32_e32 v32, v30
	v_lshlrev_b32_e32 v30, 16, v26
	v_add_f32_e32 v4, 1.0, v4
	v_pk_mul_f32 v[48:49], v[76:77], v[48:49]
	v_pk_mul_f32 v[22:23], v[32:33], v[42:43]
	v_and_b32_e32 v32, 0xffff0000, v26
	v_mul_f32_e32 v3, 0xbfb8aa3b, v32
	v_exp_f32_e32 v3, v3
	v_mul_f32_e32 v77, v94, v151
	v_rcp_f32_e32 v94, v4
	v_mul_f32_e32 v4, 0xbfb8aa3b, v34
	v_add_f32_e32 v3, 1.0, v3
	v_rcp_f32_e32 v116, v3
	v_mul_f32_e32 v3, 0xbfb8aa3b, v30
	v_exp_f32_e32 v3, v3
	v_exp_f32_e32 v4, v4
	v_mul_f32_e32 v79, v78, v79
	v_pk_mul_f32 v[44:45], v[46:47], v[44:45]
	v_add_f32_e32 v3, 1.0, v3
	v_rcp_f32_e32 v114, v3
	ds_bpermute_b32 v3, v140, v2
	v_add_f32_e32 v4, 1.0, v4
	v_rcp_f32_e32 v90, v4
	v_and_b32_e32 v78, 0xffff0000, v28
	v_mul_f32_e32 v45, v44, v45
	s_waitcnt lgkmcnt(0)
	v_add_f32_e32 v2, v2, v3
	ds_bpermute_b32 v3, v141, v2
	v_lshlrev_b32_e32 v44, 16, v9
	v_lshlrev_b32_e32 v42, 16, v28
	v_and_b32_e32 v28, 0xffff0000, v9
	v_mul_f32_e32 v9, 0xbfb8aa3b, v78
	s_waitcnt lgkmcnt(0)
	v_add_f32_e32 v2, v2, v3
	ds_bpermute_b32 v3, v142, v2
	v_exp_f32_e32 v9, v9
	v_lshlrev_b32_e32 v46, 16, v29
	v_mul_f32_e32 v11, 0xbfb8aa3b, v46
	v_exp_f32_e32 v11, v11
	s_waitcnt lgkmcnt(0)
	v_add_f32_e32 v2, v2, v3
	ds_bpermute_b32 v3, v143, v2
	v_add_f32_e32 v9, 1.0, v9
	v_rcp_f32_e32 v82, v9
	v_mul_f32_e32 v9, 0xbfb8aa3b, v42
	v_exp_f32_e32 v9, v9
	s_waitcnt lgkmcnt(0)
	v_add_f32_e32 v2, v2, v3
	ds_bpermute_b32 v3, v144, v2
	v_add_f32_e32 v11, 1.0, v11
	v_rcp_f32_e32 v76, v11
	v_mul_f32_e32 v11, 0xbfb8aa3b, v44
	v_exp_f32_e32 v11, v11
	s_waitcnt lgkmcnt(0)
	v_add_f32_e32 v2, v2, v3
	ds_bpermute_b32 v3, v145, v2
	v_add_f32_e32 v9, 1.0, v9
	v_rcp_f32_e32 v80, v9
	v_add_f32_e32 v11, 1.0, v11
	v_mul_f32_e32 v49, v48, v49
	s_waitcnt lgkmcnt(0)
	v_add_f32_e32 v2, v2, v3
	v_fmamk_f32 v2, v2, 0x3a800000, v215
	v_cmp_gt_f32_e32 vcc, s33, v2
	v_mul_f32_e32 v3, 0x4f800000, v2
	v_rcp_f32_e32 v48, v11
	v_cndmask_b32_e32 v2, v2, v3, vcc
	v_sqrt_f32_e32 v3, v2
	v_mul_f32_e32 v33, v22, v23
	v_lshl_add_u64 v[22:23], v[66:67], 0, s[28:29]
	v_and_b32_e32 v26, 0xffff0000, v29
	v_add_u32_e32 v4, -1, v3
	v_fma_f32 v6, -v4, v3, v2
	v_cmp_ge_f32_e64 s[0:1], 0, v6
	v_add_u32_e32 v6, 1, v3
	s_nop 0
	v_cndmask_b32_e64 v4, v3, v4, s[0:1]
	v_fma_f32 v3, -v6, v3, v2
	v_cmp_lt_f32_e64 s[0:1], 0, v3
	s_nop 1
	v_cndmask_b32_e64 v3, v4, v6, s[0:1]
	v_mul_f32_e32 v4, 0x37800000, v3
	v_cndmask_b32_e32 v3, v3, v4, vcc
	v_cmp_class_f32_e32 vcc, v2, v216
	s_nop 1
	v_cndmask_b32_e32 v2, v3, v2, vcc
	v_div_scale_f32 v3, s[0:1], v2, v2, 1.0
	v_rcp_f32_e32 v4, v3
	s_nop 0
	v_fma_f32 v6, -v3, v4, 1.0
	v_fmac_f32_e32 v4, v6, v4
	v_div_scale_f32 v6, vcc, 1.0, v2, 1.0
	v_mul_f32_e32 v7, v6, v4
	v_fma_f32 v8, -v3, v7, v6
	v_fmac_f32_e32 v7, v8, v4
	v_fma_f32 v3, -v3, v7, v6
	v_div_fmas_f32 v3, v3, v4, v7
	v_div_fixup_f32 v25, v3, v2, 1.0
	v_pk_mul_f32 v[2:3], v[24:25], v[130:131]
	v_mov_b32_e32 v135, v25
	v_mul_f32_e32 v3, v3, v18
	v_mul_f32_e32 v4, v2, v3
	v_pk_mul_f32 v[2:3], v[134:135], v[132:133]
	v_mov_b32_e32 v113, v25
	v_mul_f32_e32 v3, v3, v19
	v_mul_f32_e32 v6, v2, v3
	v_pk_mul_f32 v[2:3], v[112:113], v[108:109]
	v_mov_b32_e32 v127, v25
	v_mul_f32_e32 v3, v3, v20
	v_mul_f32_e32 v7, v2, v3
	v_pk_mul_f32 v[2:3], v[126:127], v[122:123]
	v_mov_b32_e32 v105, v25
	v_mul_f32_e32 v3, v3, v21
	v_mul_f32_e32 v8, v2, v3
	v_pk_mul_f32 v[2:3], v[104:105], v[102:103]
	v_mov_b32_e32 v107, v25
	v_mul_f32_e32 v3, v3, v14
	v_mul_f32_e32 v9, v2, v3
	v_pk_mul_f32 v[2:3], v[106:107], v[12:13]
	v_mov_b32_e32 v87, v25
	v_mul_f32_e32 v3, v3, v15
	v_mul_f32_e32 v12, v2, v3
	v_pk_mul_f32 v[2:3], v[86:87], v[84:85]
	v_mov_b32_e32 v11, v25
	v_mul_f32_e32 v3, v3, v16
	v_mul_f32_e32 v13, v2, v3
	v_pk_mul_f32 v[2:3], v[10:11], v[92:93]
	v_cvt_pk_bf16_f32 v6, v4, v6
	v_cvt_pk_bf16_f32 v7, v7, v8
	v_cvt_pk_bf16_f32 v8, v9, v12
	v_cvt_pk_bf16_f32 v4, v49, v31
	v_mul_f32_e32 v49, v25, v39
	v_mul_f32_e32 v3, v3, v17
	v_mul_f32_e32 v2, v2, v3
	v_cvt_pk_bf16_f32 v9, v13, v2
	v_cvt_pk_bf16_f32 v2, v5, v35
	v_cvt_pk_bf16_f32 v3, v79, v37
	v_cvt_pk_bf16_f32 v5, v45, v33
	global_store_dwordx4 v[22:23], v[6:9], off offset:-2048 sc1
	global_store_dwordx4 v[22:23], v[2:5], off sc1
	global_load_dwordx4 v[2:5], v[58:59], off offset:2064
	s_nop 0
	global_load_dwordx4 v[10:13], v[58:59], off offset:2048
	global_load_dwordx4 v[6:9], v[60:61], off offset:2064
	global_load_dwordx4 v[14:17], v[60:61], off offset:2048
	v_mov_b32_e32 v101, v25
	v_mov_b32_e32 v99, v25
	v_mov_b32_e32 v125, v25
	v_mov_b32_e32 v121, v25
	v_mov_b32_e32 v139, v25
	s_waitcnt vmcnt(3)
; __device__ __forceinline__ void gate_row(int m, int lane, const bf16_t* __restrict__ YA, const bf16_t* __restrict__ YB, const float* __restrict__ LSE, const bf16_t* __restrict__ PROJ, ...
;     v4u a[2], b0[2], b1[2], b2[2], ga[2], gb[2]; float l0[2], l1[2], l2[2];
; #pragma unroll
;     for (int j = 0; j < 2; ++j) { const int c = lane + 64 * j, hh = c >> 4;
;         a[j] = *(const v4u*)(YA + (size_t)m * DA + 8 * c);
;         b0[j] = *(const v4u*)(YB + ((size_t)0 * M + m) * DB + 8 * c); b1[j] = *(const v4u*)(YB + ((size_t)1 * M + m) * DB + 8 * c); b2[j] = *(const v4u*)(YB + ((size_t)2 * M + m) * DB + 8 * c);
;         l0[j] = LSE[((size_t)0 * M + m) * 8 + hh]; l1[j] = LSE[((size_t)1 * M + m) * 8 + hh]; l2[j] = LSE[((size_t)2 * M + m) * 8 + hh];
;         ga[j] = *(const v4u*)(PROJ + ((size_t)(H_GA + (c >> 4)) * M + m) * HD + 8 * (c & 15)); gb[j] = *(const v4u*)(PROJ + ((size_t)(H_GB + (c >> 4)) * M + m) * HD + 8 * (c & 15)); }
;     ...
;     for (int j = 0; j < 2; ++j) { const int c = lane + 64 * j;
;         const float gaf[8] = {bflo(ga[j].x), bfhi(ga[j].x), bflo(ga[j].y), bfhi(ga[j].y), bflo(ga[j].z), bfhi(ga[j].z), bflo(ga[j].w), bfhi(ga[j].w)};
;         const float gbf[8] = {bflo(gb[j].x), bfhi(gb[j].x), bflo(gb[j].y), bfhi(gb[j].y), bflo(gb[j].z), bfhi(gb[j].z), bflo(gb[j].w), bfhi(gb[j].w)};
;         const f32x4 wa0 = *(const f32x4*)(wa + 8 * c), wa1 = *(const f32x4*)(wa + 8 * c + 4), wb0 = *(const f32x4*)(wb + 8 * c), wb1 = *(const f32x4*)(wb + 8 * c + 4);
;         float za[8], zb[8];
; #pragma unroll
;         for (int i = 0; i < 8; ++i) { const float wai = i < 4 ? wa0[i & 3] : wa1[i & 3], wbi = i < 4 ? wb0[i & 3] : wb1[i & 3];
;             const float sa = gaf[i] * __builtin_amdgcn_rcpf(1.0f + __builtin_amdgcn_exp2f(-1.4426950408889634f * gaf[i])), sb = gbf[i] * __builtin_amdgcn_rcpf(1.0f + __builtin_amdgcn_exp2f(-1.4426950408889634f * gbf[i]));
;             za[i] = ya[j][i] * ra * wai * sa; zb[i] = yb[j][i] * rb * wbi * sb; }
;         v4u oa, ob; oa.x = pk2(za[0], za[1]); oa.y = pk2(za[2], za[3]); oa.z = pk2(za[4], za[5]); oa.w = pk2(za[6], za[7]);
;         ob.x = pk2(zb[0], zb[1]); ob.y = pk2(zb[2], zb[3]); ob.z = pk2(zb[4], zb[5]); ob.w = pk2(zb[6], zb[7]);
;         *(v4u*)(H + (size_t)m * DM + 8 * c) = oa; *(v4u*)(H + (size_t)m * DM + DA + 8 * c) = ob; }
	v_mov_b32_e32 v45, v4
	v_mov_b32_e32 v29, v5
	s_waitcnt vmcnt(1)
	v_mov_b32_e32 v47, v8
	v_pk_mul_f32 v[18:19], v[76:77], v[46:47]
	v_mov_b32_e32 v79, v7
	v_mul_f32_e32 v20, v18, v19
	v_pk_mul_f32 v[18:19], v[48:49], v[44:45]
	v_mov_b32_e32 v43, v6
	v_mul_f32_e32 v8, v18, v19
	v_pk_mul_f32 v[18:19], v[82:83], v[78:79]
	v_pk_mul_f32 v[6:7], v[80:81], v[42:43]
	v_mul_f32_e32 v21, v18, v19
	v_pk_mul_f32 v[18:19], v[100:101], v[96:97]
	s_waitcnt vmcnt(0)
	v_mov_b32_e32 v37, v17
	v_mul_f32_e32 v3, v19, v3
	v_mul_f32_e32 v19, v6, v7
	v_pk_mul_f32 v[6:7], v[98:99], v[88:89]
	v_mul_f32_e32 v18, v18, v3
	v_mul_f32_e32 v2, v7, v2
	v_mul_f32_e32 v6, v6, v2
	v_pk_mul_f32 v[2:3], v[94:95], v[36:37]
	v_mov_b32_e32 v35, v16
	v_mul_f32_e32 v7, v2, v3
	v_pk_mul_f32 v[2:3], v[124:125], v[118:119]
	v_mov_b32_e32 v33, v15
	v_mul_f32_e32 v3, v3, v13
	v_mul_f32_e32 v13, v2, v3
	v_pk_mul_f32 v[2:3], v[90:91], v[34:35]
	v_mov_b32_e32 v31, v14
	v_mul_f32_e32 v16, v2, v3
	v_pk_mul_f32 v[2:3], v[120:121], v[110:111]
	v_mul_f32_e32 v5, v150, v151
	v_mul_f32_e32 v3, v3, v12
	v_mul_f32_e32 v12, v2, v3
	v_pk_mul_f32 v[2:3], v[116:117], v[32:33]
	v_mov_b32_e32 v27, v9
	v_mul_f32_e32 v15, v2, v3
	v_pk_mul_f32 v[2:3], v[138:139], v[136:137]
	v_cvt_pk_bf16_f32 v7, v16, v7
	s_nop 0
	v_mul_f32_e32 v3, v3, v11
	v_mul_f32_e32 v11, v2, v3
	v_pk_mul_f32 v[2:3], v[114:115], v[30:31]
	s_nop 0
	v_mul_f32_e32 v14, v2, v3
	v_mul_f32_e32 v2, 0xbfb8aa3b, v128
	v_exp_f32_e32 v2, v2
	s_nop 0
	v_add_f32_e32 v2, 1.0, v2
	v_rcp_f32_e32 v24, v2
	s_nop 0
	v_pk_mul_f32 v[2:3], v[24:25], v[128:129]
	s_nop 0
	v_mul_f32_e32 v3, v3, v10
	v_mul_f32_e32 v10, v2, v3
	v_mul_f32_e32 v2, 0xbfb8aa3b, v28
	v_exp_f32_e32 v2, v2
	v_mul_f32_e32 v3, 0xbfb8aa3b, v26
	v_exp_f32_e32 v3, v3
	v_add_f32_e32 v2, 1.0, v2
	v_rcp_f32_e32 v2, v2
	v_add_f32_e32 v3, 1.0, v3
	v_rcp_f32_e32 v4, v3
	v_mul_f32_e32 v3, v25, v38
	v_pk_mul_f32 v[2:3], v[2:3], v[28:29]
	s_nop 0
	v_mul_f32_e32 v17, v2, v3
	v_pk_mul_f32 v[2:3], v[4:5], v[26:27]
	v_cvt_pk_bf16_f32 v4, v6, v18
	v_cvt_pk_bf16_f32 v5, v8, v17
	v_cvt_pk_bf16_f32 v6, v14, v15
	v_cvt_pk_bf16_f32 v8, v19, v21
	s_nop 0
	v_mul_f32_e32 v9, v2, v3
	v_cvt_pk_bf16_f32 v2, v10, v11
	v_cvt_pk_bf16_f32 v3, v12, v13
	v_cvt_pk_bf16_f32 v9, v20, v9
	global_store_dwordx4 v[22:23], v[2:5], off offset:-1024 sc1
	global_store_dwordx4 v[22:23], v[6:9], off offset:1024 sc1
	s_cbranch_scc1 .LBB0_40
	s_ashr_i32 s45, s44, 31
	s_lshl_b64 s[10:11], s[44:45], 11
	s_add_u32 s0, s52, s10
	s_addc_u32 s1, s8, s11
	s_add_u32 s50, s4, s10
	s_addc_u32 s51, s5, s11
	s_add_u32 s10, s44, 0x4000
	s_addc_u32 s11, s45, 0
	s_lshl_b64 s[12:13], s[10:11], 11
	s_add_u32 s12, s4, s12
	s_addc_u32 s13, s5, s13
	s_add_u32 s14, s44, 0x8000
	s_addc_u32 s15, s45, 0
	global_load_dwordx4 v[14:17], v146, s[50:51]
	global_load_dwordx4 v[18:21], v146, s[12:13]
	global_load_dwordx4 v[2:5], v148, s[12:13]
	s_lshl_b64 s[12:13], s[14:15], 11
	s_add_u32 s78, s4, s12
	s_addc_u32 s79, s5, s13
	s_lshl_b64 s[12:13], s[44:45], 5
	s_add_u32 s12, s6, s12
	s_addc_u32 s13, s7, s13
	s_lshl_b64 s[10:11], s[10:11], 5
	s_add_u32 s10, s6, s10
	s_addc_u32 s11, s7, s11
	s_lshl_b64 s[14:15], s[14:15], 5
	s_add_u32 s14, s6, s14
	global_load_dwordx4 v[10:13], v146, s[78:79]
	s_addc_u32 s15, s7, s15
	global_load_dword v80, v147, s[12:13]
	global_load_dword v81, v147, s[10:11]
	global_load_dword v82, v147, s[14:15]
	global_load_dword v83, v149, s[12:13]
	global_load_dword v84, v149, s[10:11]
	global_load_dword v85, v149, s[14:15]
	v_lshl_add_u64 v[6:7], s[44:45], 0, v[52:53]
	v_lshl_add_u64 v[8:9], s[44:45], 0, v[0:1]
	v_lshlrev_b64 v[6:7], 8, v[6:7]
	v_lshlrev_b64 v[8:9], 8, v[8:9]
	v_lshl_add_u64 v[6:7], v[50:51], 0, v[6:7]
	v_lshl_add_u64 v[8:9], v[50:51], 0, v[8:9]
	global_load_dwordx4 v[26:29], v[6:7], off
	global_load_dwordx4 v[22:25], v148, s[0:1]
	global_load_dwordx4 v[30:33], v146, s[0:1]
	global_load_dwordx4 v[34:37], v148, s[50:51]
	global_load_dwordx4 v[38:41], v148, s[78:79]
	s_nop 0
	global_load_dwordx4 v[6:9], v[8:9], off
	s_waitcnt vmcnt(15)
	v_lshlrev_b32_e32 v43, 16, v14
	s_waitcnt vmcnt(13)
	v_lshlrev_b32_e32 v93, 16, v2
	v_and_b32_e32 v94, 0xffff0000, v2
	v_and_b32_e32 v45, 0xffff0000, v14
	v_lshlrev_b32_e32 v95, 16, v3
	v_and_b32_e32 v96, 0xffff0000, v3
	v_lshlrev_b32_e32 v49, 16, v16
	v_and_b32_e32 v77, 0xffff0000, v16
	v_lshlrev_b32_e32 v86, 16, v18
	v_and_b32_e32 v87, 0xffff0000, v18
	v_lshlrev_b32_e32 v89, 16, v20
	v_and_b32_e32 v90, 0xffff0000, v20
	s_waitcnt vmcnt(9)
	v_max3_f32 v2, v80, v81, v82
	v_lshlrev_b32_e32 v42, 16, v10
	v_and_b32_e32 v44, 0xffff0000, v10
	v_lshlrev_b32_e32 v46, 16, v11
	v_and_b32_e32 v14, 0xffff0000, v11
	s_waitcnt vmcnt(6)
	v_max3_f32 v3, v83, v84, v85
	v_sub_f32_e32 v10, v80, v2
	v_sub_f32_e32 v11, v81, v2
	v_lshlrev_b32_e32 v48, 16, v12
	v_and_b32_e32 v76, 0xffff0000, v12
	v_sub_f32_e32 v2, v82, v2
	v_sub_f32_e32 v12, v83, v3
	v_sub_f32_e32 v16, v84, v3
	v_sub_f32_e32 v18, v85, v3
	v_exp_f32_e32 v3, v10
	v_exp_f32_e32 v20, v11
	v_lshlrev_b32_e32 v91, 16, v21
	v_and_b32_e32 v92, 0xffff0000, v21
	v_exp_f32_e32 v11, v12
	v_exp_f32_e32 v21, v16
	v_exp_f32_e32 v2, v2
	v_exp_f32_e32 v10, v18
	v_add_f32_e32 v12, v3, v20
	v_add_f32_e32 v16, v11, v21
	v_add_f32_e32 v12, v2, v12
	v_rcp_f32_e32 v12, v12
	v_add_f32_e32 v16, v10, v16
	v_rcp_f32_e32 v18, v16
	v_lshlrev_b32_e32 v47, 16, v15
	v_and_b32_e32 v15, 0xffff0000, v15
	v_lshlrev_b32_e32 v79, 16, v17
	v_and_b32_e32 v17, 0xffff0000, v17
	v_lshlrev_b32_e32 v78, 16, v13
	v_and_b32_e32 v16, 0xffff0000, v13
	v_pk_mul_f32 v[2:3], v[2:3], v[12:13] op_sel_hi:[1,0]
	v_lshlrev_b32_e32 v88, 16, v19
	v_and_b32_e32 v19, 0xffff0000, v19
	v_mul_f32_e32 v80, v20, v12
	v_mul_f32_e32 v81, v21, v18
	v_pk_mul_f32 v[12:13], v[2:3], v[42:43]
	v_pk_mul_f32 v[20:21], v[2:3], v[44:45]
	v_pk_mul_f32 v[42:43], v[2:3], v[46:47]
	v_pk_mul_f32 v[14:15], v[2:3], v[14:15]
	v_pk_mul_f32 v[44:45], v[2:3], v[48:49]
	v_pk_mul_f32 v[46:47], v[2:3], v[76:77]
	v_pk_mul_f32 v[48:49], v[2:3], v[78:79]
	v_pk_mul_f32 v[2:3], v[2:3], v[16:17]
	v_fma_f32 v15, v80, v19, v15
	v_fma_f32 v19, v80, v89, v45
	v_fma_f32 v3, v80, v92, v3
	v_add_f32_e32 v99, v2, v3
	v_pk_mul_f32 v[2:3], v[10:11], v[18:19] op_sel_hi:[1,0]
	s_waitcnt vmcnt(2)
; __device__ __forceinline__ float bflo(unsigned w) { return __uint_as_float(w << 16); }
; __device__ __forceinline__ float bfhi(unsigned w) { return __uint_as_float(w & 0xffff0000u); }
; __device__ __forceinline__ void gate_row(int m, int lane, const bf16_t* __restrict__ YA, const bf16_t* __restrict__ YB, const float* __restrict__ LSE, const bf16_t* __restrict__ PROJ, ...
;     ...
;     float ya[2][8], yb[2][8]; float ssa = 0.f, ssb = 0.f;
; #pragma unroll
;     for (int j = 0; j < 2; ++j) {
;         ya[j][0] = bflo(a[j].x); ya[j][1] = bfhi(a[j].x); ya[j][2] = bflo(a[j].y); ya[j][3] = bfhi(a[j].y); ya[j][4] = bflo(a[j].z); ya[j][5] = bfhi(a[j].z); ya[j][6] = bflo(a[j].w); ya[j][7] = bfhi(a[j].w);
;         const float mx = fmaxf(l0[j], fmaxf(l1[j], l2[j])); const float e0 = __builtin_amdgcn_exp2f(l0[j] - mx), e1 = __builtin_amdgcn_exp2f(l1[j] - mx), e2 = __builtin_amdgcn_exp2f(l2[j] - mx);
;         const float inv = __builtin_amdgcn_rcpf(e0 + e1 + e2); const float w0 = e0 * inv, w1 = e1 * inv, w2 = e2 * inv;
;         yb[j][0] = w0 * bflo(b0[j].x) + w1 * bflo(b1[j].x) + w2 * bflo(b2[j].x); yb[j][1] = w0 * bfhi(b0[j].x) + w1 * bfhi(b1[j].x) + w2 * bfhi(b2[j].x);
;         yb[j][2] = w0 * bflo(b0[j].y) + w1 * bflo(b1[j].y) + w2 * bflo(b2[j].y); yb[j][3] = w0 * bfhi(b0[j].y) + w1 * bfhi(b1[j].y) + w2 * bfhi(b2[j].y);
;         yb[j][4] = w0 * bflo(b0[j].z) + w1 * bflo(b1[j].z) + w2 * bflo(b2[j].z); yb[j][5] = w0 * bfhi(b0[j].z) + w1 * bfhi(b1[j].z) + w2 * bfhi(b2[j].z);
;         yb[j][6] = w0 * bflo(b0[j].w) + w1 * bflo(b1[j].w) + w2 * bflo(b2[j].w); yb[j][7] = w0 * bfhi(b0[j].w) + w1 * bfhi(b1[j].w) + w2 * bfhi(b2[j].w);
; #pragma unroll
;         for (int i = 0; i < 8; ++i) { ssa += ya[j][i] * ya[j][i]; ssb += yb[j][i] * yb[j][i]; } }
;     const float ra = 1.0f / sqrtf(wave_sum(ssa) * (1.0f / DA) + EPS), rb = 1.0f / sqrtf(wave_sum(ssb) * (1.0f / DB) + EPS);
	v_lshlrev_b32_e32 v11, 16, v34
	s_waitcnt vmcnt(1)
	v_lshlrev_b32_e32 v10, 16, v38
	v_pk_mul_f32 v[10:11], v[2:3], v[10:11]
	v_fma_f32 v16, v80, v87, v21
	v_fma_f32 v11, v81, v93, v11
	v_add_f32_e32 v84, v10, v11
	v_and_b32_e32 v11, 0xffff0000, v34
	v_and_b32_e32 v10, 0xffff0000, v38
	v_pk_mul_f32 v[10:11], v[2:3], v[10:11]
	v_fma_f32 v13, v80, v86, v13
	v_fma_f32 v11, v81, v94, v11
	v_add_f32_e32 v85, v10, v11
	v_lshlrev_b32_e32 v11, 16, v35
	v_lshlrev_b32_e32 v10, 16, v39
	v_pk_mul_f32 v[10:11], v[2:3], v[10:11]
	v_fma_f32 v21, v80, v90, v47
	v_fma_f32 v11, v81, v95, v11
	v_add_f32_e32 v47, v20, v16
	v_add_f32_e32 v86, v10, v11
	v_and_b32_e32 v11, 0xffff0000, v35
	v_and_b32_e32 v10, 0xffff0000, v39
	v_fma_f32 v17, v80, v88, v43
	v_add_f32_e32 v45, v12, v13
	v_mul_f32_e32 v12, v47, v47
	v_pk_mul_f32 v[10:11], v[2:3], v[10:11]
	v_fma_f32 v43, v80, v91, v49
	v_add_f32_e32 v49, v42, v17
	v_fmac_f32_e32 v12, v45, v45
	v_fma_f32 v11, v81, v96, v11
	v_add_f32_e32 v77, v14, v15
	v_fmac_f32_e32 v12, v49, v49
	v_add_f32_e32 v87, v10, v11
	v_lshlrev_b32_e32 v11, 16, v36
	v_lshlrev_b32_e32 v10, 16, v40
	v_lshlrev_b32_e32 v97, 16, v4
	v_add_f32_e32 v79, v44, v19
	v_fmac_f32_e32 v12, v77, v77
	v_pk_mul_f32 v[10:11], v[2:3], v[10:11]
	v_add_f32_e32 v91, v46, v21
	v_fmac_f32_e32 v12, v79, v79
	v_fma_f32 v11, v81, v97, v11
	v_add_f32_e32 v98, v48, v43
	v_fmac_f32_e32 v12, v91, v91
	v_add_f32_e32 v88, v10, v11
	v_and_b32_e32 v11, 0xffff0000, v36
	v_and_b32_e32 v10, 0xffff0000, v40
	v_fmac_f32_e32 v12, v98, v98
	v_and_b32_e32 v4, 0xffff0000, v4
	v_pk_mul_f32 v[10:11], v[2:3], v[10:11]
	v_fmac_f32_e32 v12, v99, v99
	v_fma_f32 v4, v81, v4, v11
	v_add_f32_e32 v89, v10, v4
	v_lshlrev_b32_e32 v11, 16, v37
	v_lshlrev_b32_e32 v10, 16, v41
	v_fmac_f32_e32 v12, v84, v84
	v_lshlrev_b32_e32 v13, 16, v5
	v_pk_mul_f32 v[10:11], v[2:3], v[10:11]
	v_fmac_f32_e32 v12, v85, v85
	v_fma_f32 v4, v81, v13, v11
	v_fmac_f32_e32 v12, v86, v86
	v_add_f32_e32 v90, v10, v4
	v_and_b32_e32 v10, 0xffff0000, v5
	v_and_b32_e32 v5, 0xffff0000, v37
	v_and_b32_e32 v4, 0xffff0000, v41
	v_fmac_f32_e32 v12, v87, v87
	v_pk_mul_f32 v[2:3], v[2:3], v[4:5]
	v_fmac_f32_e32 v12, v88, v88
	global_load_dwordx4 v[40:43], v[60:61], off
	global_load_dwordx4 v[14:17], v[60:61], off offset:16
	v_fma_f32 v3, v81, v10, v3
	v_fmac_f32_e32 v12, v89, v89
	v_add_f32_e32 v82, v2, v3
	v_fmac_f32_e32 v12, v90, v90
	v_fmac_f32_e32 v12, v82, v82
	ds_bpermute_b32 v2, v140, v12
	v_and_b32_e32 v34, 0xffff0000, v25
	v_lshlrev_b32_e32 v35, 16, v25
	v_lshlrev_b32_e32 v44, 16, v26
	v_and_b32_e32 v46, 0xffff0000, v26
	s_waitcnt lgkmcnt(0)
	v_add_f32_e32 v2, v12, v2
	ds_bpermute_b32 v3, v141, v2
	v_lshlrev_b32_e32 v48, 16, v27
	v_and_b32_e32 v76, 0xffff0000, v27
	v_lshlrev_b32_e32 v78, 16, v28
	v_and_b32_e32 v80, 0xffff0000, v28
	s_waitcnt lgkmcnt(0)
	v_add_f32_e32 v2, v2, v3
	ds_bpermute_b32 v3, v142, v2
	v_mul_f32_e32 v37, 0xbfb8aa3b, v80
	v_exp_f32_e32 v37, v37
	v_lshlrev_b32_e32 v92, 16, v29
	v_pk_mul_f32 v[38:39], v[34:35], v[34:35]
	s_waitcnt lgkmcnt(0)
	v_add_f32_e32 v2, v2, v3
	ds_bpermute_b32 v3, v143, v2
	s_waitcnt lgkmcnt(0)
	v_add_f32_e32 v4, v2, v3
	ds_bpermute_b32 v5, v144, v4
	v_lshl_add_u64 v[2:3], s[44:45], 0, v[54:55]
	v_lshlrev_b64 v[2:3], 8, v[2:3]
	v_lshl_add_u64 v[2:3], v[50:51], 0, v[2:3]
	s_waitcnt lgkmcnt(0)
	v_add_f32_e32 v10, v4, v5
	ds_bpermute_b32 v11, v145, v10
	v_lshl_add_u64 v[4:5], s[44:45], 0, v[56:57]
	v_lshlrev_b64 v[4:5], 8, v[4:5]
	s_lshl_b64 s[44:45], s[44:45], 12
	s_waitcnt lgkmcnt(0)
	v_add_f32_e32 v10, v10, v11
	v_fmamk_f32 v10, v10, 0x3a800000, v215
	v_mul_f32_e32 v11, 0x4f800000, v10
	v_cmp_gt_f32_e32 vcc, s33, v10
	s_waitcnt vmcnt(1)
	v_mov_b32_e32 v95, v40
	v_cndmask_b32_e32 v18, v10, v11, vcc
	v_sqrt_f32_e32 v19, v18
	v_lshl_add_u64 v[10:11], v[50:51], 0, v[4:5]
	global_load_dwordx4 v[2:5], v[2:3], off
	s_nop 0
	global_load_dwordx4 v[10:13], v[10:11], off
	v_add_u32_e32 v20, -1, v19
	v_fma_f32 v21, -v20, v19, v18
	v_cmp_ge_f32_e64 s[0:1], 0, v21
	v_add_u32_e32 v21, 1, v19
	s_nop 0
	v_cndmask_b32_e64 v20, v19, v20, s[0:1]
	v_fma_f32 v19, -v21, v19, v18
	v_cmp_lt_f32_e64 s[0:1], 0, v19
	s_nop 1
	v_cndmask_b32_e64 v19, v20, v21, s[0:1]
	v_mul_f32_e32 v20, 0x37800000, v19
	v_cndmask_b32_e32 v19, v19, v20, vcc
	v_cmp_class_f32_e32 vcc, v18, v216
	s_nop 1
	v_cndmask_b32_e32 v18, v19, v18, vcc
	v_div_scale_f32 v19, s[0:1], v18, v18, 1.0
	v_rcp_f32_e32 v20, v19
	s_nop 0
	v_fma_f32 v21, -v19, v20, 1.0
	v_fmac_f32_e32 v20, v21, v20
	v_div_scale_f32 v21, vcc, 1.0, v18, 1.0
	v_mul_f32_e32 v25, v21, v20
	v_fma_f32 v36, -v19, v25, v21
	v_fmac_f32_e32 v25, v36, v20
	v_fma_f32 v19, -v19, v25, v21
	v_div_fmas_f32 v19, v19, v20, v25
	v_div_fixup_f32 v83, v19, v18, 1.0
	v_mul_f32_e32 v18, 0xbfb8aa3b, v44
	v_exp_f32_e32 v25, v18
	v_mul_f32_e32 v47, v47, v83
	v_mul_f32_e32 v49, v49, v83
	v_mul_f32_e32 v77, v77, v83
	v_add_f32_e32 v25, 1.0, v25
	v_rcp_f32_e32 v94, v25
	v_mul_f32_e32 v25, 0xbfb8aa3b, v46
	v_exp_f32_e32 v25, v25
	v_mul_f32_e32 v79, v79, v83
	v_mul_f32_e32 v81, v91, v83
	v_and_b32_e32 v36, 0xffff0000, v29
	v_add_f32_e32 v25, 1.0, v25
	v_rcp_f32_e32 v40, v25
	v_mul_f32_e32 v25, 0xbfb8aa3b, v48
	v_exp_f32_e32 v25, v25
	v_mul_f32_e32 v93, v98, v83
	v_pk_mul_f32 v[40:41], v[40:41], v[46:47]
	v_lshlrev_b32_e32 v46, 16, v8
	v_add_f32_e32 v25, 1.0, v25
	v_mul_f32_e32 v105, v40, v41
	v_rcp_f32_e32 v40, v25
	v_mul_f32_e32 v25, 0xbfb8aa3b, v76
	v_exp_f32_e32 v25, v25
	v_mov_b32_e32 v41, v42
	v_pk_mul_f32 v[40:41], v[40:41], v[48:49]
	v_mul_f32_e32 v45, v45, v83
	v_add_f32_e32 v25, 1.0, v25
	v_rcp_f32_e32 v42, v25
	v_mul_f32_e32 v25, 0xbfb8aa3b, v78
	v_exp_f32_e32 v25, v25
	v_mul_f32_e32 v106, v40, v41
	v_pk_mul_f32 v[40:41], v[42:43], v[76:77]
	v_pk_mul_f32 v[44:45], v[94:95], v[44:45]
	v_add_f32_e32 v25, 1.0, v25
	v_mul_f32_e32 v107, v40, v41
	v_rcp_f32_e32 v40, v25
	s_waitcnt vmcnt(2)
; __device__ __forceinline__ float bflo(unsigned w) { return __uint_as_float(w << 16); }
; __device__ __forceinline__ void gate_row(int m, int lane, const bf16_t* __restrict__ YA, const bf16_t* __restrict__ YB, const float* __restrict__ LSE, const bf16_t* __restrict__ PROJ, ...
;     ...
;     float ya[2][8], yb[2][8]; float ssa = 0.f, ssb = 0.f;
; #pragma unroll
;     for (int j = 0; j < 2; ++j) {
;         ya[j][0] = bflo(a[j].x); ya[j][1] = bfhi(a[j].x); ya[j][2] = bflo(a[j].y); ya[j][3] = bfhi(a[j].y); ya[j][4] = bflo(a[j].z); ya[j][5] = bfhi(a[j].z); ya[j][6] = bflo(a[j].w); ya[j][7] = bfhi(a[j].w);
;         const float mx = fmaxf(l0[j], fmaxf(l1[j], l2[j])); const float e0 = __builtin_amdgcn_exp2f(l0[j] - mx), e1 = __builtin_amdgcn_exp2f(l1[j] - mx), e2 = __builtin_amdgcn_exp2f(l2[j] - mx);
;         const float inv = __builtin_amdgcn_rcpf(e0 + e1 + e2); const float w0 = e0 * inv, w1 = e1 * inv, w2 = e2 * inv;
;         yb[j][0] = w0 * bflo(b0[j].x) + w1 * bflo(b1[j].x) + w2 * bflo(b2[j].x); yb[j][1] = w0 * bfhi(b0[j].x) + w1 * bfhi(b1[j].x) + w2 * bfhi(b2[j].x);
;         yb[j][2] = w0 * bflo(b0[j].y) + w1 * bflo(b1[j].y) + w2 * bflo(b2[j].y); yb[j][3] = w0 * bfhi(b0[j].y) + w1 * bfhi(b1[j].y) + w2 * bfhi(b2[j].y);
;         yb[j][4] = w0 * bflo(b0[j].z) + w1 * bflo(b1[j].z) + w2 * bflo(b2[j].z); yb[j][5] = w0 * bfhi(b0[j].z) + w1 * bfhi(b1[j].z) + w2 * bfhi(b2[j].z);
;         yb[j][6] = w0 * bflo(b0[j].w) + w1 * bflo(b1[j].w) + w2 * bflo(b2[j].w); yb[j][7] = w0 * bfhi(b0[j].w) + w1 * bfhi(b1[j].w) + w2 * bfhi(b2[j].w);
; #pragma unroll
;         for (int i = 0; i < 8; ++i) { ssa += ya[j][i] * ya[j][i]; ssb += yb[j][i] * yb[j][i]; } }
;     const float ra = 1.0f / sqrtf(wave_sum(ssa) * (1.0f / DA) + EPS), rb = 1.0f / sqrtf(wave_sum(ssb) * (1.0f / DB) + EPS);
; #pragma unroll
;     for (int j = 0; j < 2; ++j) { const int c = lane + 64 * j;
;         const float gaf[8] = {bflo(ga[j].x), bfhi(ga[j].x), bflo(ga[j].y), bfhi(ga[j].y), bflo(ga[j].z), bfhi(ga[j].z), bflo(ga[j].w), bfhi(ga[j].w)};
;         const float gbf[8] = {bflo(gb[j].x), bfhi(gb[j].x), bflo(gb[j].y), bfhi(gb[j].y), bflo(gb[j].z), bfhi(gb[j].z), bflo(gb[j].w), bfhi(gb[j].w)};
;         const f32x4 wa0 = *(const f32x4*)(wa + 8 * c), wa1 = *(const f32x4*)(wa + 8 * c + 4), wb0 = *(const f32x4*)(wb + 8 * c), wb1 = *(const f32x4*)(wb + 8 * c + 4);
;         float za[8], zb[8];
; #pragma unroll
	v_mov_b32_e32 v41, v14
	v_add_f32_e32 v14, 1.0, v37
	v_rcp_f32_e32 v14, v14
	v_pk_mul_f32 v[40:41], v[40:41], v[78:79]
	v_mul_f32_e32 v104, v44, v45
	v_mul_f32_e32 v108, v40, v41
	v_pk_mul_f32 v[14:15], v[14:15], v[80:81]
	v_lshlrev_b32_e32 v40, 16, v9
	v_mul_f32_e32 v91, v14, v15
	v_mul_f32_e32 v14, 0xbfb8aa3b, v92
	v_mul_f32_e32 v15, 0xbfb8aa3b, v40
	v_exp_f32_e32 v14, v14
	v_exp_f32_e32 v15, v15
	v_lshlrev_b32_e32 v41, 16, v33
	v_and_b32_e32 v45, 0xffff0000, v33
	v_add_f32_e32 v14, 1.0, v14
	v_add_f32_e32 v15, 1.0, v15
	v_rcp_f32_e32 v14, v14
	v_rcp_f32_e32 v42, v15
	v_mul_f32_e32 v15, 0xbfb8aa3b, v36
	v_exp_f32_e32 v25, v15
	v_mov_b32_e32 v15, v16
	v_pk_mul_f32 v[14:15], v[14:15], v[92:93]
	v_lshlrev_b32_e32 v93, 16, v30
	v_mul_f32_e32 v14, v14, v15
	v_add_f32_e32 v15, 1.0, v25
	v_rcp_f32_e32 v16, v15
	v_mul_f32_e32 v15, 0xbfb8aa3b, v46
	v_exp_f32_e32 v15, v15
	v_and_b32_e32 v44, 0xffff0000, v9
	v_lshlrev_b32_e32 v79, 16, v31
	v_and_b32_e32 v81, 0xffff0000, v31
	v_add_f32_e32 v9, 1.0, v15
	v_and_b32_e32 v95, 0xffff0000, v30
	v_lshlrev_b32_e32 v15, 16, v23
	v_and_b32_e32 v31, 0xffff0000, v23
	v_lshlrev_b32_e32 v23, 16, v22
	v_and_b32_e32 v33, 0xffff0000, v22
	v_mul_f32_e32 v22, v93, v93
	v_fmac_f32_e32 v22, v95, v95
	global_load_dwordx4 v[18:21], v[58:59], off offset:16
	global_load_dwordx4 v[26:29], v[58:59], off
	v_fmac_f32_e32 v22, v79, v79
	v_lshlrev_b32_e32 v47, 16, v32
	v_fmac_f32_e32 v22, v81, v81
	v_and_b32_e32 v49, 0xffff0000, v32
	v_fmac_f32_e32 v22, v47, v47
	v_fmac_f32_e32 v22, v49, v49
	v_fmac_f32_e32 v22, v41, v41
	v_fmac_f32_e32 v22, v45, v45
	v_fmac_f32_e32 v22, v23, v23
	v_fmac_f32_e32 v22, v33, v33
	v_fmac_f32_e32 v22, v15, v15
	v_rcp_f32_e32 v76, v9
	v_lshlrev_b32_e32 v9, 16, v24
	v_fmac_f32_e32 v22, v31, v31
	v_and_b32_e32 v25, 0xffff0000, v24
	v_fmac_f32_e32 v22, v9, v9
	v_fmac_f32_e32 v22, v25, v25
	v_add_f32_e32 v22, v39, v22
	v_add_f32_e32 v22, v38, v22
	ds_bpermute_b32 v24, v140, v22
	v_and_b32_e32 v48, 0xffff0000, v8
	v_mul_f32_e32 v8, 0xbfb8aa3b, v48
	v_lshlrev_b32_e32 v78, 16, v7
	v_exp_f32_e32 v8, v8
	s_waitcnt lgkmcnt(0)
	v_add_f32_e32 v22, v22, v24
	ds_bpermute_b32 v24, v141, v22
	v_mul_f32_e32 v30, 0xbfb8aa3b, v78
	v_exp_f32_e32 v30, v30
	v_add_f32_e32 v8, 1.0, v8
	v_and_b32_e32 v80, 0xffff0000, v7
	s_waitcnt lgkmcnt(0)
	v_add_f32_e32 v22, v22, v24
	ds_bpermute_b32 v24, v142, v22
	v_rcp_f32_e32 v38, v8
	v_add_f32_e32 v8, 1.0, v30
	v_mul_f32_e32 v7, 0xbfb8aa3b, v80
	v_lshlrev_b32_e32 v92, 16, v6
	s_waitcnt lgkmcnt(0)
	v_add_f32_e32 v22, v22, v24
	ds_bpermute_b32 v24, v143, v22
	v_exp_f32_e32 v7, v7
	v_mul_f32_e32 v30, 0xbfb8aa3b, v92
	v_rcp_f32_e32 v96, v8
	v_exp_f32_e32 v30, v30
	s_waitcnt lgkmcnt(0)
	v_add_f32_e32 v8, v22, v24
	ds_bpermute_b32 v22, v144, v8
	v_add_f32_e32 v7, 1.0, v7
	v_and_b32_e32 v94, 0xffff0000, v6
	v_rcp_f32_e32 v98, v7
	v_add_f32_e32 v7, 1.0, v30
	v_mul_f32_e32 v6, 0xbfb8aa3b, v94
	v_exp_f32_e32 v24, v6
	v_rcp_f32_e32 v6, v7
	s_waitcnt lgkmcnt(0)
	v_add_f32_e32 v7, v8, v22
	ds_bpermute_b32 v8, v145, v7
	v_add_f32_e32 v22, 1.0, v24
	v_rcp_f32_e32 v100, v22
	v_mul_f32_e32 v22, 0xbfb8aa3b, v44
	v_exp_f32_e32 v22, v22
	s_waitcnt lgkmcnt(0)
	v_add_f32_e32 v7, v7, v8
	v_fmamk_f32 v7, v7, 0x3a800000, v215
	v_mul_f32_e32 v8, 0x4f800000, v7
	v_cmp_gt_f32_e32 vcc, s33, v7
	v_add_f32_e32 v22, 1.0, v22
	v_rcp_f32_e32 v102, v22
	v_cndmask_b32_e32 v7, v7, v8, vcc
	v_sqrt_f32_e32 v8, v7
	v_mul_f32_e32 v37, v99, v83
	v_pk_mul_f32 v[16:17], v[16:17], v[36:37]
	v_mul_f32_e32 v109, v85, v83
	v_add_u32_e32 v22, -1, v8
	v_fma_f32 v24, -v22, v8, v7
	v_cmp_ge_f32_e64 s[0:1], 0, v24
	v_add_u32_e32 v24, 1, v8
	v_mul_f32_e32 v111, v84, v83
	v_cndmask_b32_e64 v22, v8, v22, s[0:1]
	v_fma_f32 v8, -v24, v8, v7
	v_cmp_lt_f32_e64 s[0:1], 0, v8
	s_nop 1
	v_cndmask_b32_e64 v8, v22, v24, s[0:1]
	v_mul_f32_e32 v22, 0x37800000, v8
	v_cndmask_b32_e32 v8, v8, v22, vcc
	v_cmp_class_f32_e32 vcc, v7, v216
	v_mul_f32_e32 v24, v16, v17
	v_lshl_add_u64 v[16:17], v[62:63], 0, s[44:45]
	v_cndmask_b32_e32 v7, v8, v7, vcc
	v_div_scale_f32 v8, s[0:1], v7, v7, 1.0
	v_rcp_f32_e32 v22, v8
	s_nop 0
	v_fma_f32 v30, -v8, v22, 1.0
	v_fmac_f32_e32 v22, v30, v22
	v_div_scale_f32 v30, vcc, 1.0, v7, 1.0
	v_mul_f32_e32 v32, v30, v22
	v_fma_f32 v36, -v8, v32, v30
	v_fmac_f32_e32 v32, v36, v22
	v_fma_f32 v8, -v8, v32, v30
	v_div_fmas_f32 v8, v8, v22, v32
	v_div_fixup_f32 v7, v8, v7, 1.0
	v_pk_mul_f32 v[36:37], v[6:7], v[92:93]
	v_mov_b32_e32 v101, v7
	s_waitcnt vmcnt(0)
; __device__ __forceinline__ unsigned pk2(float lo, float hi) { unsigned r; asm("v_cvt_pk_bf16_f32 %0, %1, %2" : "=v"(r) : "v"(lo), "v"(hi)); return r; }
; __device__ __forceinline__ float bflo(unsigned w) { return __uint_as_float(w << 16); }
; __device__ __forceinline__ float bfhi(unsigned w) { return __uint_as_float(w & 0xffff0000u); }
; __device__ __forceinline__ void gate_row(int m, int lane, const bf16_t* __restrict__ YA, const bf16_t* __restrict__ YB, const float* __restrict__ LSE, const bf16_t* __restrict__ PROJ, ...
;     ...
;     for (int j = 0; j < 2; ++j) { const int c = lane + 64 * j;
;         const float gaf[8] = {bflo(ga[j].x), bfhi(ga[j].x), bflo(ga[j].y), bfhi(ga[j].y), bflo(ga[j].z), bfhi(ga[j].z), bflo(ga[j].w), bfhi(ga[j].w)};
;         const float gbf[8] = {bflo(gb[j].x), bfhi(gb[j].x), bflo(gb[j].y), bfhi(gb[j].y), bflo(gb[j].z), bfhi(gb[j].z), bflo(gb[j].w), bfhi(gb[j].w)};
;         const f32x4 wa0 = *(const f32x4*)(wa + 8 * c), wa1 = *(const f32x4*)(wa + 8 * c + 4), wb0 = *(const f32x4*)(wb + 8 * c), wb1 = *(const f32x4*)(wb + 8 * c + 4);
;         float za[8], zb[8];
; #pragma unroll
;         for (int i = 0; i < 8; ++i) { const float wai = i < 4 ? wa0[i & 3] : wa1[i & 3], wbi = i < 4 ? wb0[i & 3] : wb1[i & 3];
;             const float sa = gaf[i] * __builtin_amdgcn_rcpf(1.0f + __builtin_amdgcn_exp2f(-1.4426950408889634f * gaf[i])), sb = gbf[i] * __builtin_amdgcn_rcpf(1.0f + __builtin_amdgcn_exp2f(-1.4426950408889634f * gbf[i]));
;             za[i] = ya[j][i] * ra * wai * sa; zb[i] = yb[j][i] * rb * wbi * sb; }
;         v4u oa, ob; oa.x = pk2(za[0], za[1]); oa.y = pk2(za[2], za[3]); oa.z = pk2(za[4], za[5]); oa.w = pk2(za[6], za[7]);
;         ob.x = pk2(zb[0], zb[1]); ob.y = pk2(zb[2], zb[3]); ob.z = pk2(zb[4], zb[5]); ob.w = pk2(zb[6], zb[7]);
;         *(v4u*)(H + (size_t)m * DM + 8 * c) = oa; *(v4u*)(H + (size_t)m * DM + DA + 8 * c) = ob; }
	v_mul_f32_e32 v6, v26, v37
	v_mul_f32_e32 v6, v36, v6
	v_pk_mul_f32 v[36:37], v[100:101], v[94:95]
	v_mov_b32_e32 v97, v7
	v_mul_f32_e32 v8, v27, v37
	v_pk_mul_f32 v[26:27], v[96:97], v[78:79]
	v_mov_b32_e32 v99, v7
	v_mul_f32_e32 v22, v28, v27
	v_mul_f32_e32 v22, v26, v22
	v_pk_mul_f32 v[26:27], v[98:99], v[80:81]
	v_mov_b32_e32 v77, v7
	v_mul_f32_e32 v27, v29, v27
	v_mul_f32_e32 v28, v26, v27
	v_pk_mul_f32 v[26:27], v[76:77], v[46:47]
	v_mov_b32_e32 v39, v7
	v_mul_f32_e32 v18, v18, v27
	v_mul_f32_e32 v29, v26, v18
	v_pk_mul_f32 v[26:27], v[38:39], v[48:49]
	v_mov_b32_e32 v43, v7
	v_mul_f32_e32 v18, v19, v27
	v_mul_f32_e32 v26, v26, v18
	v_pk_mul_f32 v[18:19], v[42:43], v[40:41]
	v_mov_b32_e32 v103, v7
	v_mul_f32_e32 v19, v20, v19
	v_mul_f32_e32 v27, v18, v19
	v_pk_mul_f32 v[18:19], v[102:103], v[44:45]
	v_mul_f32_e32 v8, v36, v8
	v_mul_f32_e32 v19, v21, v19
	v_mul_f32_e32 v21, v18, v19
	v_cvt_pk_bf16_f32 v18, v6, v8
	v_cvt_pk_bf16_f32 v19, v22, v28
	v_cvt_pk_bf16_f32 v20, v29, v26
	v_cvt_pk_bf16_f32 v21, v27, v21
	v_cvt_pk_bf16_f32 v26, v104, v105
	v_cvt_pk_bf16_f32 v27, v106, v107
	v_cvt_pk_bf16_f32 v28, v108, v91
	v_cvt_pk_bf16_f32 v29, v14, v24
	global_store_dwordx4 v[16:17], v[18:21], off sc1
	global_store_dwordx4 v[16:17], v[26:29], off offset:2048 sc1
	global_load_dwordx4 v[18:21], v[60:61], off offset:2064
	v_lshlrev_b32_e32 v40, 16, v13
	global_load_dwordx4 v[26:29], v[58:59], off offset:2064
	global_load_dwordx4 v[36:39], v[58:59], off offset:2048
	v_mul_f32_e32 v45, v90, v83
	v_lshlrev_b32_e32 v48, 16, v10
	v_and_b32_e32 v76, 0xffff0000, v10
	v_lshlrev_b32_e32 v78, 16, v11
	v_and_b32_e32 v80, 0xffff0000, v11
	v_lshlrev_b32_e32 v90, 16, v12
	v_and_b32_e32 v92, 0xffff0000, v12
	v_and_b32_e32 v94, 0xffff0000, v13
	global_load_dwordx4 v[10:13], v[60:61], off offset:2048
	v_mul_f32_e32 v6, 0xbfb8aa3b, v40
	v_lshlrev_b32_e32 v42, 16, v5
	v_exp_f32_e32 v6, v6
	v_mul_f32_e32 v8, 0xbfb8aa3b, v42
	v_exp_f32_e32 v8, v8
	v_and_b32_e32 v96, 0xffff0000, v5
	v_add_f32_e32 v6, 1.0, v6
	v_rcp_f32_e32 v44, v6
	v_add_f32_e32 v6, 1.0, v8
	v_mul_f32_e32 v5, 0xbfb8aa3b, v92
	v_rcp_f32_e32 v46, v6
	v_exp_f32_e32 v5, v5
	v_mul_f32_e32 v6, 0xbfb8aa3b, v90
	v_exp_f32_e32 v6, v6
	v_lshlrev_b32_e32 v8, 16, v4
	v_add_f32_e32 v5, 1.0, v5
	v_rcp_f32_e32 v98, v5
	v_add_f32_e32 v5, 1.0, v6
	v_rcp_f32_e32 v100, v5
	v_mul_f32_e32 v5, 0xbfb8aa3b, v8
	v_exp_f32_e32 v5, v5
	v_mul_f32_e32 v101, v88, v83
	v_and_b32_e32 v30, 0xffff0000, v3
	v_lshlrev_b32_e32 v14, 16, v3
	v_add_f32_e32 v5, 1.0, v5
	v_rcp_f32_e32 v88, v5
	v_mul_f32_e32 v5, 0xbfb8aa3b, v78
	v_exp_f32_e32 v5, v5
	v_mul_f32_e32 v3, 0xbfb8aa3b, v30
	v_exp_f32_e32 v3, v3
	v_mul_f32_e32 v105, v86, v83
	v_add_f32_e32 v5, 1.0, v5
	v_rcp_f32_e32 v104, v5
	v_mul_f32_e32 v5, 0xbfb8aa3b, v14
	v_exp_f32_e32 v5, v5
	v_add_f32_e32 v3, 1.0, v3
	v_rcp_f32_e32 v86, v3
	v_and_b32_e32 v24, 0xffff0000, v4
	v_add_f32_e32 v3, 1.0, v5
	v_mul_f32_e32 v5, 0xbfb8aa3b, v76
	v_exp_f32_e32 v5, v5
	v_mul_f32_e32 v4, 0xbfb8aa3b, v24
	v_exp_f32_e32 v4, v4
	v_and_b32_e32 v32, 0xffff0000, v2
	v_add_f32_e32 v5, 1.0, v5
	v_rcp_f32_e32 v108, v5
	v_mul_f32_e32 v5, 0xbfb8aa3b, v32
	v_add_f32_e32 v4, 1.0, v4
	v_mul_f32_e32 v6, 0xbfb8aa3b, v80
	v_rcp_f32_e32 v106, v3
	v_mul_f32_e32 v3, 0xbfb8aa3b, v48
	v_exp_f32_e32 v5, v5
	v_rcp_f32_e32 v4, v4
	v_exp_f32_e32 v6, v6
	v_exp_f32_e32 v3, v3
	v_lshlrev_b32_e32 v22, 16, v2
	v_add_f32_e32 v2, 1.0, v5
	v_mov_b32_e32 v5, v7
	v_add_f32_e32 v6, 1.0, v6
	v_add_f32_e32 v3, 1.0, v3
	v_pk_mul_f32 v[4:5], v[4:5], v[24:25]
	v_rcp_f32_e32 v102, v6
	v_rcp_f32_e32 v110, v3
	v_mul_f32_e32 v99, v89, v83
	v_mov_b32_e32 v89, v7
	v_mul_f32_e32 v103, v87, v83
	v_mov_b32_e32 v87, v7
	s_waitcnt vmcnt(3)
	v_mov_b32_e32 v91, v18
	v_mov_b32_e32 v107, v7
	s_waitcnt vmcnt(2)
	v_mul_f32_e32 v3, v5, v27
	v_mul_f32_e32 v24, v4, v3
	v_pk_mul_f32 v[4:5], v[100:101], v[90:91]
	v_rcp_f32_e32 v2, v2
	v_mul_f32_e32 v18, v4, v5
	v_pk_mul_f32 v[4:5], v[88:89], v[8:9]
	v_mov_b32_e32 v41, v20
	v_mul_f32_e32 v3, v5, v26
	v_mul_f32_e32 v8, v4, v3
	v_mov_b32_e32 v97, v29
	s_waitcnt vmcnt(0)
	v_mov_b32_e32 v81, v13
	v_pk_mul_f32 v[4:5], v[102:103], v[80:81]
	v_mov_b32_e32 v79, v12
	v_mul_f32_e32 v9, v4, v5
	v_pk_mul_f32 v[4:5], v[86:87], v[30:31]
	v_mov_b32_e32 v77, v11
	v_mul_f32_e32 v3, v5, v39
	v_mul_f32_e32 v13, v4, v3
	v_pk_mul_f32 v[4:5], v[104:105], v[78:79]
	v_mov_b32_e32 v49, v10
	v_mul_f32_e32 v12, v4, v5
	v_pk_mul_f32 v[4:5], v[106:107], v[14:15]
	v_pk_mul_f32 v[40:41], v[44:45], v[40:41]
	v_mul_f32_e32 v3, v5, v38
	v_mul_f32_e32 v14, v4, v3
	v_pk_mul_f32 v[4:5], v[108:109], v[76:77]
	v_mov_b32_e32 v3, v7
	v_mul_f32_e32 v11, v4, v5
	v_mul_f32_e32 v4, 0xbfb8aa3b, v22
	v_exp_f32_e32 v4, v4
	v_pk_mul_f32 v[2:3], v[2:3], v[32:33]
	v_mul_f32_e32 v5, 0xbfb8aa3b, v94
	v_mul_f32_e32 v3, v3, v37
	v_mul_f32_e32 v15, v2, v3
	v_add_f32_e32 v2, 1.0, v4
	v_rcp_f32_e32 v6, v2
	v_mul_f32_e32 v4, 0xbfb8aa3b, v96
	v_exp_f32_e32 v4, v4
	v_pk_mul_f32 v[2:3], v[110:111], v[48:49]
	v_exp_f32_e32 v5, v5
	v_mul_f32_e32 v10, v2, v3
	v_pk_mul_f32 v[2:3], v[6:7], v[22:23]
	v_mul_f32_e32 v47, v7, v35
	v_mul_f32_e32 v3, v3, v36
	v_mul_f32_e32 v6, v2, v3
	v_add_f32_e32 v2, 1.0, v4
	v_rcp_f32_e32 v2, v2
	v_add_f32_e32 v3, 1.0, v5
	v_rcp_f32_e32 v4, v3
	v_mul_f32_e32 v3, v7, v34
	v_mov_b32_e32 v43, v28
	v_pk_mul_f32 v[2:3], v[2:3], v[96:97]
	v_mul_f32_e32 v5, v82, v83
	v_mov_b32_e32 v95, v21
	v_mul_f32_e32 v20, v40, v41
	v_pk_mul_f32 v[40:41], v[46:47], v[42:43]
	v_mov_b32_e32 v93, v19
	v_mul_f32_e32 v7, v2, v3
	v_pk_mul_f32 v[2:3], v[4:5], v[94:95]
	v_mul_f32_e32 v28, v40, v41
	v_pk_mul_f32 v[40:41], v[98:99], v[92:93]
	v_mul_f32_e32 v21, v2, v3
	v_cvt_pk_bf16_f32 v2, v6, v15
	v_cvt_pk_bf16_f32 v3, v14, v13
	v_cvt_pk_bf16_f32 v4, v8, v24
	v_cvt_pk_bf16_f32 v5, v28, v7
	v_mul_f32_e32 v19, v40, v41
	v_cvt_pk_bf16_f32 v6, v10, v11
	v_cvt_pk_bf16_f32 v7, v12, v9
	v_cvt_pk_bf16_f32 v8, v18, v19
	v_cvt_pk_bf16_f32 v9, v20, v21
	global_store_dwordx4 v[16:17], v[2:5], off offset:1024 sc1
	global_store_dwordx4 v[16:17], v[6:9], off offset:3072 sc1
	s_branch .LBB0_40

; __device__ __forceinline__ int crow(int r, int hi) { return (r & 3) + 8 * (r >> 2) + 4 * hi; }
;     ...
;   if (hi == 0) li_l[r32] = l_reg; asm volatile("s_waitcnt lgkmcnt(0)" ::: "memory");
;   if constexpr (DIL) { if (hi == 0) lse_o[(long)(wid * QBLK + r32) * lse_s] = m_reg + __log2f(l_reg); }
;   float rli[16];
; #pragma unroll
;   for (int r = 0; r < 16; ++r) rli[r] = __builtin_amdgcn_rcpf(li_l[crow(r, hi)]);
;   bf16* Ow = Ob + (long)(wid * QBLK) * os;
;     ...
;   { char* stg = DIL ? ((wid < 4 ? K_lds : V_lds) + 2 * SHM_K + (wid & 3) * 8192) : (K_lds + wid * 8192);
; #pragma unroll
;     for (int r = 0; r < 16; ++r) { const int orow = crow(r, hi);
; #pragma unroll
;       for (int d0 = 0; d0 < 4; ++d0) *(bf16*)(stg + orow * 256 + (d0 * 32 + r32) * 2) = __float2bfloat16(o[d0][r] * rli[r]); }
.LBB0_48:
	s_or_b64 exec, exec, s[0:1]
	s_waitcnt lgkmcnt(0)
	v_add_u32_e32 v0, s12, v0
	ds_read_b128 v[66:69], v0
	ds_read_b128 v[70:73], v0 offset:32
	s_lshl_b64 s[0:1], s[2:3], 24
	s_add_u32 s0, s52, s0
	s_addc_u32 s1, s8, s1
	s_lshl_b32 s2, s51, 11
	s_waitcnt lgkmcnt(0)
	v_rcp_f32_e32 v74, v66
	v_rcp_f32_e32 v75, v67
	v_rcp_f32_e32 v76, v68
	v_rcp_f32_e32 v77, v69
	v_rcp_f32_e32 v78, v70
	ds_read_b128 v[66:69], v0 offset:64
	v_rcp_f32_e32 v79, v71
	v_rcp_f32_e32 v80, v72
	v_rcp_f32_e32 v81, v73
	ds_read_b128 v[70:73], v0 offset:96
	s_add_u32 s0, s0, s2
	s_addc_u32 s1, s1, 0
	s_lshl_b32 s2, s11, 8
	s_add_u32 s2, s0, s2
	s_addc_u32 s3, s1, 0
	s_ashr_i32 s51, s50, 31
	s_lshl_b32 s10, s10, 13
	s_waitcnt lgkmcnt(0)
	v_rcp_f32_e32 v0, v66
	v_rcp_f32_e32 v66, v67
	v_rcp_f32_e32 v67, v68
	v_rcp_f32_e32 v68, v69
	v_rcp_f32_e32 v69, v70
	v_rcp_f32_e32 v70, v71
	v_rcp_f32_e32 v71, v72
	v_rcp_f32_e32 v72, v73
	s_lshl_b64 s[0:1], s[50:51], 11
	s_add_i32 s10, s10, 0
	v_lshlrev_b32_e32 v73, 10, v233
	v_lshlrev_b32_e32 v82, 1, v232
	v_mul_f32_e32 v2, v2, v74
	v_add3_u32 v73, s10, v73, v82
	v_cvt_pk_bf16_f32 v2, v2, s0
	ds_write_b16 v73, v2
	v_mul_f32_e32 v2, v50, v74
	v_cvt_pk_bf16_f32 v2, v2, s0
	ds_write_b16 v73, v2 offset:64
	v_mul_f32_e32 v2, v34, v74
	v_cvt_pk_bf16_f32 v2, v2, s0
	ds_write_b16 v73, v2 offset:128
	v_mul_f32_e32 v2, v18, v74
	v_cvt_pk_bf16_f32 v2, v2, s0
	ds_write_b16 v73, v2 offset:192
	v_mul_f32_e32 v2, v3, v75
	v_cvt_pk_bf16_f32 v2, v2, s0
	ds_write_b16 v73, v2 offset:256
	v_mul_f32_e32 v2, v51, v75
	v_cvt_pk_bf16_f32 v2, v2, s0
	ds_write_b16 v73, v2 offset:320
	v_mul_f32_e32 v2, v35, v75
	v_cvt_pk_bf16_f32 v2, v2, s0
	ds_write_b16 v73, v2 offset:384
	v_mul_f32_e32 v2, v19, v75
	v_cvt_pk_bf16_f32 v2, v2, s0
	ds_write_b16 v73, v2 offset:448
	v_mul_f32_e32 v2, v4, v76
	v_cvt_pk_bf16_f32 v2, v2, s0
	ds_write_b16 v73, v2 offset:512
	v_mul_f32_e32 v2, v52, v76
	v_cvt_pk_bf16_f32 v2, v2, s0
	ds_write_b16 v73, v2 offset:576
	v_mul_f32_e32 v2, v36, v76
	v_cvt_pk_bf16_f32 v2, v2, s0
	ds_write_b16 v73, v2 offset:640
	v_mul_f32_e32 v2, v20, v76
	v_cvt_pk_bf16_f32 v2, v2, s0
	ds_write_b16 v73, v2 offset:704
	v_mul_f32_e32 v2, v5, v77
	v_cvt_pk_bf16_f32 v2, v2, s0
	ds_write_b16 v73, v2 offset:768
	v_mul_f32_e32 v2, v53, v77
	v_cvt_pk_bf16_f32 v2, v2, s0
	ds_write_b16 v73, v2 offset:832
	v_mul_f32_e32 v2, v37, v77
	v_cvt_pk_bf16_f32 v2, v2, s0
	ds_write_b16 v73, v2 offset:896
	v_mul_f32_e32 v2, v21, v77
	v_cvt_pk_bf16_f32 v2, v2, s0
	ds_write_b16 v73, v2 offset:960
	v_mul_f32_e32 v2, v6, v78
	v_cvt_pk_bf16_f32 v2, v2, s0
	ds_write_b16 v73, v2 offset:2048
	v_mul_f32_e32 v2, v54, v78
	v_cvt_pk_bf16_f32 v2, v2, s0
	ds_write_b16 v73, v2 offset:2112
	v_mul_f32_e32 v2, v38, v78
	v_cvt_pk_bf16_f32 v2, v2, s0
	ds_write_b16 v73, v2 offset:2176
	v_mul_f32_e32 v2, v22, v78
	v_cvt_pk_bf16_f32 v2, v2, s0
	ds_write_b16 v73, v2 offset:2240
	v_mul_f32_e32 v2, v7, v79
	v_cvt_pk_bf16_f32 v2, v2, s0
	ds_write_b16 v73, v2 offset:2304
	v_mul_f32_e32 v2, v55, v79
	v_cvt_pk_bf16_f32 v2, v2, s0
	ds_write_b16 v73, v2 offset:2368
	v_mul_f32_e32 v2, v39, v79
	v_cvt_pk_bf16_f32 v2, v2, s0
	ds_write_b16 v73, v2 offset:2432
	v_mul_f32_e32 v2, v23, v79
	v_cvt_pk_bf16_f32 v2, v2, s0
	ds_write_b16 v73, v2 offset:2496
	v_mul_f32_e32 v2, v8, v80
	v_cvt_pk_bf16_f32 v2, v2, s0
	ds_write_b16 v73, v2 offset:2560
	v_mul_f32_e32 v2, v56, v80
	v_cvt_pk_bf16_f32 v2, v2, s0
	ds_write_b16 v73, v2 offset:2624
	v_mul_f32_e32 v2, v40, v80
	v_cvt_pk_bf16_f32 v2, v2, s0
	ds_write_b16 v73, v2 offset:2688
	v_mul_f32_e32 v2, v24, v80
	v_cvt_pk_bf16_f32 v2, v2, s0
	ds_write_b16 v73, v2 offset:2752
	v_mul_f32_e32 v2, v9, v81
	v_cvt_pk_bf16_f32 v2, v2, s0
	ds_write_b16 v73, v2 offset:2816
	v_mul_f32_e32 v2, v57, v81
	v_cvt_pk_bf16_f32 v2, v2, s0
	ds_write_b16 v73, v2 offset:2880
	v_mul_f32_e32 v2, v41, v81
	v_cvt_pk_bf16_f32 v2, v2, s0
	ds_write_b16 v73, v2 offset:2944
	v_mul_f32_e32 v2, v25, v81
	v_cvt_pk_bf16_f32 v2, v2, s0
	ds_write_b16 v73, v2 offset:3008
	v_mul_f32_e32 v2, v10, v0
	v_cvt_pk_bf16_f32 v2, v2, s0
	ds_write_b16 v73, v2 offset:4096
	v_mul_f32_e32 v2, v58, v0
	v_cvt_pk_bf16_f32 v2, v2, s0
	ds_write_b16 v73, v2 offset:4160
	v_mul_f32_e32 v2, v42, v0
	v_mul_f32_e32 v0, v26, v0
	v_cvt_pk_bf16_f32 v0, v0, s0
	ds_write_b16 v73, v0 offset:4288
	v_mul_f32_e32 v0, v11, v66
	v_cvt_pk_bf16_f32 v0, v0, s0
	ds_write_b16 v73, v0 offset:4352
	v_mul_f32_e32 v0, v59, v66
	v_cvt_pk_bf16_f32 v0, v0, s0
	ds_write_b16 v73, v0 offset:4416
	v_mul_f32_e32 v0, v43, v66
	v_cvt_pk_bf16_f32 v0, v0, s0
	ds_write_b16 v73, v0 offset:4480
	v_mul_f32_e32 v0, v27, v66
	v_cvt_pk_bf16_f32 v0, v0, s0
	ds_write_b16 v73, v0 offset:4544
	v_mul_f32_e32 v0, v12, v67
	v_cvt_pk_bf16_f32 v0, v0, s0
	ds_write_b16 v73, v0 offset:4608
	v_mul_f32_e32 v0, v60, v67
	v_cvt_pk_bf16_f32 v0, v0, s0
	ds_write_b16 v73, v0 offset:4672
	v_mul_f32_e32 v0, v44, v67
	v_cvt_pk_bf16_f32 v0, v0, s0
	ds_write_b16 v73, v0 offset:4736
	v_mul_f32_e32 v0, v28, v67
	v_cvt_pk_bf16_f32 v0, v0, s0
	ds_write_b16 v73, v0 offset:4800
	v_mul_f32_e32 v0, v13, v68
	v_cvt_pk_bf16_f32 v0, v0, s0
	ds_write_b16 v73, v0 offset:4864
	v_mul_f32_e32 v0, v61, v68
	v_cvt_pk_bf16_f32 v0, v0, s0
	ds_write_b16 v73, v0 offset:4928
	v_mul_f32_e32 v0, v45, v68
	v_cvt_pk_bf16_f32 v0, v0, s0
	ds_write_b16 v73, v0 offset:4992
	v_mul_f32_e32 v0, v29, v68
	v_cvt_pk_bf16_f32 v0, v0, s0
	ds_write_b16 v73, v0 offset:5056
	v_mul_f32_e32 v0, v14, v69
	v_cvt_pk_bf16_f32 v0, v0, s0
	ds_write_b16 v73, v0 offset:6144
	v_mul_f32_e32 v0, v62, v69
	v_cvt_pk_bf16_f32 v0, v0, s0
	ds_write_b16 v73, v0 offset:6208
	v_mul_f32_e32 v0, v46, v69
	v_cvt_pk_bf16_f32 v0, v0, s0
	ds_write_b16 v73, v0 offset:6272
	v_mul_f32_e32 v0, v30, v69
	v_cvt_pk_bf16_f32 v0, v0, s0
	ds_write_b16 v73, v0 offset:6336
	v_mul_f32_e32 v0, v15, v70
	v_cvt_pk_bf16_f32 v0, v0, s0
	ds_write_b16 v73, v0 offset:6400
	v_mul_f32_e32 v0, v63, v70
	v_cvt_pk_bf16_f32 v0, v0, s0
	ds_write_b16 v73, v0 offset:6464
	v_mul_f32_e32 v0, v47, v70
	v_cvt_pk_bf16_f32 v0, v0, s0
	ds_write_b16 v73, v0 offset:6528
	v_mul_f32_e32 v0, v31, v70
	v_cvt_pk_bf16_f32 v0, v0, s0
	ds_write_b16 v73, v0 offset:6592
	v_mul_f32_e32 v0, v16, v71
	v_cvt_pk_bf16_f32 v0, v0, s0
	ds_write_b16 v73, v0 offset:6656
	v_mul_f32_e32 v0, v64, v71
	v_cvt_pk_bf16_f32 v0, v0, s0
	ds_write_b16 v73, v0 offset:6720
	v_mul_f32_e32 v0, v48, v71
	v_cvt_pk_bf16_f32 v0, v0, s0
	ds_write_b16 v73, v0 offset:6784
	v_mul_f32_e32 v0, v32, v71
	v_cvt_pk_bf16_f32 v0, v0, s0
	ds_write_b16 v73, v0 offset:6848
	v_mul_f32_e32 v0, v17, v72
	v_cvt_pk_bf16_f32 v0, v0, s0
	ds_write_b16 v73, v0 offset:6912
	v_mul_f32_e32 v0, v65, v72
	v_cvt_pk_bf16_f32 v0, v0, s0
	ds_write_b16 v73, v0 offset:6976
	v_mul_f32_e32 v0, v49, v72
	v_cvt_pk_bf16_f32 v0, v0, s0
	ds_write_b16 v73, v0 offset:7040
	v_mul_f32_e32 v0, v33, v72
	v_cvt_pk_bf16_f32 v0, v0, s0
	v_cvt_pk_bf16_f32 v2, v2, s0
	ds_write_b16 v73, v0 offset:7104
	s_add_u32 s0, s2, s0
	v_lshlrev_b32_e32 v0, 4, v231
	ds_write_b16 v73, v2 offset:4224
	s_addc_u32 s1, s3, s1
	v_add_u32_e32 v14, s10, v0
	s_waitcnt lgkmcnt(0)
; __device__ __forceinline__ int crow(int r, int hi) { return (r & 3) + 8 * (r >> 2) + 4 * hi; }
;     ...
;     asm volatile("s_waitcnt lgkmcnt(0)" ::: "memory");
; #pragma unroll
;     for (int i = 0; i < 8; ++i) { const int row = i * 4 + (lane >> 4), ch = lane & 15;
;       const u32x4 v = *(const u32x4*)(stg + row * 256 + ch * 16);
;       *(u32x4*)(Ow + (long)row * os + ch * 8) = v; } }
;     ...
; #pragma unroll
;   for (int r = 0; r < 16; ++r) { const int orow = crow(r, hi);
; #pragma unroll
;     for (int d0 = 0; d0 < 4; ++d0) Ow[(long)orow * os + d0 * 32 + r32] = __float2bfloat16(o[d0][r] * rli[r]); }
;     ...
;   asm volatile("s_waitcnt lgkmcnt(0)\n\ts_barrier" ::: "memory");
	v_lshl_add_u64 v[10:11], s[0:1], 0, v[0:1]
	v_lshl_add_u32 v0, v230, 8, v14
	v_or_b32_e32 v15, 4, v230
	ds_read_b128 v[2:5], v0
	v_lshl_add_u32 v6, v15, 8, v14
	ds_read_b128 v[6:9], v6
	v_lshlrev_b32_e32 v0, 11, v230
	v_lshl_add_u64 v[12:13], v[10:11], 0, v[0:1]
	v_lshlrev_b32_e32 v0, 11, v15
	s_waitcnt lgkmcnt(0)
	global_store_dwordx4 v[12:13], v[2:5], off sc1
	v_or_b32_e32 v15, 12, v230
	s_add_i32 s25, s25, s98
	v_lshl_add_u64 v[2:3], v[10:11], 0, v[0:1]
	v_or_b32_e32 v0, 8, v230
	global_store_dwordx4 v[2:3], v[6:9], off sc1
	v_lshl_add_u32 v2, v0, 8, v14
	ds_read_b128 v[2:5], v2
	v_lshl_add_u32 v6, v15, 8, v14
	ds_read_b128 v[6:9], v6
	v_lshlrev_b32_e32 v0, 11, v0
	v_lshl_add_u64 v[12:13], v[10:11], 0, v[0:1]
	v_lshlrev_b32_e32 v0, 11, v15
	s_waitcnt lgkmcnt(0)
	global_store_dwordx4 v[12:13], v[2:5], off sc1
	v_or_b32_e32 v15, 20, v230
	s_cmpk_gt_i32 s25, 0x1ff
	v_lshl_add_u64 v[2:3], v[10:11], 0, v[0:1]
	v_or_b32_e32 v0, 16, v230
	global_store_dwordx4 v[2:3], v[6:9], off sc1
	v_lshl_add_u32 v2, v0, 8, v14
	ds_read_b128 v[2:5], v2
	v_lshl_add_u32 v6, v15, 8, v14
	ds_read_b128 v[6:9], v6
	v_lshlrev_b32_e32 v0, 11, v0
	v_lshl_add_u64 v[12:13], v[10:11], 0, v[0:1]
	v_lshlrev_b32_e32 v0, 11, v15
	s_waitcnt lgkmcnt(0)
	global_store_dwordx4 v[12:13], v[2:5], off sc1
	v_or_b32_e32 v15, 28, v230
	s_nop 0
	v_lshl_add_u64 v[2:3], v[10:11], 0, v[0:1]
	v_or_b32_e32 v0, 24, v230
	global_store_dwordx4 v[2:3], v[6:9], off sc1
	v_lshl_add_u32 v2, v0, 8, v14
	ds_read_b128 v[2:5], v2
	v_lshl_add_u32 v6, v15, 8, v14
	ds_read_b128 v[6:9], v6
	v_lshlrev_b32_e32 v0, 11, v0
	v_lshl_add_u64 v[12:13], v[10:11], 0, v[0:1]
	v_lshlrev_b32_e32 v0, 11, v15
	s_waitcnt lgkmcnt(0)
	global_store_dwordx4 v[12:13], v[2:5], off sc1
	s_nop 1
	v_lshl_add_u64 v[2:3], v[10:11], 0, v[0:1]
	global_store_dwordx4 v[2:3], v[6:9], off sc1
	s_waitcnt lgkmcnt(0)
	s_barrier
	s_cbranch_scc1 .LBB0_124

; __device__ __forceinline__ float bflo(unsigned w) { return __uint_as_float(w << 16); }
; __device__ __forceinline__ float bfhi(unsigned w) { return __uint_as_float(w & 0xffff0000u); }
; __global__ void __launch_bounds__(512, 2) mk_fwd(Params p) {
;     ...
;                 for (int it0 = gw; it0 < NQKI; it0 += QKU * NGW) {
;                     const int j = lane & 15, half = j >> 3, jj = j & 7, e = half * 64 + 4 * jj;
;                     v2u a[QKU], b[QKU]; f32x4 cs[QKU], sn[QKU]; bf16_t* pp[QKU]; bool isq[QKU];
; #pragma unroll
;                     for (int u = 0; u < QKU; ++u) { const int it = min(it0 + u * NGW, NQKI - 1);
;                         const int g = it * 4 + (lane >> 4), row = MK_QFUSE ? (g >> 1) : g / 10, hs = MK_QFUSE ? 8 + (g & 1) : g - row * 10; isq[u] = hs < 8;
;                         pp[u] = PROJ + ((size_t)hs * M + row) * HD + e; a[u] = *(const v2u*)pp[u]; b[u] = *(const v2u*)(pp[u] + 32);
;                         const int t = row & (T - 1), pos = half ? 128 + (t & 63) : (t >> 6);
;                         cs[u] = *(const f32x4*)(RCOS + pos * 32 + 4 * jj); sn[u] = *(const f32x4*)(RSIN + pos * 32 + 4 * jj); }
;                     asm volatile("" ::: "memory");
; #pragma unroll
;                     for (int u = 0; u < QKU; ++u) {
;                         float x1[4] = {bflo(a[u].x), bfhi(a[u].x), bflo(a[u].y), bfhi(a[u].y)}, x2[4] = {bflo(b[u].x), bfhi(b[u].x), bflo(b[u].y), bfhi(b[u].y)};
;                         float ss = 0.f;
; #pragma unroll
;                         for (int i = 0; i < 4; ++i) ss += x1[i] * x1[i] + x2[i] * x2[i];
;                         ss += __shfl_xor(ss, 1); ss += __shfl_xor(ss, 2); ss += __shfl_xor(ss, 4); ss += __shfl_xor(ss, 8);
;                         const float rstd = 1.0f / sqrtf(ss * (1.0f / HD) + EPS);
;                         const float* gn = isq[u] ? qg : kg;
;                         const float qsc = (MK_NEGM && isq[u]) ? att::SCALE * att::LOG2E : 1.0f;
;                         const f32x4 g1 = *(const f32x4*)(gn + e), g2 = *(const f32x4*)(gn + e + 32);
.LBB0_130:
	v_ashrrev_i32_e32 v2, 1, v53
	v_ashrrev_i32_e32 v3, 31, v2
	v_lshl_add_u64 v[4:5], v[2:3], 0, v[26:27]
	v_lshlrev_b64 v[4:5], 8, v[4:5]
	v_lshl_add_u64 v[50:51], v[28:29], 0, v[4:5]
	global_load_dwordx2 v[54:55], v[50:51], off
	global_load_dwordx2 v[56:57], v[50:51], off offset:64
	v_and_or_b32 v0, v2, 63, v226
	v_bfe_u32 v2, v2, 6, 7
	v_cndmask_b32_e64 v0, v0, v2, s[38:39]
	s_add_i32 s12, s26, s9
	v_lshlrev_b32_e32 v0, 7, v0
	s_min_i32 s0, s12, 0x1fff
	v_lshl_add_u64 v[2:3], v[30:31], 0, v[0:1]
	v_lshl_add_u64 v[4:5], v[32:33], 0, v[0:1]
	v_lshl_or_b32 v0, s0, 2, v52
	global_load_dwordx4 v[58:61], v[2:3], off
	global_load_dwordx4 v[62:65], v[4:5], off
	v_ashrrev_i32_e32 v2, 1, v0
	v_ashrrev_i32_e32 v3, 31, v2
	v_lshl_add_u64 v[4:5], v[2:3], 0, v[26:27]
	v_and_or_b32 v0, v2, 63, v226
	v_bfe_u32 v2, v2, 6, 7
	v_cndmask_b32_e64 v0, v0, v2, s[38:39]
	s_add_i32 s11, s3, s9
	v_lshlrev_b64 v[4:5], 8, v[4:5]
	v_lshlrev_b32_e32 v0, 7, v0
	s_min_i32 s0, s11, 0x1fff
	v_lshl_add_u64 v[44:45], v[28:29], 0, v[4:5]
	v_lshl_add_u64 v[2:3], v[30:31], 0, v[0:1]
	v_lshl_add_u64 v[4:5], v[32:33], 0, v[0:1]
	v_lshl_or_b32 v0, s0, 2, v52
	global_load_dwordx4 v[22:25], v[2:3], off
	global_load_dwordx4 v[18:21], v[4:5], off
	v_ashrrev_i32_e32 v2, 1, v0
	v_ashrrev_i32_e32 v3, 31, v2
	v_lshl_add_u64 v[4:5], v[2:3], 0, v[26:27]
	v_and_or_b32 v0, v2, 63, v226
	v_bfe_u32 v2, v2, 6, 7
	s_mul_i32 s10, s98, 24
	v_cndmask_b32_e64 v0, v0, v2, s[38:39]
	s_add_i32 s10, s10, s9
	v_lshlrev_b64 v[4:5], 8, v[4:5]
	v_lshlrev_b32_e32 v0, 7, v0
	s_min_i32 s0, s10, 0x1fff
	v_lshl_add_u64 v[42:43], v[28:29], 0, v[4:5]
	v_lshl_add_u64 v[2:3], v[30:31], 0, v[0:1]
	v_lshl_add_u64 v[4:5], v[32:33], 0, v[0:1]
	v_lshl_or_b32 v0, s0, 2, v52
	global_load_dwordx2 v[74:75], v[44:45], off
	global_load_dwordx2 v[76:77], v[44:45], off offset:64
	global_load_dwordx2 v[48:49], v[42:43], off
	global_load_dwordx2 v[46:47], v[42:43], off offset:64
	global_load_dwordx4 v[14:17], v[2:3], off
	global_load_dwordx4 v[10:13], v[4:5], off
	v_ashrrev_i32_e32 v2, 1, v0
	v_ashrrev_i32_e32 v3, 31, v2
	v_lshl_add_u64 v[4:5], v[2:3], 0, v[26:27]
	v_and_or_b32 v0, v2, 63, v226
	v_bfe_u32 v2, v2, 6, 7
	v_cndmask_b32_e64 v0, v0, v2, s[38:39]
	v_lshlrev_b64 v[4:5], 8, v[4:5]
	v_lshlrev_b32_e32 v0, 7, v0
	v_lshl_add_u64 v[36:37], v[28:29], 0, v[4:5]
	v_lshl_add_u64 v[2:3], v[30:31], 0, v[0:1]
	v_lshl_add_u64 v[4:5], v[32:33], 0, v[0:1]
	global_load_dwordx2 v[40:41], v[36:37], off
	global_load_dwordx2 v[38:39], v[36:37], off offset:64
	global_load_dwordx4 v[6:9], v[2:3], off
	s_nop 0
	global_load_dwordx4 v[2:5], v[4:5], off
	global_load_dwordx4 v[66:69], v[34:35], off
	global_load_dwordx4 v[70:73], v[34:35], off offset:128
	v_cmp_lt_i32_e32 vcc, v220, v219
	s_cmpk_gt_i32 s12, 0x1fff
	s_waitcnt vmcnt(0)
	v_lshlrev_b32_e32 v78, 16, v55
	v_lshlrev_b32_e32 v79, 16, v57
	v_and_b32_e32 v81, 0xffff0000, v57
	v_and_b32_e32 v80, 0xffff0000, v55
	v_lshlrev_b32_e32 v83, 16, v56
	v_and_b32_e32 v85, 0xffff0000, v56
	v_mov_b32_e32 v56, v79
	v_mov_b32_e32 v57, v81
	v_lshlrev_b32_e32 v82, 16, v54
	v_and_b32_e32 v84, 0xffff0000, v54
	v_mov_b32_e32 v54, v78
	v_mov_b32_e32 v55, v80
	v_pk_mul_f32 v[56:57], v[56:57], v[56:57]
	v_mov_b32_e32 v86, v83
	v_mov_b32_e32 v87, v85
	v_pk_fma_f32 v[54:55], v[54:55], v[54:55], v[56:57]
	v_mov_b32_e32 v56, v82
	v_mov_b32_e32 v57, v84
	v_pk_mul_f32 v[86:87], v[86:87], v[86:87]
	v_cndmask_b32_e32 v0, v218, v220, vcc
	v_pk_fma_f32 v[56:57], v[56:57], v[56:57], v[86:87]
	v_lshlrev_b32_e32 v0, 2, v0
	v_add_f32_e32 v56, v56, v57
	v_add_f32_e32 v54, v56, v54
	v_add_f32_e32 v55, v54, v55
	ds_bpermute_b32 v56, v0, v55
	v_cmp_lt_i32_e32 vcc, v221, v219
	v_mov_b32_e32 v92, v62
	v_mov_b32_e32 v93, v58
	v_cndmask_b32_e32 v54, v218, v221, vcc
	v_lshlrev_b32_e32 v54, 2, v54
	s_waitcnt lgkmcnt(0)
	v_add_f32_e32 v56, v55, v56
	ds_bpermute_b32 v57, v54, v56
	v_cmp_lt_i32_e32 vcc, v222, v219
	v_mov_b32_e32 v89, v60
	s_waitcnt lgkmcnt(0)
	v_add_f32_e32 v57, v56, v57
	v_cndmask_b32_e32 v55, v218, v222, vcc
	v_lshlrev_b32_e32 v55, 2, v55
	ds_bpermute_b32 v86, v55, v57
	v_cmp_lt_i32_e32 vcc, v223, v219
	s_waitcnt lgkmcnt(0)
	v_add_f32_e32 v57, v57, v86
	v_cndmask_b32_e32 v56, v218, v223, vcc
	v_lshlrev_b32_e32 v56, 2, v56
	ds_bpermute_b32 v88, v56, v57
	s_waitcnt lgkmcnt(0)
; __device__ __forceinline__ unsigned pk2(float lo, float hi) { unsigned r; asm("v_cvt_pk_bf16_f32 %0, %1, %2" : "=v"(r) : "v"(lo), "v"(hi)); return r; }
; __device__ __forceinline__ float bflo(unsigned w) { return __uint_as_float(w << 16); }
; __device__ __forceinline__ float bfhi(unsigned w) { return __uint_as_float(w & 0xffff0000u); }
; __global__ void __launch_bounds__(512, 2) mk_fwd(Params p) {
;     ...
;                     for (int u = 0; u < QKU; ++u) {
;                         float x1[4] = {bflo(a[u].x), bfhi(a[u].x), bflo(a[u].y), bfhi(a[u].y)}, x2[4] = {bflo(b[u].x), bfhi(b[u].x), bflo(b[u].y), bfhi(b[u].y)};
;                         float ss = 0.f;
; #pragma unroll
;                         for (int i = 0; i < 4; ++i) ss += x1[i] * x1[i] + x2[i] * x2[i];
;                         ss += __shfl_xor(ss, 1); ss += __shfl_xor(ss, 2); ss += __shfl_xor(ss, 4); ss += __shfl_xor(ss, 8);
;                         const float rstd = 1.0f / sqrtf(ss * (1.0f / HD) + EPS);
;                         const float* gn = isq[u] ? qg : kg;
;                         const float qsc = (MK_NEGM && isq[u]) ? att::SCALE * att::LOG2E : 1.0f;
;                         const f32x4 g1 = *(const f32x4*)(gn + e), g2 = *(const f32x4*)(gn + e + 32);
;                         float o1[4], o2[4];
; #pragma unroll
;                         for (int i = 0; i < 4; ++i) { const float y1 = x1[i] * rstd * g1[i], y2 = x2[i] * rstd * g2[i]; o1[i] = (y1 * cs[u][i] - y2 * sn[u][i]) * qsc; o2[i] = (y1 * sn[u][i] + y2 * cs[u][i]) * qsc; }
;                         v2u w1, w2; w1.x = pk2(o1[0], o1[1]); w1.y = pk2(o1[2], o1[3]); w2.x = pk2(o2[0], o2[1]); w2.y = pk2(o2[2], o2[3]);
;                         if (it0 + u * NGW < NQKI) { *(v2u*)pp[u] = w1; *(v2u*)(pp[u] + 32) = w2; }
;                     }
	v_add_f32_e32 v57, v57, v88
	v_fmamk_f32 v57, v57, 0x3c000000, v215
	v_cmp_gt_f32_e32 vcc, s33, v57
	v_mov_b32_e32 v88, v64
	v_mov_b32_e32 v86, v68
	v_mul_f32_e32 v68, 0x4f800000, v57
	v_cndmask_b32_e32 v57, v57, v68, vcc
	v_sqrt_f32_e32 v68, v57
	v_mov_b32_e32 v90, v66
	v_mov_b32_e32 v87, v72
	v_mov_b32_e32 v91, v70
	v_add_u32_e32 v66, -1, v68
	v_fma_f32 v72, -v66, v68, v57
	v_cmp_ge_f32_e64 s[0:1], 0, v72
	v_add_u32_e32 v72, 1, v68
	s_nop 0
	v_cndmask_b32_e64 v66, v68, v66, s[0:1]
	v_fma_f32 v68, -v72, v68, v57
	v_cmp_lt_f32_e64 s[0:1], 0, v68
	s_nop 1
	v_cndmask_b32_e64 v66, v66, v72, s[0:1]
	v_mul_f32_e32 v68, 0x37800000, v66
	v_cndmask_b32_e32 v66, v66, v68, vcc
	v_cmp_class_f32_e32 vcc, v57, v216
	s_nop 1
	v_cndmask_b32_e32 v57, v66, v57, vcc
	v_div_scale_f32 v66, s[0:1], v57, v57, 1.0
	v_rcp_f32_e32 v68, v66
	s_nop 0
	v_fma_f32 v70, -v66, v68, 1.0
	v_fmac_f32_e32 v68, v70, v68
	v_div_scale_f32 v70, vcc, 1.0, v57, 1.0
	v_mul_f32_e32 v72, v70, v68
	v_fma_f32 v94, -v66, v72, v70
	v_fmac_f32_e32 v72, v94, v68
	v_fma_f32 v66, -v66, v72, v70
	v_div_fmas_f32 v66, v66, v68, v72
	v_div_fixup_f32 v66, v66, v57, 1.0
	v_pk_mul_f32 v[82:83], v[66:67], v[82:83] op_sel_hi:[0,1]
	v_pk_mul_f32 v[82:83], v[90:91], v[82:83]
	v_mov_b32_e32 v90, v58
	v_mov_b32_e32 v91, v62
	v_pk_mul_f32 v[90:91], v[90:91], v[82:83]
	v_pk_mul_f32 v[82:83], v[92:93], v[82:83]
	v_mov_b32_e32 v70, v67
	v_add_f32_e32 v68, v82, v83
	v_pk_mul_f32 v[82:83], v[66:67], v[84:85] op_sel_hi:[0,1]
	v_pk_mul_f32 v[70:71], v[70:71], v[82:83]
	v_mov_b32_e32 v62, v59
	v_pk_mul_f32 v[82:83], v[62:63], v[70:71]
	v_mov_b32_e32 v58, v63
	v_sub_f32_e32 v67, v82, v83
	v_pk_mul_f32 v[58:59], v[58:59], v[70:71]
	v_mov_b32_e32 v62, v60
	v_add_f32_e32 v70, v58, v59
	v_pk_mul_f32 v[58:59], v[66:67], v[78:79] op_sel_hi:[0,1]
	v_pk_mul_f32 v[58:59], v[86:87], v[58:59]
	v_mov_b32_e32 v63, v64
	v_pk_mul_f32 v[62:63], v[62:63], v[58:59]
	v_pk_mul_f32 v[58:59], v[88:89], v[58:59]
	v_mov_b32_e32 v72, v69
	v_add_f32_e32 v78, v58, v59
	v_pk_mul_f32 v[58:59], v[66:67], v[80:81] op_sel_hi:[0,1]
	v_pk_mul_f32 v[58:59], v[72:73], v[58:59]
	v_mov_b32_e32 v64, v61
	v_mov_b32_e32 v60, v65
	v_sub_f32_e32 v71, v62, v63
	v_pk_mul_f32 v[62:63], v[64:65], v[58:59]
	v_pk_mul_f32 v[58:59], v[60:61], v[58:59]
	v_sub_f32_e32 v57, v90, v91
	v_sub_f32_e32 v62, v62, v63
	v_add_f32_e32 v61, v58, v59
	v_cvt_pk_bf16_f32 v58, v57, v67
	v_cvt_pk_bf16_f32 v59, v71, v62
	v_cvt_pk_bf16_f32 v60, v68, v70
	v_cvt_pk_bf16_f32 v61, v78, v61
	global_store_dwordx2 v[50:51], v[58:59], off sc1
	global_store_dwordx2 v[50:51], v[60:61], off offset:64 sc1
	global_load_dwordx4 v[58:61], v[34:35], off offset:128
	s_nop 0
	global_load_dwordx4 v[62:65], v[34:35], off
	v_lshlrev_b32_e32 v67, 16, v76
	v_and_b32_e32 v68, 0xffff0000, v76
	v_lshlrev_b32_e32 v50, 16, v74
	v_and_b32_e32 v51, 0xffff0000, v74
	v_mul_f32_e32 v71, v67, v67
	v_mul_f32_e32 v72, v68, v68
	v_lshlrev_b32_e32 v69, 16, v77
	v_fmac_f32_e32 v71, v50, v50
	v_fmac_f32_e32 v72, v51, v51
	v_lshlrev_b32_e32 v57, 16, v75
	v_add_f32_e32 v71, v71, v72
	v_mul_f32_e32 v72, v69, v69
	v_and_b32_e32 v70, 0xffff0000, v77
	v_fmac_f32_e32 v72, v57, v57
	v_and_b32_e32 v66, 0xffff0000, v75
	v_add_f32_e32 v71, v71, v72
	v_mul_f32_e32 v72, v70, v70
	v_fmac_f32_e32 v72, v66, v66
	v_add_f32_e32 v71, v71, v72
	ds_bpermute_b32 v72, v0, v71
	s_waitcnt lgkmcnt(0)
	v_add_f32_e32 v71, v71, v72
	ds_bpermute_b32 v72, v54, v71
	s_waitcnt lgkmcnt(0)
	v_add_f32_e32 v71, v71, v72
	ds_bpermute_b32 v72, v55, v71
	s_waitcnt lgkmcnt(0)
	v_add_f32_e32 v71, v71, v72
	ds_bpermute_b32 v72, v56, v71
	s_waitcnt lgkmcnt(0)
	v_add_f32_e32 v71, v71, v72
	v_fmamk_f32 v71, v71, 0x3c000000, v215
	v_mul_f32_e32 v72, 0x4f800000, v71
	v_cmp_gt_f32_e32 vcc, s33, v71
	s_nop 1
	v_cndmask_b32_e32 v71, v71, v72, vcc
	v_sqrt_f32_e32 v72, v71
	s_nop 0
	v_add_u32_e32 v73, -1, v72
	v_fma_f32 v74, -v73, v72, v71
	v_cmp_ge_f32_e64 s[0:1], 0, v74
	v_add_u32_e32 v74, 1, v72
	s_nop 0
	v_cndmask_b32_e64 v73, v72, v73, s[0:1]
	v_fma_f32 v72, -v74, v72, v71
	v_cmp_lt_f32_e64 s[0:1], 0, v72
	s_nop 1
	v_cndmask_b32_e64 v72, v73, v74, s[0:1]
	v_mul_f32_e32 v73, 0x37800000, v72
	v_cndmask_b32_e32 v72, v72, v73, vcc
	v_cmp_class_f32_e32 vcc, v71, v216
	s_nop 1
	v_cndmask_b32_e32 v71, v72, v71, vcc
	v_div_scale_f32 v72, s[0:1], v71, v71, 1.0
	v_rcp_f32_e32 v73, v72
	s_nop 0
	v_fma_f32 v74, -v72, v73, 1.0
	v_fmac_f32_e32 v73, v74, v73
	v_div_scale_f32 v74, vcc, 1.0, v71, 1.0
	v_mul_f32_e32 v75, v74, v73
	v_fma_f32 v76, -v72, v75, v74
	v_fmac_f32_e32 v75, v76, v73
	v_fma_f32 v72, -v72, v75, v74
	v_div_fmas_f32 v72, v72, v73, v75
	v_div_fixup_f32 v71, v72, v71, 1.0
	v_mul_f32_e32 v50, v71, v50
	s_waitcnt vmcnt(0)
	v_mul_f32_e32 v50, v62, v50
	v_mul_f32_e32 v62, v71, v67
	v_mul_f32_e32 v58, v58, v62
	v_mul_f32_e32 v62, v18, v58
	v_fma_f32 v62, v22, v50, -v62
	v_mul_f32_e32 v22, v22, v58
	v_fmac_f32_e32 v22, v18, v50
	v_mul_f32_e32 v50, v71, v68
	v_mul_f32_e32 v18, v71, v51
	v_mul_f32_e32 v50, v59, v50
	v_mul_f32_e32 v18, v63, v18
	v_mul_f32_e32 v51, v19, v50
	v_fma_f32 v51, v23, v18, -v51
	v_mul_f32_e32 v23, v23, v50
	v_fmac_f32_e32 v23, v19, v18
	v_mul_f32_e32 v19, v71, v69
	v_mul_f32_e32 v18, v71, v57
	v_mul_f32_e32 v19, v60, v19
	v_mul_f32_e32 v18, v64, v18
	v_mul_f32_e32 v50, v20, v19
	v_fma_f32 v50, v24, v18, -v50
	v_mul_f32_e32 v24, v24, v19
	v_mul_f32_e32 v19, v71, v70
	v_fmac_f32_e32 v24, v20, v18
	v_mul_f32_e32 v18, v71, v66
	v_mul_f32_e32 v19, v61, v19
	v_mul_f32_e32 v18, v65, v18
	v_mul_f32_e32 v20, v21, v19
	v_fma_f32 v20, v25, v18, -v20
	v_mul_f32_e32 v25, v25, v19
	v_fmac_f32_e32 v25, v21, v18
	v_cvt_pk_bf16_f32 v18, v62, v51
	v_cvt_pk_bf16_f32 v19, v50, v20
	v_cvt_pk_bf16_f32 v20, v22, v23
	v_cvt_pk_bf16_f32 v21, v24, v25
	s_cbranch_scc1 .LBB0_132
	global_store_dwordx2 v[44:45], v[18:19], off sc1
	global_store_dwordx2 v[44:45], v[20:21], off offset:64 sc1
; __device__ __forceinline__ unsigned pk2(float lo, float hi) { unsigned r; asm("v_cvt_pk_bf16_f32 %0, %1, %2" : "=v"(r) : "v"(lo), "v"(hi)); return r; }
; __device__ __forceinline__ float bflo(unsigned w) { return __uint_as_float(w << 16); }
; __device__ __forceinline__ float bfhi(unsigned w) { return __uint_as_float(w & 0xffff0000u); }
; __global__ void __launch_bounds__(512, 2) mk_fwd(Params p) {
;     ...
;                     for (int u = 0; u < QKU; ++u) {
;                         float x1[4] = {bflo(a[u].x), bfhi(a[u].x), bflo(a[u].y), bfhi(a[u].y)}, x2[4] = {bflo(b[u].x), bfhi(b[u].x), bflo(b[u].y), bfhi(b[u].y)};
;                         float ss = 0.f;
; #pragma unroll
;                         for (int i = 0; i < 4; ++i) ss += x1[i] * x1[i] + x2[i] * x2[i];
;                         ss += __shfl_xor(ss, 1); ss += __shfl_xor(ss, 2); ss += __shfl_xor(ss, 4); ss += __shfl_xor(ss, 8);
;                         const float rstd = 1.0f / sqrtf(ss * (1.0f / HD) + EPS);
;                         const float* gn = isq[u] ? qg : kg;
;                         const float qsc = (MK_NEGM && isq[u]) ? att::SCALE * att::LOG2E : 1.0f;
;                         const f32x4 g1 = *(const f32x4*)(gn + e), g2 = *(const f32x4*)(gn + e + 32);
;                         float o1[4], o2[4];
; #pragma unroll
;                         for (int i = 0; i < 4; ++i) { const float y1 = x1[i] * rstd * g1[i], y2 = x2[i] * rstd * g2[i]; o1[i] = (y1 * cs[u][i] - y2 * sn[u][i]) * qsc; o2[i] = (y1 * sn[u][i] + y2 * cs[u][i]) * qsc; }
;                         v2u w1, w2; w1.x = pk2(o1[0], o1[1]); w1.y = pk2(o1[2], o1[3]); w2.x = pk2(o2[0], o2[1]); w2.y = pk2(o2[2], o2[3]);
;                         if (it0 + u * NGW < NQKI) { *(v2u*)pp[u] = w1; *(v2u*)(pp[u] + 32) = w2; }
;                     }
.LBB0_132:
	v_lshlrev_b32_e32 v50, 16, v49
	v_and_b32_e32 v44, 0xffff0000, v49
	v_lshlrev_b32_e32 v49, 16, v46
	v_and_b32_e32 v58, 0xffff0000, v46
	v_lshlrev_b32_e32 v51, 16, v48
	v_and_b32_e32 v57, 0xffff0000, v48
	v_mul_f32_e32 v18, v49, v49
	v_mul_f32_e32 v19, v58, v58
	v_lshlrev_b32_e32 v48, 16, v47
	v_fmac_f32_e32 v18, v51, v51
	v_fmac_f32_e32 v19, v57, v57
	v_add_f32_e32 v18, v18, v19
	v_mul_f32_e32 v19, v48, v48
	v_and_b32_e32 v45, 0xffff0000, v47
	v_fmac_f32_e32 v19, v50, v50
	v_add_f32_e32 v18, v18, v19
	v_mul_f32_e32 v19, v45, v45
	v_fmac_f32_e32 v19, v44, v44
	v_add_f32_e32 v18, v18, v19
	ds_bpermute_b32 v19, v0, v18
	s_cmpk_gt_i32 s11, 0x1fff
	s_waitcnt lgkmcnt(0)
	v_add_f32_e32 v18, v18, v19
	ds_bpermute_b32 v19, v54, v18
	s_waitcnt lgkmcnt(0)
	v_add_f32_e32 v18, v18, v19
	ds_bpermute_b32 v19, v55, v18
	s_waitcnt lgkmcnt(0)
	v_add_f32_e32 v18, v18, v19
	ds_bpermute_b32 v19, v56, v18
	s_waitcnt lgkmcnt(0)
	v_add_f32_e32 v18, v18, v19
	v_fmamk_f32 v18, v18, 0x3c000000, v215
	v_cmp_gt_f32_e32 vcc, s33, v18
	v_mul_f32_e32 v19, 0x4f800000, v18
	s_nop 0
	v_cndmask_b32_e32 v18, v18, v19, vcc
	v_sqrt_f32_e32 v19, v18
	s_nop 0
	v_add_u32_e32 v20, -1, v19
	v_fma_f32 v21, -v20, v19, v18
	v_cmp_ge_f32_e64 s[0:1], 0, v21
	v_add_u32_e32 v21, 1, v19
	s_nop 0
	v_cndmask_b32_e64 v20, v19, v20, s[0:1]
	v_fma_f32 v19, -v21, v19, v18
	v_cmp_lt_f32_e64 s[0:1], 0, v19
	s_nop 1
	v_cndmask_b32_e64 v19, v20, v21, s[0:1]
	v_mul_f32_e32 v20, 0x37800000, v19
	v_cndmask_b32_e32 v19, v19, v20, vcc
	v_cmp_class_f32_e32 vcc, v18, v216
	s_nop 1
	v_cndmask_b32_e32 v18, v19, v18, vcc
	v_div_scale_f32 v19, s[0:1], v18, v18, 1.0
	v_rcp_f32_e32 v20, v19
	s_nop 0
	v_fma_f32 v21, -v19, v20, 1.0
	v_fmac_f32_e32 v20, v21, v20
	v_div_scale_f32 v21, vcc, 1.0, v18, 1.0
	v_mul_f32_e32 v22, v21, v20
	v_fma_f32 v23, -v19, v22, v21
	v_fmac_f32_e32 v22, v23, v20
	v_fma_f32 v19, -v19, v22, v21
	v_div_fmas_f32 v19, v19, v20, v22
	v_div_fixup_f32 v46, v19, v18, 1.0
	global_load_dwordx4 v[18:21], v[34:35], off
	global_load_dwordx4 v[22:25], v[34:35], off offset:128
	v_mul_f32_e32 v49, v46, v49
	v_mul_f32_e32 v47, v46, v51
	s_waitcnt vmcnt(1)
	v_mul_f32_e32 v47, v18, v47
	s_waitcnt vmcnt(0)
	v_mul_f32_e32 v49, v22, v49
	v_mul_f32_e32 v51, v10, v49
	v_fma_f32 v51, v14, v47, -v51
	v_mul_f32_e32 v14, v14, v49
	v_fmac_f32_e32 v14, v10, v47
	v_mul_f32_e32 v47, v46, v58
	v_mul_f32_e32 v10, v46, v57
	v_mul_f32_e32 v47, v23, v47
	v_mul_f32_e32 v10, v19, v10
	v_mul_f32_e32 v49, v11, v47
	v_fma_f32 v49, v15, v10, -v49
	v_mul_f32_e32 v15, v15, v47
	v_fmac_f32_e32 v15, v11, v10
	v_mul_f32_e32 v11, v46, v48
	v_mul_f32_e32 v10, v46, v50
	v_mul_f32_e32 v11, v24, v11
	v_mul_f32_e32 v10, v20, v10
	v_mul_f32_e32 v47, v12, v11
	v_fma_f32 v47, v16, v10, -v47
	v_mul_f32_e32 v16, v16, v11
	v_mul_f32_e32 v11, v46, v45
	v_fmac_f32_e32 v16, v12, v10
	v_mul_f32_e32 v10, v46, v44
	v_mul_f32_e32 v11, v25, v11
	v_mul_f32_e32 v10, v21, v10
	v_mul_f32_e32 v12, v13, v11
	v_fma_f32 v12, v17, v10, -v12
	v_mul_f32_e32 v17, v17, v11
	v_fmac_f32_e32 v17, v13, v10
	v_cvt_pk_bf16_f32 v10, v51, v49
	v_cvt_pk_bf16_f32 v11, v47, v12
	v_cvt_pk_bf16_f32 v12, v14, v15
	v_cvt_pk_bf16_f32 v13, v16, v17
	s_cbranch_scc1 .LBB0_134
	global_store_dwordx2 v[42:43], v[10:11], off sc1
	global_store_dwordx2 v[42:43], v[12:13], off offset:64 sc1
	global_load_dwordx4 v[18:21], v[34:35], off
	global_load_dwordx4 v[22:25], v[34:35], off offset:128
.LBB0_134:
	v_lshlrev_b32_e32 v14, 16, v38
	v_and_b32_e32 v15, 0xffff0000, v38
	v_lshlrev_b32_e32 v10, 16, v40
	v_and_b32_e32 v11, 0xffff0000, v40
	v_lshlrev_b32_e32 v16, 16, v39
	v_and_b32_e32 v17, 0xffff0000, v39
	v_mul_f32_e32 v38, v14, v14
	v_mul_f32_e32 v39, v15, v15
	v_fmac_f32_e32 v38, v10, v10
	v_fmac_f32_e32 v39, v11, v11
	v_lshlrev_b32_e32 v12, 16, v41
	v_add_f32_e32 v38, v38, v39
	v_mul_f32_e32 v39, v16, v16
	v_fmac_f32_e32 v39, v12, v12
	v_and_b32_e32 v13, 0xffff0000, v41
	v_add_f32_e32 v38, v38, v39
	v_mul_f32_e32 v39, v17, v17
	v_fmac_f32_e32 v39, v13, v13
	v_add_f32_e32 v38, v38, v39
	ds_bpermute_b32 v0, v0, v38
	s_cmpk_gt_i32 s10, 0x1fff
	s_waitcnt lgkmcnt(0)
	v_add_f32_e32 v0, v38, v0
	ds_bpermute_b32 v38, v54, v0
	s_waitcnt lgkmcnt(0)
	v_add_f32_e32 v0, v0, v38
	ds_bpermute_b32 v38, v55, v0
	s_waitcnt lgkmcnt(0)
	v_add_f32_e32 v0, v0, v38
	ds_bpermute_b32 v38, v56, v0
	s_waitcnt lgkmcnt(0)
	v_add_f32_e32 v0, v0, v38
	v_fmamk_f32 v0, v0, 0x3c000000, v215
	v_mul_f32_e32 v38, 0x4f800000, v0
	v_cmp_gt_f32_e32 vcc, s33, v0
	s_nop 1
	v_cndmask_b32_e32 v0, v0, v38, vcc
	v_sqrt_f32_e32 v38, v0
	s_nop 0
	v_add_u32_e32 v39, -1, v38
	v_add_u32_e32 v40, 1, v38
	v_fma_f32 v41, -v39, v38, v0
	v_fma_f32 v42, -v40, v38, v0
	v_cmp_ge_f32_e64 s[0:1], 0, v41
	s_nop 1
	v_cndmask_b32_e64 v38, v38, v39, s[0:1]
	v_cmp_lt_f32_e64 s[0:1], 0, v42
	s_nop 1
	v_cndmask_b32_e64 v38, v38, v40, s[0:1]
	v_mul_f32_e32 v39, 0x37800000, v38
	v_cndmask_b32_e32 v38, v38, v39, vcc
	v_cmp_class_f32_e32 vcc, v0, v216
	s_nop 1
	v_cndmask_b32_e32 v0, v38, v0, vcc
	v_div_scale_f32 v38, s[0:1], v0, v0, 1.0
	v_rcp_f32_e32 v39, v38
	v_div_scale_f32 v40, vcc, 1.0, v0, 1.0
	v_fma_f32 v41, -v38, v39, 1.0
	v_fmac_f32_e32 v39, v41, v39
	v_mul_f32_e32 v41, v40, v39
	v_fma_f32 v42, -v38, v41, v40
	v_fmac_f32_e32 v41, v42, v39
	v_fma_f32 v38, -v38, v41, v40
	v_div_fmas_f32 v38, v38, v39, v41
	v_div_fixup_f32 v0, v38, v0, 1.0
	v_mul_f32_e32 v14, v0, v14
	v_mul_f32_e32 v10, v0, v10
	s_waitcnt vmcnt(0)
	v_mul_f32_e32 v14, v22, v14
	v_mul_f32_e32 v10, v18, v10
	v_mul_f32_e32 v18, v2, v14
	v_fma_f32 v18, v6, v10, -v18
	v_mul_f32_e32 v6, v6, v14
	v_fmac_f32_e32 v6, v2, v10
	v_mul_f32_e32 v10, v0, v15
	v_mul_f32_e32 v2, v0, v11
	v_mul_f32_e32 v10, v23, v10
	v_mul_f32_e32 v2, v19, v2
	v_mul_f32_e32 v11, v3, v10
	v_fma_f32 v11, v7, v2, -v11
	v_mul_f32_e32 v7, v7, v10
	v_fmac_f32_e32 v7, v3, v2
	v_mul_f32_e32 v3, v0, v16
	v_mul_f32_e32 v2, v0, v12
	v_mul_f32_e32 v3, v24, v3
	v_mul_f32_e32 v2, v20, v2
	v_mul_f32_e32 v10, v4, v3
	v_fma_f32 v10, v8, v2, -v10
	v_mul_f32_e32 v8, v8, v3
	v_fmac_f32_e32 v8, v4, v2
	v_mul_f32_e32 v2, v0, v13
	v_mul_f32_e32 v0, v0, v17
	v_mul_f32_e32 v0, v25, v0
	v_mul_f32_e32 v2, v21, v2
	v_mul_f32_e32 v3, v5, v0
	v_fma_f32 v3, v9, v2, -v3
	v_mul_f32_e32 v0, v9, v0
	v_fmac_f32_e32 v0, v5, v2
	v_cvt_pk_bf16_f32 v2, v18, v11
	v_cvt_pk_bf16_f32 v3, v10, v3
	v_cvt_pk_bf16_f32 v4, v6, v7
	v_cvt_pk_bf16_f32 v5, v8, v0
	s_cbranch_scc1 .LBB0_129
	global_store_dwordx2 v[36:37], v[2:3], off sc1
	global_store_dwordx2 v[36:37], v[4:5], off offset:64 sc1
	s_branch .LBB0_129
; __device__ __forceinline__ int crow(int r, int hi) { return (r & 3) + 8 * (r >> 2) + 4 * hi; }
;     ...
;   if (hi == 0) li_l[r32] = l_reg; asm volatile("s_waitcnt lgkmcnt(0)" ::: "memory");
;   if constexpr (DIL) { if (hi == 0) lse_o[(long)(wid * QBLK + r32) * lse_s] = m_reg + __log2f(l_reg); }
;   float rli[16];
; #pragma unroll
;   for (int r = 0; r < 16; ++r) rli[r] = __builtin_amdgcn_rcpf(li_l[crow(r, hi)]);
;   bf16* Ow = Ob + (long)(wid * QBLK) * os;
;     ...
;   { char* stg = DIL ? ((wid < 4 ? K_lds : V_lds) + 2 * SHM_K + (wid & 3) * 8192) : (K_lds + wid * 8192);
; #pragma unroll
;     for (int r = 0; r < 16; ++r) { const int orow = crow(r, hi);
; #pragma unroll
;       for (int d0 = 0; d0 < 4; ++d0) *(bf16*)(stg + orow * 256 + (d0 * 32 + r32) * 2) = __float2bfloat16(o[d0][r] * rli[r]); }
.LBB0_136:
	s_or_b64 exec, exec, s[36:37]
	s_lshl_b64 s[0:1], s[0:1], 11
	s_add_u32 s0, s4, s0
	s_addc_u32 s1, s5, s1
	s_lshl_b32 s9, s9, 8
	v_add_u32_e32 v0, s15, v130
	s_add_u32 s10, s0, s9
	ds_read_b128 v[66:69], v0
	ds_read_b128 v[70:73], v0 offset:32
	s_addc_u32 s11, s1, 0
	s_ashr_i32 s23, s22, 31
	s_and_b64 s[0:1], s[2:3], exec
	s_cselect_b32 s2, 12, 14
	s_and_b64 s[0:1], s[18:19], exec
	s_waitcnt lgkmcnt(0)
	v_rcp_f32_e32 v74, v66
	v_rcp_f32_e32 v75, v67
	v_rcp_f32_e32 v76, v68
	v_rcp_f32_e32 v77, v69
	ds_read_b128 v[66:69], v0 offset:64
	s_cselect_b32 s9, 10, s2
	s_lshl_b64 s[0:1], s[22:23], s9
	s_mov_b64 s[2:3], src_shared_base
	s_cmp_lg_u32 0, -1
	s_cselect_b32 s2, 0, 0
	s_cselect_b32 s3, s3, 0
	s_add_u32 s2, s2, 0x8000
	s_waitcnt lgkmcnt(0)
	v_rcp_f32_e32 v78, v66
	v_rcp_f32_e32 v79, v67
	v_rcp_f32_e32 v80, v68
	v_rcp_f32_e32 v81, v69
	ds_read_b128 v[66:69], v0 offset:96
	s_addc_u32 s3, s3, 0
	s_cmp_lg_u64 s[2:3], 0
	s_cselect_b32 s2, s2, -1
	s_cmp_lt_i32 s8, 4
	s_cselect_b32 s2, s2, s90
	s_lshl_b32 s3, s8, 13
	s_and_b32 s3, s3, 0x6000
	s_waitcnt lgkmcnt(0)
	v_rcp_f32_e32 v0, v66
	v_rcp_f32_e32 v66, v67
	v_rcp_f32_e32 v67, v68
	v_rcp_f32_e32 v68, v69
	s_add_i32 s2, s2, s3
	v_lshlrev_b32_e32 v69, 10, v142
	v_lshlrev_b32_e32 v82, 1, v141
	v_mul_f32_e32 v2, v2, v74
	v_add3_u32 v69, s2, v69, v82
	v_cvt_pk_bf16_f32 v2, v2, s0
	ds_write_b16 v69, v2 offset:192
	v_mul_f32_e32 v2, v51, v75
	v_cvt_pk_bf16_f32 v2, v2, s0
	ds_write_b16 v69, v2 offset:256
	v_mul_f32_e32 v2, v35, v75
	v_cvt_pk_bf16_f32 v2, v2, s0
	ds_write_b16 v69, v2 offset:320
	v_mul_f32_e32 v2, v19, v75
	v_cvt_pk_bf16_f32 v2, v2, s0
	ds_write_b16 v69, v2 offset:384
	v_mul_f32_e32 v2, v3, v75
	v_cvt_pk_bf16_f32 v2, v2, s0
	ds_write_b16 v69, v2 offset:448
	v_mul_f32_e32 v2, v52, v76
	v_cvt_pk_bf16_f32 v2, v2, s0
	ds_write_b16 v69, v2 offset:512
	v_mul_f32_e32 v2, v36, v76
	v_cvt_pk_bf16_f32 v2, v2, s0
	ds_write_b16 v69, v2 offset:576
	v_mul_f32_e32 v2, v20, v76
	v_cvt_pk_bf16_f32 v2, v2, s0
	ds_write_b16 v69, v2 offset:640
	v_mul_f32_e32 v2, v4, v76
	v_cvt_pk_bf16_f32 v2, v2, s0
	ds_write_b16 v69, v2 offset:704
	v_mul_f32_e32 v2, v53, v77
	v_cvt_pk_bf16_f32 v2, v2, s0
	ds_write_b16 v69, v2 offset:768
	v_mul_f32_e32 v2, v37, v77
	v_cvt_pk_bf16_f32 v2, v2, s0
	v_rcp_f32_e32 v70, v70
	ds_write_b16 v69, v2 offset:832
	v_mul_f32_e32 v2, v21, v77
	v_cvt_pk_bf16_f32 v2, v2, s0
	ds_write_b16 v69, v2 offset:896
	v_mul_f32_e32 v2, v5, v77
	v_cvt_pk_bf16_f32 v2, v2, s0
	ds_write_b16 v69, v2 offset:960
	v_mul_f32_e32 v2, v54, v70
	v_cvt_pk_bf16_f32 v2, v2, s0
	ds_write_b16 v69, v2 offset:2048
	v_mul_f32_e32 v2, v38, v70
	v_cvt_pk_bf16_f32 v2, v2, s0
	v_rcp_f32_e32 v71, v71
	ds_write_b16 v69, v2 offset:2112
	v_mul_f32_e32 v2, v22, v70
	v_cvt_pk_bf16_f32 v2, v2, s0
	ds_write_b16 v69, v2 offset:2176
	v_mul_f32_e32 v2, v6, v70
	v_cvt_pk_bf16_f32 v2, v2, s0
	ds_write_b16 v69, v2 offset:2240
	v_mul_f32_e32 v2, v55, v71
	v_cvt_pk_bf16_f32 v2, v2, s0
	ds_write_b16 v69, v2 offset:2304
	v_mul_f32_e32 v2, v39, v71
	v_cvt_pk_bf16_f32 v2, v2, s0
	v_rcp_f32_e32 v72, v72
	ds_write_b16 v69, v2 offset:2368
	v_mul_f32_e32 v2, v23, v71
	v_cvt_pk_bf16_f32 v2, v2, s0
	ds_write_b16 v69, v2 offset:2432
	v_mul_f32_e32 v2, v7, v71
	v_cvt_pk_bf16_f32 v2, v2, s0
	ds_write_b16 v69, v2 offset:2496
	v_mul_f32_e32 v2, v56, v72
	v_cvt_pk_bf16_f32 v2, v2, s0
	ds_write_b16 v69, v2 offset:2560
	v_mul_f32_e32 v2, v40, v72
	v_cvt_pk_bf16_f32 v2, v2, s0
	v_rcp_f32_e32 v73, v73
	ds_write_b16 v69, v2 offset:2624
	v_mul_f32_e32 v2, v24, v72
	v_cvt_pk_bf16_f32 v2, v2, s0
	ds_write_b16 v69, v2 offset:2688
	v_mul_f32_e32 v2, v8, v72
	v_cvt_pk_bf16_f32 v2, v2, s0
	ds_write_b16 v69, v2 offset:2752
	v_mul_f32_e32 v2, v57, v73
	v_cvt_pk_bf16_f32 v2, v2, s0
	ds_write_b16 v69, v2 offset:2816
	v_mul_f32_e32 v2, v41, v73
	v_cvt_pk_bf16_f32 v2, v2, s0
	ds_write_b16 v69, v2 offset:2880
	v_mul_f32_e32 v2, v25, v73
	v_cvt_pk_bf16_f32 v2, v2, s0
	ds_write_b16 v69, v2 offset:2944
	v_mul_f32_e32 v2, v9, v73
	v_cvt_pk_bf16_f32 v2, v2, s0
	ds_write_b16 v69, v2 offset:3008
	v_mul_f32_e32 v2, v58, v78
	v_cvt_pk_bf16_f32 v2, v2, s0
	ds_write_b16 v69, v2 offset:4096
	v_mul_f32_e32 v2, v42, v78
	v_cvt_pk_bf16_f32 v2, v2, s0
	ds_write_b16 v69, v2 offset:4160
	v_mul_f32_e32 v2, v26, v78
	v_cvt_pk_bf16_f32 v2, v2, s0
	ds_write_b16 v69, v2 offset:4224
	v_mul_f32_e32 v2, v10, v78
	v_cvt_pk_bf16_f32 v2, v2, s0
	ds_write_b16 v69, v2 offset:4288
	v_mul_f32_e32 v2, v59, v79
	v_cvt_pk_bf16_f32 v2, v2, s0
	ds_write_b16 v69, v2 offset:4352
	v_mul_f32_e32 v2, v43, v79
	v_cvt_pk_bf16_f32 v2, v2, s0
	ds_write_b16 v69, v2 offset:4416
	v_mul_f32_e32 v2, v27, v79
	v_cvt_pk_bf16_f32 v2, v2, s0
	ds_write_b16 v69, v2 offset:4480
	v_mul_f32_e32 v2, v11, v79
	v_cvt_pk_bf16_f32 v2, v2, s0
	ds_write_b16 v69, v2 offset:4544
; __device__ __forceinline__ int crow(int r, int hi) { return (r & 3) + 8 * (r >> 2) + 4 * hi; }
;     ...
;   { char* stg = DIL ? ((wid < 4 ? K_lds : V_lds) + 2 * SHM_K + (wid & 3) * 8192) : (K_lds + wid * 8192);
; #pragma unroll
;     for (int r = 0; r < 16; ++r) { const int orow = crow(r, hi);
; #pragma unroll
;       for (int d0 = 0; d0 < 4; ++d0) *(bf16*)(stg + orow * 256 + (d0 * 32 + r32) * 2) = __float2bfloat16(o[d0][r] * rli[r]); }
;     asm volatile("s_waitcnt lgkmcnt(0)" ::: "memory");
; #pragma unroll
;     for (int i = 0; i < 8; ++i) { const int row = i * 4 + (lane >> 4), ch = lane & 15;
;       const u32x4 v = *(const u32x4*)(stg + row * 256 + ch * 16);
;       *(u32x4*)(Ow + (long)row * os + ch * 8) = v; } }
;     ...
; #pragma unroll
;   for (int r = 0; r < 16; ++r) { const int orow = crow(r, hi);
; #pragma unroll
;     for (int d0 = 0; d0 < 4; ++d0) Ow[(long)orow * os + d0 * 32 + r32] = __float2bfloat16(o[d0][r] * rli[r]); }
;     ...
;   asm volatile("s_waitcnt lgkmcnt(0)\n\ts_barrier" ::: "memory");
	v_mul_f32_e32 v2, v60, v80
	v_cvt_pk_bf16_f32 v2, v2, s0
	ds_write_b16 v69, v2 offset:4608
	v_mul_f32_e32 v2, v44, v80
	v_cvt_pk_bf16_f32 v2, v2, s0
	ds_write_b16 v69, v2 offset:4672
	v_mul_f32_e32 v2, v28, v80
	v_cvt_pk_bf16_f32 v2, v2, s0
	ds_write_b16 v69, v2 offset:4736
	v_mul_f32_e32 v2, v12, v80
	v_cvt_pk_bf16_f32 v2, v2, s0
	ds_write_b16 v69, v2 offset:4800
	v_mul_f32_e32 v2, v61, v81
	v_cvt_pk_bf16_f32 v2, v2, s0
	ds_write_b16 v69, v2 offset:4864
	v_mul_f32_e32 v2, v45, v81
	v_cvt_pk_bf16_f32 v2, v2, s0
	ds_write_b16 v69, v2 offset:4928
	v_mul_f32_e32 v2, v29, v81
	v_cvt_pk_bf16_f32 v2, v2, s0
	ds_write_b16 v69, v2 offset:4992
	v_mul_f32_e32 v2, v13, v81
	v_cvt_pk_bf16_f32 v2, v2, s0
	ds_write_b16 v69, v2 offset:5056
	v_mul_f32_e32 v2, v62, v0
	v_cvt_pk_bf16_f32 v2, v2, s0
	ds_write_b16 v69, v2 offset:6144
	v_mul_f32_e32 v2, v46, v0
	v_cvt_pk_bf16_f32 v2, v2, s0
	ds_write_b16 v69, v2 offset:6208
	v_mul_f32_e32 v2, v30, v0
	v_mul_f32_e32 v0, v14, v0
	v_cvt_pk_bf16_f32 v0, v0, s0
	ds_write_b16 v69, v0 offset:6336
	v_mul_f32_e32 v0, v63, v66
	v_cvt_pk_bf16_f32 v0, v0, s0
	ds_write_b16 v69, v0 offset:6400
	v_mul_f32_e32 v0, v47, v66
	v_cvt_pk_bf16_f32 v0, v0, s0
	ds_write_b16 v69, v0 offset:6464
	v_mul_f32_e32 v0, v31, v66
	v_cvt_pk_bf16_f32 v0, v0, s0
	ds_write_b16 v69, v0 offset:6528
	v_mul_f32_e32 v0, v15, v66
	v_cvt_pk_bf16_f32 v0, v0, s0
	ds_write_b16 v69, v0 offset:6592
	v_mul_f32_e32 v0, v64, v67
	v_cvt_pk_bf16_f32 v0, v0, s0
	ds_write_b16 v69, v0 offset:6656
	v_mul_f32_e32 v0, v48, v67
	v_cvt_pk_bf16_f32 v0, v0, s0
	ds_write_b16 v69, v0 offset:6720
	v_mul_f32_e32 v0, v32, v67
	v_cvt_pk_bf16_f32 v0, v0, s0
	ds_write_b16 v69, v0 offset:6784
	v_mul_f32_e32 v0, v16, v67
	v_cvt_pk_bf16_f32 v0, v0, s0
	ds_write_b16 v69, v0 offset:6848
	v_mul_f32_e32 v0, v65, v68
	v_cvt_pk_bf16_f32 v0, v0, s0
	ds_write_b16 v69, v0 offset:6912
	v_mul_f32_e32 v0, v49, v68
	v_cvt_pk_bf16_f32 v0, v0, s0
	ds_write_b16 v69, v0 offset:6976
	v_mul_f32_e32 v0, v33, v68
	v_cvt_pk_bf16_f32 v0, v0, s0
	v_mul_f32_e32 v50, v50, v74
	v_mul_f32_e32 v34, v34, v74
	v_mul_f32_e32 v18, v18, v74
	ds_write_b16 v69, v0 offset:7040
	v_mul_f32_e32 v0, v17, v68
	v_cvt_pk_bf16_f32 v50, v50, s0
	v_cvt_pk_bf16_f32 v34, v34, s0
	v_cvt_pk_bf16_f32 v18, v18, s0
	v_cvt_pk_bf16_f32 v2, v2, s0
	v_cvt_pk_bf16_f32 v0, v0, s0
	s_lshl_b64 s[0:1], s[0:1], 1
	ds_write_b16 v69, v0 offset:7104
	s_add_u32 s0, s10, s0
	v_lshlrev_b32_e32 v0, 4, v140
	ds_write_b16 v69, v50
	ds_write_b16 v69, v34 offset:64
	ds_write_b16 v69, v18 offset:128
	ds_write_b16 v69, v2 offset:6272
	s_addc_u32 s1, s11, s1
	v_add_u32_e32 v10, s2, v0
	s_waitcnt lgkmcnt(0)
	v_lshl_add_u64 v[6:7], s[0:1], 0, v[0:1]
	v_lshl_add_u32 v0, v131, 8, v10
	ds_read_b128 v[2:5], v0
	v_lshlrev_b32_e32 v0, s9, v131
	v_lshlrev_b32_e32 v0, 1, v0
	v_lshl_add_u64 v[8:9], v[6:7], 0, v[0:1]
	v_or_b32_e32 v0, 4, v131
	s_waitcnt lgkmcnt(0)
	global_store_dwordx4 v[8:9], v[2:5], off sc1
	s_add_i32 s99, s99, s98
	s_nop 0
	v_lshl_add_u32 v2, v0, 8, v10
	ds_read_b128 v[2:5], v2
	v_lshlrev_b32_e32 v0, s9, v0
	v_lshlrev_b32_e32 v0, 1, v0
	v_lshl_add_u64 v[8:9], v[6:7], 0, v[0:1]
	v_or_b32_e32 v0, 8, v131
	s_waitcnt lgkmcnt(0)
	global_store_dwordx4 v[8:9], v[2:5], off sc1
	s_nop 1
	v_lshl_add_u32 v2, v0, 8, v10
	ds_read_b128 v[2:5], v2
	v_lshlrev_b32_e32 v0, s9, v0
	v_lshlrev_b32_e32 v0, 1, v0
	v_lshl_add_u64 v[8:9], v[6:7], 0, v[0:1]
	v_or_b32_e32 v0, 12, v131
	s_waitcnt lgkmcnt(0)
	global_store_dwordx4 v[8:9], v[2:5], off sc1
	s_nop 1
	v_lshl_add_u32 v2, v0, 8, v10
	ds_read_b128 v[2:5], v2
	v_lshlrev_b32_e32 v0, s9, v0
	v_lshlrev_b32_e32 v0, 1, v0
	v_lshl_add_u64 v[8:9], v[6:7], 0, v[0:1]
	v_or_b32_e32 v0, 16, v131
	s_waitcnt lgkmcnt(0)
	global_store_dwordx4 v[8:9], v[2:5], off sc1
	s_nop 1
	v_lshl_add_u32 v2, v0, 8, v10
	ds_read_b128 v[2:5], v2
	v_lshlrev_b32_e32 v0, s9, v0
	v_lshlrev_b32_e32 v0, 1, v0
	v_lshl_add_u64 v[8:9], v[6:7], 0, v[0:1]
	v_or_b32_e32 v0, 20, v131
	s_waitcnt lgkmcnt(0)
	global_store_dwordx4 v[8:9], v[2:5], off sc1
	s_nop 1
	v_lshl_add_u32 v2, v0, 8, v10
	ds_read_b128 v[2:5], v2
	v_lshlrev_b32_e32 v0, s9, v0
	v_lshlrev_b32_e32 v0, 1, v0
	v_lshl_add_u64 v[8:9], v[6:7], 0, v[0:1]
	v_or_b32_e32 v0, 24, v131
	s_waitcnt lgkmcnt(0)
	global_store_dwordx4 v[8:9], v[2:5], off sc1
	s_nop 1
	v_lshl_add_u32 v2, v0, 8, v10
	ds_read_b128 v[2:5], v2
	v_lshlrev_b32_e32 v0, s9, v0
	v_lshlrev_b32_e32 v0, 1, v0
	v_lshl_add_u64 v[8:9], v[6:7], 0, v[0:1]
	v_or_b32_e32 v0, 28, v131
	s_waitcnt lgkmcnt(0)
	global_store_dwordx4 v[8:9], v[2:5], off sc1
	s_nop 1
	v_lshl_add_u32 v2, v0, 8, v10
	ds_read_b128 v[2:5], v2
	v_lshlrev_b32_e32 v0, s9, v0
	v_lshlrev_b32_e32 v0, 1, v0
	v_lshl_add_u64 v[6:7], v[6:7], 0, v[0:1]
	s_waitcnt lgkmcnt(0)
	global_store_dwordx4 v[6:7], v[2:5], off sc1
	s_waitcnt lgkmcnt(0)
	s_barrier

;     ...
;   if (hi == 0) li_l[r32] = l_reg; asm volatile("s_waitcnt lgkmcnt(0)" ::: "memory");
;   if constexpr (DIL) { if (hi == 0) lse_o[(long)(wid * QBLK + r32) * lse_s] = m_reg + __log2f(l_reg); }
.LBB0_153:
	s_and_saveexec_b64 s[0:1], s[38:39]
	ds_write_b32 v147, v153
	s_or_b64 exec, exec, s[0:1]
	s_ashr_i32 s37, s36, 31
	s_lshl_b64 s[0:1], s[36:37], 14
	s_or_b64 s[0:1], s[0:1], s[52:53]
	s_and_b64 s[10:11], s[2:3], exec
	s_cselect_b32 s12, 2, 4
	s_and_b64 s[10:11], s[18:19], exec
	s_cselect_b32 s10, 0, s12
	s_lshl_b64 s[10:11], s[40:41], s10
	s_waitcnt lgkmcnt(0)
	s_add_u32 s0, s0, s10
	s_addc_u32 s1, s1, s11
	s_and_saveexec_b64 s[36:37], s[38:39]
	s_cbranch_execz .LBB0_136
	s_lshl_b64 s[10:11], s[0:1], 5
	s_add_u32 s10, s6, s10
	s_addc_u32 s11, s7, s11
	s_lshl_b32 s12, s9, 2
	s_add_u32 s10, s10, s12
	s_addc_u32 s11, s11, 0
	v_log_f32_e32 v0, v153
	s_and_b64 s[12:13], s[2:3], exec
	s_cselect_b32 s14, 5, 7
	s_and_b64 s[12:13], s[18:19], exec
	s_cselect_b32 s12, 3, s14
	v_lshlrev_b64 v[66:67], s12, v[132:133]
	v_add_f32_e32 v0, v144, v0
	v_lshl_add_u64 v[66:67], v[66:67], 2, s[10:11]
	global_store_dword v[66:67], v0, off sc1
	s_branch .LBB0_136

; __device__ __forceinline__ unsigned cvt_pk_bf16(float lo, float hi) { unsigned r; asm volatile("v_cvt_pk_bf16_f32 %0, %1, %2" : "=v"(r) : "v"(lo), "v"(hi)); return r; }
;     __device__ __forceinline__ void operator()(const f32x4 (&acc)[2][2][4][2], const Unit& u, int wr, int wc, int fr, int fq) const {
;     ...
;             u32x4 pre[4][2];
; #pragma unroll
;             for (int m = 0; m < 4; ++m) { const size_t off = (size_t)(u.pm * BM + ai * HALF + wr * 64 + m * 16 + fr) * ldc + col0;
; #pragma unroll
;                 for (int bj = 0; bj < 2; ++bj) pre[m][bj] = *(const u32x4*)(xb + off + bj * HALF); }
;             asm volatile("" ::: "memory");
; #pragma unroll
;             for (int m = 0; m < 4; ++m) { const int row = u.pm * BM + ai * HALF + wr * 64 + m * 16 + fr; const size_t off = (size_t)row * ldc + col0; float ss = 0.f;
; #pragma unroll
;                 for (int bj = 0; bj < 2; ++bj) { const u32x4 pb = pre[m][bj]; const f32x4 a0 = acc[ai][bj][m][0], a1 = acc[ai][bj][m][1];
;                     u32x4 w; w.x = cvt_pk_bf16(__uint_as_float(pb.x << 16) + a0[0], __uint_as_float(pb.x & 0xffff0000u) + a0[1]); w.y = cvt_pk_bf16(__uint_as_float(pb.y << 16) + a0[2], __uint_as_float(pb.y & 0xffff0000u) + a0[3]);
;                     w.z = cvt_pk_bf16(__uint_as_float(pb.z << 16) + a1[0], __uint_as_float(pb.z & 0xffff0000u) + a1[1]); w.w = cvt_pk_bf16(__uint_as_float(pb.w << 16) + a1[2], __uint_as_float(pb.w & 0xffff0000u) + a1[3]);
; #pragma unroll
;                     for (int q = 0; q < 4; ++q) { const float r0 = __uint_as_float(w[q] << 16), r1 = __uint_as_float(w[q] & 0xffff0000u); ss += r0 * r0 + r1 * r1; }
;                     *(u32x4*)(xb + off + bj * HALF) = w; }
;                 ss += __shfl_xor(ss, 16); ss += __shfl_xor(ss, 32);
;                 if (fq == 0) rowsq[(size_t)row * 32 + u.pn * 4 + wc] = ss; }
.LBB0_183:
	v_lshl_or_b32 v164, s46, 8, v178
	v_lshl_add_u32 v168, s50, 8, v176
	v_ashrrev_i32_e32 v165, 31, v164
	v_lshlrev_b64 v[130:131], 1, v[164:165]
	v_ashrrev_i32_e32 v169, 31, v168
	v_lshl_add_u64 v[166:167], s[30:31], 0, v[130:131]
	v_lshlrev_b64 v[132:133], 12, v[168:169]
	v_lshl_add_u64 v[134:135], v[166:167], 0, v[132:133]
	global_load_dwordx4 v[180:183], v[134:135], off
	global_load_dwordx4 v[184:187], v[134:135], off offset:256
	v_or_b32_e32 v174, 16, v168
	v_or_b32_e32 v172, 32, v168
	v_or_b32_e32 v170, 48, v168
	v_ashrrev_i32_e32 v175, 31, v174
	v_ashrrev_i32_e32 v173, 31, v172
	v_ashrrev_i32_e32 v171, 31, v170
	v_lshlrev_b64 v[134:135], 12, v[174:175]
	v_lshlrev_b64 v[136:137], 12, v[172:173]
	v_lshlrev_b64 v[138:139], 12, v[170:171]
	v_lshl_add_u64 v[132:133], s[30:31], 0, v[132:133]
	v_lshl_add_u64 v[134:135], v[166:167], 0, v[134:135]
	v_lshl_add_u64 v[136:137], v[166:167], 0, v[136:137]
	v_lshl_add_u64 v[188:189], v[166:167], 0, v[138:139]
	v_lshl_add_u64 v[190:191], v[132:133], 0, v[130:131]
	global_load_dwordx4 v[150:153], v[134:135], off
	global_load_dwordx4 v[146:149], v[134:135], off offset:256
	global_load_dwordx4 v[142:145], v[136:137], off
	global_load_dwordx4 v[138:141], v[136:137], off offset:256
	s_nop 0
	global_load_dwordx4 v[134:137], v[188:189], off
	global_load_dwordx4 v[130:133], v[188:189], off offset:256
	v_cmp_lt_i32_e32 vcc, v224, v219
	s_lshl_b32 s46, s46, 2
	s_ashr_i32 s47, s46, 31
	s_waitcnt vmcnt(0)
	v_lshlrev_b32_e32 v192, 16, v182
	v_and_b32_e32 v182, 0xffff0000, v182
	v_lshlrev_b32_e32 v193, 16, v183
	v_and_b32_e32 v183, 0xffff0000, v183
	v_lshlrev_b32_e32 v188, 16, v180
	v_and_b32_e32 v180, 0xffff0000, v180
	v_lshlrev_b32_e32 v189, 16, v181
	v_and_b32_e32 v181, 0xffff0000, v181
	v_lshlrev_b32_e32 v196, 16, v186
	v_and_b32_e32 v186, 0xffff0000, v186
	v_lshlrev_b32_e32 v197, 16, v187
	v_and_b32_e32 v187, 0xffff0000, v187
	v_add_f32_e32 v123, v123, v182
	v_add_f32_e32 v125, v125, v183
	v_add_f32_e32 v126, v126, v188
	v_add_f32_e32 v127, v127, v180
	v_add_f32_e32 v128, v128, v189
	v_add_f32_e32 v129, v129, v181
	v_add_f32_e32 v122, v122, v192
	v_add_f32_e32 v124, v124, v193
	v_add_f32_e32 v180, v114, v196
	v_add_f32_e32 v181, v115, v186
	v_add_f32_e32 v182, v116, v197
	v_add_f32_e32 v183, v117, v187
	v_cvt_pk_bf16_f32 v114, v126, v127
	v_cvt_pk_bf16_f32 v115, v128, v129
	v_cvt_pk_bf16_f32 v116, v122, v123
	v_cvt_pk_bf16_f32 v117, v124, v125
	v_lshlrev_b32_e32 v194, 16, v184
	v_and_b32_e32 v123, 0xffff0000, v114
	v_and_b32_e32 v125, 0xffff0000, v115
	v_lshlrev_b32_e32 v122, 16, v114
	v_lshlrev_b32_e32 v124, 16, v115
	v_and_b32_e32 v127, 0xffff0000, v116
	global_store_dwordx4 v[190:191], v[114:117], off sc1
	v_and_b32_e32 v184, 0xffff0000, v184
	v_add_f32_e32 v118, v118, v194
	v_mul_f32_e32 v114, v123, v123
	v_mul_f32_e32 v115, v125, v125
	v_lshlrev_b32_e32 v126, 16, v116
	v_and_b32_e32 v129, 0xffff0000, v117
	v_mul_f32_e32 v116, v127, v127
	v_fmac_f32_e32 v114, v122, v122
	v_fmac_f32_e32 v115, v124, v124
	v_lshlrev_b32_e32 v195, 16, v185
	v_and_b32_e32 v185, 0xffff0000, v185
	v_add_f32_e32 v119, v119, v184
	v_lshlrev_b32_e32 v128, 16, v117
	v_cvt_pk_bf16_f32 v118, v118, v119
	v_mul_f32_e32 v117, v129, v129
	v_and_b32_e32 v125, 0xffff0000, v118
	v_fmac_f32_e32 v116, v126, v126
	v_add_f32_e32 v114, v114, v115
	v_add_f32_e32 v120, v120, v195
	v_add_f32_e32 v121, v121, v185
	v_cvt_pk_bf16_f32 v119, v120, v121
	v_lshlrev_b32_e32 v123, 16, v118
	v_fmac_f32_e32 v117, v128, v128
	v_mul_f32_e32 v122, v125, v125
	v_add_f32_e32 v114, v114, v116
	v_and_b32_e32 v116, 0xffff0000, v119
	v_add_f32_e32 v114, v114, v117
	v_fmac_f32_e32 v122, v123, v123
	v_lshlrev_b32_e32 v115, 16, v119
	v_mul_f32_e32 v116, v116, v116
	v_add_f32_e32 v114, v114, v122
	v_fmac_f32_e32 v116, v115, v115
	v_cvt_pk_bf16_f32 v120, v180, v181
	v_add_f32_e32 v114, v114, v116
	v_and_b32_e32 v116, 0xffff0000, v120
	v_lshlrev_b32_e32 v115, 16, v120
	v_mul_f32_e32 v116, v116, v116
	v_fmac_f32_e32 v116, v115, v115
	v_cvt_pk_bf16_f32 v121, v182, v183
	v_add_f32_e32 v114, v114, v116
	v_and_b32_e32 v116, 0xffff0000, v121
	v_lshlrev_b32_e32 v115, 16, v121
	v_mul_f32_e32 v116, v116, v116
	v_fmac_f32_e32 v116, v115, v115
	v_add_f32_e32 v115, v114, v116
	v_cndmask_b32_e32 v114, v218, v224, vcc
	v_lshlrev_b32_e32 v114, 2, v114
	ds_bpermute_b32 v116, v114, v115
	v_cmp_lt_i32_e32 vcc, v225, v219
	global_store_dwordx4 v[190:191], v[118:121], off offset:256 sc1
	s_waitcnt lgkmcnt(0)
	v_add_f32_e32 v116, v115, v116
	v_cndmask_b32_e32 v115, v218, v225, vcc
	v_lshlrev_b32_e32 v115, 2, v115
	ds_bpermute_b32 v117, v115, v116
	s_and_saveexec_b64 s[50:51], s[38:39]
	s_cbranch_execz .LBB0_185
	v_lshlrev_b64 v[118:119], 7, v[168:169]
	v_lshl_add_u64 v[118:119], s[2:3], 0, v[118:119]
	v_lshl_add_u64 v[118:119], s[46:47], 2, v[118:119]
	s_lshl_b32 s52, s11, 2
	v_lshl_add_u64 v[118:119], v[118:119], 0, s[52:53]
	s_waitcnt lgkmcnt(0)
	v_add_f32_e32 v116, v116, v117
	global_store_dword v[118:119], v116, off sc1
; __device__ __forceinline__ unsigned cvt_pk_bf16(float lo, float hi) { unsigned r; asm volatile("v_cvt_pk_bf16_f32 %0, %1, %2" : "=v"(r) : "v"(lo), "v"(hi)); return r; }
;     __device__ __forceinline__ void operator()(const f32x4 (&acc)[2][2][4][2], const Unit& u, int wr, int wc, int fr, int fq) const {
;     ...
;             for (int m = 0; m < 4; ++m) { const int row = u.pm * BM + ai * HALF + wr * 64 + m * 16 + fr; const size_t off = (size_t)row * ldc + col0; float ss = 0.f;
; #pragma unroll
;                 for (int bj = 0; bj < 2; ++bj) { const u32x4 pb = pre[m][bj]; const f32x4 a0 = acc[ai][bj][m][0], a1 = acc[ai][bj][m][1];
;                     u32x4 w; w.x = cvt_pk_bf16(__uint_as_float(pb.x << 16) + a0[0], __uint_as_float(pb.x & 0xffff0000u) + a0[1]); w.y = cvt_pk_bf16(__uint_as_float(pb.y << 16) + a0[2], __uint_as_float(pb.y & 0xffff0000u) + a0[3]);
;                     w.z = cvt_pk_bf16(__uint_as_float(pb.z << 16) + a1[0], __uint_as_float(pb.z & 0xffff0000u) + a1[1]); w.w = cvt_pk_bf16(__uint_as_float(pb.w << 16) + a1[2], __uint_as_float(pb.w & 0xffff0000u) + a1[3]);
; #pragma unroll
;                     for (int q = 0; q < 4; ++q) { const float r0 = __uint_as_float(w[q] << 16), r1 = __uint_as_float(w[q] & 0xffff0000u); ss += r0 * r0 + r1 * r1; }
;                     *(u32x4*)(xb + off + bj * HALF) = w; }
;                 ss += __shfl_xor(ss, 16); ss += __shfl_xor(ss, 32);
;                 if (fq == 0) rowsq[(size_t)row * 32 + u.pn * 4 + wc] = ss; }
.LBB0_185:
	s_or_b64 exec, exec, s[50:51]
	v_lshlrev_b32_e32 v118, 16, v150
	v_add_f32_e32 v110, v110, v118
	v_and_b32_e32 v118, 0xffff0000, v150
	v_add_f32_e32 v111, v111, v118
	v_cvt_pk_bf16_f32 v110, v110, v111
	v_lshlrev_b32_e32 v111, 16, v151
	v_add_f32_e32 v111, v112, v111
	v_and_b32_e32 v112, 0xffff0000, v151
	v_add_f32_e32 v112, v113, v112
	v_cvt_pk_bf16_f32 v111, v111, v112
	v_lshlrev_b32_e32 v112, 16, v152
	v_add_f32_e32 v106, v106, v112
	v_and_b32_e32 v112, 0xffff0000, v152
	v_add_f32_e32 v107, v107, v112
	v_cvt_pk_bf16_f32 v112, v106, v107
	v_and_b32_e32 v107, 0xffff0000, v153
	v_lshlrev_b32_e32 v106, 16, v153
	v_add_f32_e32 v107, v109, v107
	v_add_f32_e32 v106, v108, v106
	v_cvt_pk_bf16_f32 v113, v106, v107
	v_and_b32_e32 v107, 0xffff0000, v110
	v_lshlrev_b32_e32 v106, 16, v110
	v_mul_f32_e32 v107, v107, v107
	v_and_b32_e32 v108, 0xffff0000, v111
	v_fmac_f32_e32 v107, v106, v106
	v_lshlrev_b32_e32 v106, 16, v111
	v_mul_f32_e32 v108, v108, v108
	v_fmac_f32_e32 v108, v106, v106
	v_add_f32_e32 v106, v107, v108
	v_and_b32_e32 v108, 0xffff0000, v112
	v_lshlrev_b32_e32 v107, 16, v112
	v_mul_f32_e32 v108, v108, v108
	v_fmac_f32_e32 v108, v107, v107
	v_add_f32_e32 v106, v106, v108
	v_and_b32_e32 v108, 0xffff0000, v113
	v_lshlrev_b32_e32 v107, 16, v113
	v_mul_f32_e32 v108, v108, v108
	s_waitcnt lgkmcnt(0)
	v_lshlrev_b64 v[116:117], 11, v[174:175]
	v_fmac_f32_e32 v108, v107, v107
	v_lshlrev_b32_e32 v109, 16, v146
	v_add_f32_e32 v108, v106, v108
	v_lshl_add_u64 v[106:107], v[116:117], 1, s[30:31]
	v_add_f32_e32 v102, v102, v109
	v_and_b32_e32 v109, 0xffff0000, v146
	v_lshl_add_u64 v[106:107], v[164:165], 1, v[106:107]
	v_add_f32_e32 v103, v103, v109
	global_store_dwordx4 v[106:107], v[110:113], off sc1
	v_cvt_pk_bf16_f32 v102, v102, v103
	v_lshlrev_b32_e32 v103, 16, v147
	v_add_f32_e32 v103, v104, v103
	v_and_b32_e32 v104, 0xffff0000, v147
	v_add_f32_e32 v104, v105, v104
	v_cvt_pk_bf16_f32 v103, v103, v104
	v_lshlrev_b32_e32 v104, 16, v148
	v_add_f32_e32 v98, v98, v104
	v_and_b32_e32 v104, 0xffff0000, v148
	v_add_f32_e32 v99, v99, v104
	v_cvt_pk_bf16_f32 v104, v98, v99
	v_and_b32_e32 v99, 0xffff0000, v149
	v_lshlrev_b32_e32 v98, 16, v149
	v_add_f32_e32 v99, v101, v99
	v_add_f32_e32 v98, v100, v98
	v_cvt_pk_bf16_f32 v105, v98, v99
	v_and_b32_e32 v99, 0xffff0000, v102
	v_lshlrev_b32_e32 v98, 16, v102
	v_mul_f32_e32 v99, v99, v99
	v_fmac_f32_e32 v99, v98, v98
	v_and_b32_e32 v100, 0xffff0000, v103
	v_add_f32_e32 v98, v108, v99
	v_lshlrev_b32_e32 v99, 16, v103
	v_mul_f32_e32 v100, v100, v100
	v_fmac_f32_e32 v100, v99, v99
	v_add_f32_e32 v98, v98, v100
	v_and_b32_e32 v100, 0xffff0000, v104
	v_lshlrev_b32_e32 v99, 16, v104
	v_mul_f32_e32 v100, v100, v100
	v_fmac_f32_e32 v100, v99, v99
	v_add_f32_e32 v98, v98, v100
	v_and_b32_e32 v100, 0xffff0000, v105
	v_lshlrev_b32_e32 v99, 16, v105
	v_mul_f32_e32 v100, v100, v100
	v_fmac_f32_e32 v100, v99, v99
	v_add_f32_e32 v98, v98, v100
	ds_bpermute_b32 v99, v114, v98
	global_store_dwordx4 v[106:107], v[102:105], off offset:256 sc1
	s_waitcnt lgkmcnt(0)
	v_add_f32_e32 v98, v98, v99
	ds_bpermute_b32 v99, v115, v98
	s_and_saveexec_b64 s[50:51], s[38:39]
	s_cbranch_execz .LBB0_187
	v_lshlrev_b64 v[100:101], 7, v[174:175]
	v_lshl_add_u64 v[100:101], s[2:3], 0, v[100:101]
	v_lshl_add_u64 v[100:101], s[46:47], 2, v[100:101]
	s_lshl_b32 s52, s11, 2
	v_lshl_add_u64 v[100:101], v[100:101], 0, s[52:53]
	s_waitcnt lgkmcnt(0)
	v_add_f32_e32 v98, v98, v99
	global_store_dword v[100:101], v98, off sc1
.LBB0_187:
	s_or_b64 exec, exec, s[50:51]
	v_lshlrev_b32_e32 v100, 16, v142
	v_add_f32_e32 v94, v94, v100
	v_and_b32_e32 v100, 0xffff0000, v142
	v_add_f32_e32 v95, v95, v100
	v_cvt_pk_bf16_f32 v94, v94, v95
	v_lshlrev_b32_e32 v95, 16, v143
	v_add_f32_e32 v95, v96, v95
	v_and_b32_e32 v96, 0xffff0000, v143
	v_add_f32_e32 v96, v97, v96
	v_cvt_pk_bf16_f32 v95, v95, v96
	v_lshlrev_b32_e32 v96, 16, v144
	v_add_f32_e32 v90, v90, v96
	v_and_b32_e32 v96, 0xffff0000, v144
	v_add_f32_e32 v91, v91, v96
	v_cvt_pk_bf16_f32 v96, v90, v91
	v_and_b32_e32 v91, 0xffff0000, v145
	v_lshlrev_b32_e32 v90, 16, v145
	v_add_f32_e32 v91, v93, v91
	v_add_f32_e32 v90, v92, v90
	v_cvt_pk_bf16_f32 v97, v90, v91
	v_and_b32_e32 v91, 0xffff0000, v94
	v_lshlrev_b32_e32 v90, 16, v94
	v_mul_f32_e32 v91, v91, v91
	v_and_b32_e32 v92, 0xffff0000, v95
	v_fmac_f32_e32 v91, v90, v90
	v_lshlrev_b32_e32 v90, 16, v95
	v_mul_f32_e32 v92, v92, v92
	v_fmac_f32_e32 v92, v90, v90
	v_add_f32_e32 v90, v91, v92
	v_and_b32_e32 v92, 0xffff0000, v96
	v_lshlrev_b32_e32 v91, 16, v96
	v_mul_f32_e32 v92, v92, v92
	v_fmac_f32_e32 v92, v91, v91
	v_add_f32_e32 v90, v90, v92
	v_and_b32_e32 v92, 0xffff0000, v97
	v_lshlrev_b32_e32 v91, 16, v97
	v_mul_f32_e32 v92, v92, v92
	s_waitcnt lgkmcnt(0)
	v_lshlrev_b64 v[98:99], 11, v[172:173]
	v_fmac_f32_e32 v92, v91, v91
	v_lshlrev_b32_e32 v93, 16, v138
	v_add_f32_e32 v92, v90, v92
	v_lshl_add_u64 v[90:91], v[98:99], 1, s[30:31]
	v_add_f32_e32 v86, v86, v93
	v_and_b32_e32 v93, 0xffff0000, v138
	v_lshl_add_u64 v[90:91], v[164:165], 1, v[90:91]
	v_add_f32_e32 v87, v87, v93
	global_store_dwordx4 v[90:91], v[94:97], off sc1
	v_cvt_pk_bf16_f32 v86, v86, v87
	v_lshlrev_b32_e32 v87, 16, v139
	v_add_f32_e32 v87, v88, v87
	v_and_b32_e32 v88, 0xffff0000, v139
	v_add_f32_e32 v88, v89, v88
	v_cvt_pk_bf16_f32 v87, v87, v88
	v_lshlrev_b32_e32 v88, 16, v140
	v_add_f32_e32 v82, v82, v88
	v_and_b32_e32 v88, 0xffff0000, v140
	v_add_f32_e32 v83, v83, v88
	v_cvt_pk_bf16_f32 v88, v82, v83
	v_and_b32_e32 v83, 0xffff0000, v141
	v_lshlrev_b32_e32 v82, 16, v141
	v_add_f32_e32 v83, v85, v83
	v_add_f32_e32 v82, v84, v82
	v_cvt_pk_bf16_f32 v89, v82, v83
	v_and_b32_e32 v83, 0xffff0000, v86
	v_lshlrev_b32_e32 v82, 16, v86
	v_mul_f32_e32 v83, v83, v83
	v_fmac_f32_e32 v83, v82, v82
	v_and_b32_e32 v84, 0xffff0000, v87
	v_add_f32_e32 v82, v92, v83
	v_lshlrev_b32_e32 v83, 16, v87
	v_mul_f32_e32 v84, v84, v84
	v_fmac_f32_e32 v84, v83, v83
	v_add_f32_e32 v82, v82, v84
	v_and_b32_e32 v84, 0xffff0000, v88
	v_lshlrev_b32_e32 v83, 16, v88
	v_mul_f32_e32 v84, v84, v84
	v_fmac_f32_e32 v84, v83, v83
	v_add_f32_e32 v82, v82, v84
	v_and_b32_e32 v84, 0xffff0000, v89
	v_lshlrev_b32_e32 v83, 16, v89
	v_mul_f32_e32 v84, v84, v84
	v_fmac_f32_e32 v84, v83, v83
	v_add_f32_e32 v82, v82, v84
	ds_bpermute_b32 v83, v114, v82
	global_store_dwordx4 v[90:91], v[86:89], off offset:256 sc1
	s_waitcnt lgkmcnt(0)
	v_add_f32_e32 v82, v82, v83
	ds_bpermute_b32 v83, v115, v82
	s_and_saveexec_b64 s[50:51], s[38:39]
	s_cbranch_execz .LBB0_189
	v_lshlrev_b64 v[84:85], 7, v[172:173]
	v_lshl_add_u64 v[84:85], s[2:3], 0, v[84:85]
	v_lshl_add_u64 v[84:85], s[46:47], 2, v[84:85]
	s_lshl_b32 s52, s11, 2
	v_lshl_add_u64 v[84:85], v[84:85], 0, s[52:53]
	s_waitcnt lgkmcnt(0)
	v_add_f32_e32 v82, v82, v83
	global_store_dword v[84:85], v82, off sc1
; __device__ __forceinline__ unsigned cvt_pk_bf16(float lo, float hi) { unsigned r; asm volatile("v_cvt_pk_bf16_f32 %0, %1, %2" : "=v"(r) : "v"(lo), "v"(hi)); return r; }
;     __device__ __forceinline__ void operator()(const f32x4 (&acc)[2][2][4][2], const Unit& u, int wr, int wc, int fr, int fq) const {
;     ...
;             u32x4 pre[4][2];
; #pragma unroll
;             for (int m = 0; m < 4; ++m) { const size_t off = (size_t)(u.pm * BM + ai * HALF + wr * 64 + m * 16 + fr) * ldc + col0;
; #pragma unroll
;                 for (int bj = 0; bj < 2; ++bj) pre[m][bj] = *(const u32x4*)(xb + off + bj * HALF); }
;             asm volatile("" ::: "memory");
; #pragma unroll
;             for (int m = 0; m < 4; ++m) { const int row = u.pm * BM + ai * HALF + wr * 64 + m * 16 + fr; const size_t off = (size_t)row * ldc + col0; float ss = 0.f;
; #pragma unroll
;                 for (int bj = 0; bj < 2; ++bj) { const u32x4 pb = pre[m][bj]; const f32x4 a0 = acc[ai][bj][m][0], a1 = acc[ai][bj][m][1];
;                     u32x4 w; w.x = cvt_pk_bf16(__uint_as_float(pb.x << 16) + a0[0], __uint_as_float(pb.x & 0xffff0000u) + a0[1]); w.y = cvt_pk_bf16(__uint_as_float(pb.y << 16) + a0[2], __uint_as_float(pb.y & 0xffff0000u) + a0[3]);
;                     w.z = cvt_pk_bf16(__uint_as_float(pb.z << 16) + a1[0], __uint_as_float(pb.z & 0xffff0000u) + a1[1]); w.w = cvt_pk_bf16(__uint_as_float(pb.w << 16) + a1[2], __uint_as_float(pb.w & 0xffff0000u) + a1[3]);
; #pragma unroll
;                     for (int q = 0; q < 4; ++q) { const float r0 = __uint_as_float(w[q] << 16), r1 = __uint_as_float(w[q] & 0xffff0000u); ss += r0 * r0 + r1 * r1; }
;                     *(u32x4*)(xb + off + bj * HALF) = w; }
;                 ss += __shfl_xor(ss, 16); ss += __shfl_xor(ss, 32);
;                 if (fq == 0) rowsq[(size_t)row * 32 + u.pn * 4 + wc] = ss; }
.LBB0_189:
	s_or_b64 exec, exec, s[50:51]
	v_lshlrev_b32_e32 v84, 16, v134
	v_add_f32_e32 v78, v78, v84
	v_and_b32_e32 v84, 0xffff0000, v134
	v_add_f32_e32 v79, v79, v84
	v_cvt_pk_bf16_f32 v78, v78, v79
	v_lshlrev_b32_e32 v79, 16, v135
	v_add_f32_e32 v79, v80, v79
	v_and_b32_e32 v80, 0xffff0000, v135
	v_add_f32_e32 v80, v81, v80
	v_cvt_pk_bf16_f32 v79, v79, v80
	v_lshlrev_b32_e32 v80, 16, v136
	v_add_f32_e32 v74, v74, v80
	v_and_b32_e32 v80, 0xffff0000, v136
	v_add_f32_e32 v75, v75, v80
	v_cvt_pk_bf16_f32 v80, v74, v75
	v_and_b32_e32 v75, 0xffff0000, v137
	v_lshlrev_b32_e32 v74, 16, v137
	v_add_f32_e32 v75, v77, v75
	v_add_f32_e32 v74, v76, v74
	v_cvt_pk_bf16_f32 v81, v74, v75
	v_and_b32_e32 v75, 0xffff0000, v78
	v_lshlrev_b32_e32 v74, 16, v78
	v_mul_f32_e32 v75, v75, v75
	v_and_b32_e32 v76, 0xffff0000, v79
	v_fmac_f32_e32 v75, v74, v74
	v_lshlrev_b32_e32 v74, 16, v79
	v_mul_f32_e32 v76, v76, v76
	v_fmac_f32_e32 v76, v74, v74
	v_add_f32_e32 v74, v75, v76
	v_and_b32_e32 v76, 0xffff0000, v80
	v_lshlrev_b32_e32 v75, 16, v80
	v_mul_f32_e32 v76, v76, v76
	v_fmac_f32_e32 v76, v75, v75
	v_add_f32_e32 v74, v74, v76
	v_and_b32_e32 v76, 0xffff0000, v81
	v_lshlrev_b32_e32 v75, 16, v81
	v_mul_f32_e32 v76, v76, v76
	s_waitcnt lgkmcnt(0)
	v_lshlrev_b64 v[82:83], 11, v[170:171]
	v_fmac_f32_e32 v76, v75, v75
	v_lshlrev_b32_e32 v77, 16, v130
	v_add_f32_e32 v76, v74, v76
	v_lshl_add_u64 v[74:75], v[82:83], 1, s[30:31]
	v_add_f32_e32 v70, v70, v77
	v_and_b32_e32 v77, 0xffff0000, v130
	v_lshl_add_u64 v[74:75], v[164:165], 1, v[74:75]
	v_add_f32_e32 v71, v71, v77
	global_store_dwordx4 v[74:75], v[78:81], off sc1
	v_cvt_pk_bf16_f32 v70, v70, v71
	v_lshlrev_b32_e32 v71, 16, v131
	v_add_f32_e32 v71, v72, v71
	v_and_b32_e32 v72, 0xffff0000, v131
	v_add_f32_e32 v72, v73, v72
	v_cvt_pk_bf16_f32 v71, v71, v72
	v_lshlrev_b32_e32 v72, 16, v132
	v_add_f32_e32 v66, v66, v72
	v_and_b32_e32 v72, 0xffff0000, v132
	v_add_f32_e32 v67, v67, v72
	v_cvt_pk_bf16_f32 v72, v66, v67
	v_and_b32_e32 v67, 0xffff0000, v133
	v_lshlrev_b32_e32 v66, 16, v133
	v_add_f32_e32 v67, v69, v67
	v_add_f32_e32 v66, v68, v66
	v_cvt_pk_bf16_f32 v73, v66, v67
	v_and_b32_e32 v67, 0xffff0000, v70
	v_lshlrev_b32_e32 v66, 16, v70
	v_mul_f32_e32 v67, v67, v67
	v_fmac_f32_e32 v67, v66, v66
	v_and_b32_e32 v68, 0xffff0000, v71
	v_add_f32_e32 v66, v76, v67
	v_lshlrev_b32_e32 v67, 16, v71
	v_mul_f32_e32 v68, v68, v68
	v_fmac_f32_e32 v68, v67, v67
	v_add_f32_e32 v66, v66, v68
	v_and_b32_e32 v68, 0xffff0000, v72
	v_lshlrev_b32_e32 v67, 16, v72
	v_mul_f32_e32 v68, v68, v68
	v_fmac_f32_e32 v68, v67, v67
	v_add_f32_e32 v66, v66, v68
	v_and_b32_e32 v68, 0xffff0000, v73
	v_lshlrev_b32_e32 v67, 16, v73
	v_mul_f32_e32 v68, v68, v68
	v_fmac_f32_e32 v68, v67, v67
	v_add_f32_e32 v66, v66, v68
	ds_bpermute_b32 v67, v114, v66
	global_store_dwordx4 v[74:75], v[70:73], off offset:256 sc1
	s_waitcnt lgkmcnt(0)
	v_add_f32_e32 v66, v66, v67
	ds_bpermute_b32 v67, v115, v66
	s_and_saveexec_b64 s[50:51], s[38:39]
	s_cbranch_execz .LBB0_191
	v_lshlrev_b64 v[68:69], 7, v[170:171]
	v_lshl_add_u64 v[68:69], s[2:3], 0, v[68:69]
	v_lshl_add_u64 v[68:69], s[46:47], 2, v[68:69]
	s_lshl_b32 s52, s11, 2
	v_lshl_add_u64 v[68:69], v[68:69], 0, s[52:53]
	s_waitcnt lgkmcnt(0)
	v_add_f32_e32 v66, v66, v67
	global_store_dword v[68:69], v66, off sc1
.LBB0_191:
	s_or_b64 exec, exec, s[50:51]
	v_add_u32_e32 v96, 0x80, v168
	v_ashrrev_i32_e32 v97, 31, v96
	s_waitcnt lgkmcnt(0)
	v_lshlrev_b64 v[66:67], 12, v[96:97]
	v_lshl_add_u64 v[68:69], v[166:167], 0, v[66:67]
	global_load_dwordx4 v[98:101], v[68:69], off
	global_load_dwordx4 v[102:105], v[68:69], off offset:256
	v_add_u32_e32 v94, 0x90, v168
	v_add_u32_e32 v92, 0xa0, v168
	v_add_u32_e32 v90, 0xb0, v168
	v_ashrrev_i32_e32 v95, 31, v94
	v_ashrrev_i32_e32 v93, 31, v92
	v_ashrrev_i32_e32 v91, 31, v90
	v_lshlrev_b64 v[68:69], 12, v[94:95]
	v_lshlrev_b64 v[70:71], 12, v[92:93]
	v_lshlrev_b64 v[72:73], 12, v[90:91]
	v_lshl_add_u64 v[68:69], v[166:167], 0, v[68:69]
	v_lshl_add_u64 v[70:71], v[166:167], 0, v[70:71]
	v_lshl_add_u64 v[106:107], v[166:167], 0, v[72:73]
	v_lshl_add_u64 v[108:109], s[30:31], 0, v[66:67]
	global_load_dwordx4 v[86:89], v[68:69], off
	global_load_dwordx4 v[82:85], v[68:69], off offset:256
	global_load_dwordx4 v[78:81], v[70:71], off
	global_load_dwordx4 v[74:77], v[70:71], off offset:256
	s_nop 0
	global_load_dwordx4 v[70:73], v[106:107], off
	global_load_dwordx4 v[66:69], v[106:107], off offset:256
	v_lshl_add_u64 v[106:107], v[164:165], 1, v[108:109]
	s_waitcnt vmcnt(7)
	v_lshlrev_b32_e32 v110, 16, v100
	v_and_b32_e32 v100, 0xffff0000, v100
	v_lshlrev_b32_e32 v111, 16, v101
	v_and_b32_e32 v101, 0xffff0000, v101
	v_lshlrev_b32_e32 v108, 16, v98
	v_and_b32_e32 v98, 0xffff0000, v98
	v_lshlrev_b32_e32 v109, 16, v99
	v_and_b32_e32 v99, 0xffff0000, v99
	s_waitcnt vmcnt(6)
; __device__ __forceinline__ unsigned cvt_pk_bf16(float lo, float hi) { unsigned r; asm volatile("v_cvt_pk_bf16_f32 %0, %1, %2" : "=v"(r) : "v"(lo), "v"(hi)); return r; }
;     __device__ __forceinline__ void operator()(const f32x4 (&acc)[2][2][4][2], const Unit& u, int wr, int wc, int fr, int fq) const {
;     ...
;             for (int m = 0; m < 4; ++m) { const int row = u.pm * BM + ai * HALF + wr * 64 + m * 16 + fr; const size_t off = (size_t)row * ldc + col0; float ss = 0.f;
; #pragma unroll
;                 for (int bj = 0; bj < 2; ++bj) { const u32x4 pb = pre[m][bj]; const f32x4 a0 = acc[ai][bj][m][0], a1 = acc[ai][bj][m][1];
;                     u32x4 w; w.x = cvt_pk_bf16(__uint_as_float(pb.x << 16) + a0[0], __uint_as_float(pb.x & 0xffff0000u) + a0[1]); w.y = cvt_pk_bf16(__uint_as_float(pb.y << 16) + a0[2], __uint_as_float(pb.y & 0xffff0000u) + a0[3]);
;                     w.z = cvt_pk_bf16(__uint_as_float(pb.z << 16) + a1[0], __uint_as_float(pb.z & 0xffff0000u) + a1[1]); w.w = cvt_pk_bf16(__uint_as_float(pb.w << 16) + a1[2], __uint_as_float(pb.w & 0xffff0000u) + a1[3]);
; #pragma unroll
;                     for (int q = 0; q < 4; ++q) { const float r0 = __uint_as_float(w[q] << 16), r1 = __uint_as_float(w[q] & 0xffff0000u); ss += r0 * r0 + r1 * r1; }
;                     *(u32x4*)(xb + off + bj * HALF) = w; }
;                 ss += __shfl_xor(ss, 16); ss += __shfl_xor(ss, 32);
;                 if (fq == 0) rowsq[(size_t)row * 32 + u.pn * 4 + wc] = ss; }
	v_lshlrev_b32_e32 v116, 16, v104
	v_and_b32_e32 v104, 0xffff0000, v104
	v_lshlrev_b32_e32 v117, 16, v105
	v_and_b32_e32 v105, 0xffff0000, v105
	v_add_f32_e32 v59, v59, v100
	v_add_f32_e32 v61, v61, v101
	v_lshlrev_b32_e32 v113, 16, v103
	v_add_f32_e32 v62, v62, v108
	v_add_f32_e32 v63, v63, v98
	v_add_f32_e32 v64, v64, v109
	v_add_f32_e32 v65, v65, v99
	v_add_f32_e32 v58, v58, v110
	v_add_f32_e32 v60, v60, v111
	v_add_f32_e32 v98, v50, v116
	v_add_f32_e32 v99, v51, v104
	v_add_f32_e32 v100, v52, v117
	v_add_f32_e32 v101, v53, v105
	v_cvt_pk_bf16_f32 v50, v62, v63
	v_cvt_pk_bf16_f32 v51, v64, v65
	v_cvt_pk_bf16_f32 v52, v58, v59
	v_cvt_pk_bf16_f32 v53, v60, v61
	v_lshlrev_b32_e32 v112, 16, v102
	v_and_b32_e32 v59, 0xffff0000, v50
	v_and_b32_e32 v61, 0xffff0000, v51
	v_and_b32_e32 v102, 0xffff0000, v102
	v_and_b32_e32 v103, 0xffff0000, v103
	v_add_f32_e32 v56, v56, v113
	v_lshlrev_b32_e32 v58, 16, v50
	v_lshlrev_b32_e32 v60, 16, v51
	v_and_b32_e32 v63, 0xffff0000, v52
	global_store_dwordx4 v[106:107], v[50:53], off sc1
	v_add_f32_e32 v54, v54, v112
	v_add_f32_e32 v55, v55, v102
	v_mul_f32_e32 v50, v59, v59
	v_mul_f32_e32 v51, v61, v61
	v_add_f32_e32 v57, v57, v103
	v_lshlrev_b32_e32 v62, 16, v52
	v_lshlrev_b32_e32 v64, 16, v53
	v_and_b32_e32 v65, 0xffff0000, v53
	v_cvt_pk_bf16_f32 v52, v54, v55
	v_cvt_pk_bf16_f32 v53, v56, v57
	v_mul_f32_e32 v56, v63, v63
	v_fmac_f32_e32 v50, v58, v58
	v_fmac_f32_e32 v51, v60, v60
	v_mul_f32_e32 v57, v65, v65
	v_and_b32_e32 v61, 0xffff0000, v52
	v_fmac_f32_e32 v56, v62, v62
	v_add_f32_e32 v50, v50, v51
	v_lshlrev_b32_e32 v59, 16, v52
	v_fmac_f32_e32 v57, v64, v64
	v_mul_f32_e32 v58, v61, v61
	v_add_f32_e32 v50, v50, v56
	v_and_b32_e32 v51, 0xffff0000, v53
	v_lshlrev_b32_e32 v63, 16, v53
	v_fmac_f32_e32 v58, v59, v59
	v_add_f32_e32 v50, v50, v57
	v_mul_f32_e32 v51, v51, v51
	v_cvt_pk_bf16_f32 v54, v98, v99
	v_add_f32_e32 v50, v50, v58
	v_fmac_f32_e32 v51, v63, v63
	v_and_b32_e32 v56, 0xffff0000, v54
	v_add_f32_e32 v50, v50, v51
	v_lshlrev_b32_e32 v51, 16, v54
	v_mul_f32_e32 v56, v56, v56
	v_fmac_f32_e32 v56, v51, v51
	v_cvt_pk_bf16_f32 v55, v100, v101
	v_add_f32_e32 v50, v50, v56
	v_and_b32_e32 v56, 0xffff0000, v55
	v_lshlrev_b32_e32 v51, 16, v55
	v_mul_f32_e32 v56, v56, v56
	v_fmac_f32_e32 v56, v51, v51
	v_add_f32_e32 v50, v50, v56
	ds_bpermute_b32 v51, v114, v50
	global_store_dwordx4 v[106:107], v[52:55], off offset:256 sc1
	s_waitcnt lgkmcnt(0)
	v_add_f32_e32 v50, v50, v51
	ds_bpermute_b32 v51, v115, v50
	s_and_saveexec_b64 s[50:51], s[38:39]
	s_cbranch_execz .LBB0_193
	v_lshlrev_b64 v[52:53], 7, v[96:97]
	v_lshl_add_u64 v[52:53], s[2:3], 0, v[52:53]
	v_lshl_add_u64 v[52:53], s[46:47], 2, v[52:53]
	s_lshl_b32 s52, s11, 2
	v_lshl_add_u64 v[52:53], v[52:53], 0, s[52:53]
	s_waitcnt lgkmcnt(0)
	v_add_f32_e32 v50, v50, v51
	global_store_dword v[52:53], v50, off sc1
.LBB0_193:
	s_or_b64 exec, exec, s[50:51]
	s_waitcnt vmcnt(7)
	v_lshlrev_b32_e32 v52, 16, v86
	v_add_f32_e32 v46, v46, v52
	v_and_b32_e32 v52, 0xffff0000, v86
	v_add_f32_e32 v47, v47, v52
	v_cvt_pk_bf16_f32 v46, v46, v47
	v_lshlrev_b32_e32 v47, 16, v87
	v_add_f32_e32 v47, v48, v47
	v_and_b32_e32 v48, 0xffff0000, v87
	v_add_f32_e32 v48, v49, v48
	v_cvt_pk_bf16_f32 v47, v47, v48
	v_lshlrev_b32_e32 v48, 16, v88
	v_add_f32_e32 v42, v42, v48
	v_and_b32_e32 v48, 0xffff0000, v88
	v_add_f32_e32 v43, v43, v48
	v_cvt_pk_bf16_f32 v48, v42, v43
	v_and_b32_e32 v43, 0xffff0000, v89
	v_lshlrev_b32_e32 v42, 16, v89
	v_add_f32_e32 v43, v45, v43
	v_add_f32_e32 v42, v44, v42
	v_cvt_pk_bf16_f32 v49, v42, v43
	v_and_b32_e32 v43, 0xffff0000, v46
	v_lshlrev_b32_e32 v42, 16, v46
	v_mul_f32_e32 v43, v43, v43
	v_and_b32_e32 v44, 0xffff0000, v47
	v_fmac_f32_e32 v43, v42, v42
	v_lshlrev_b32_e32 v42, 16, v47
	v_mul_f32_e32 v44, v44, v44
	v_fmac_f32_e32 v44, v42, v42
	v_add_f32_e32 v42, v43, v44
	v_and_b32_e32 v44, 0xffff0000, v48
	v_lshlrev_b32_e32 v43, 16, v48
	v_mul_f32_e32 v44, v44, v44
	v_fmac_f32_e32 v44, v43, v43
	v_add_f32_e32 v42, v42, v44
	v_and_b32_e32 v44, 0xffff0000, v49
	v_lshlrev_b32_e32 v43, 16, v49
	v_mul_f32_e32 v44, v44, v44
	s_waitcnt lgkmcnt(0)
	v_lshlrev_b64 v[50:51], 11, v[94:95]
	v_fmac_f32_e32 v44, v43, v43
	s_waitcnt vmcnt(6)
	v_lshlrev_b32_e32 v45, 16, v82
	v_add_f32_e32 v44, v42, v44
	v_lshl_add_u64 v[42:43], v[50:51], 1, s[30:31]
	v_add_f32_e32 v38, v38, v45
	v_and_b32_e32 v45, 0xffff0000, v82
	v_lshl_add_u64 v[42:43], v[164:165], 1, v[42:43]
	v_add_f32_e32 v39, v39, v45
	global_store_dwordx4 v[42:43], v[46:49], off sc1
	v_cvt_pk_bf16_f32 v38, v38, v39
	v_lshlrev_b32_e32 v39, 16, v83
	v_add_f32_e32 v39, v40, v39
	v_and_b32_e32 v40, 0xffff0000, v83
	v_add_f32_e32 v40, v41, v40
	v_cvt_pk_bf16_f32 v39, v39, v40
	v_lshlrev_b32_e32 v40, 16, v84
	v_add_f32_e32 v34, v34, v40
	v_and_b32_e32 v40, 0xffff0000, v84
	v_add_f32_e32 v35, v35, v40
	v_cvt_pk_bf16_f32 v40, v34, v35
	v_and_b32_e32 v35, 0xffff0000, v85
	v_lshlrev_b32_e32 v34, 16, v85
	v_add_f32_e32 v35, v37, v35
	v_add_f32_e32 v34, v36, v34
	v_cvt_pk_bf16_f32 v41, v34, v35
	v_and_b32_e32 v35, 0xffff0000, v38
	v_lshlrev_b32_e32 v34, 16, v38
	v_mul_f32_e32 v35, v35, v35
	v_fmac_f32_e32 v35, v34, v34
	v_and_b32_e32 v36, 0xffff0000, v39
	v_add_f32_e32 v34, v44, v35
	v_lshlrev_b32_e32 v35, 16, v39
	v_mul_f32_e32 v36, v36, v36
	v_fmac_f32_e32 v36, v35, v35
	v_add_f32_e32 v34, v34, v36
	v_and_b32_e32 v36, 0xffff0000, v40
	v_lshlrev_b32_e32 v35, 16, v40
	v_mul_f32_e32 v36, v36, v36
	v_fmac_f32_e32 v36, v35, v35
	v_add_f32_e32 v34, v34, v36
	v_and_b32_e32 v36, 0xffff0000, v41
	v_lshlrev_b32_e32 v35, 16, v41
	v_mul_f32_e32 v36, v36, v36
	v_fmac_f32_e32 v36, v35, v35
	v_add_f32_e32 v34, v34, v36
	ds_bpermute_b32 v35, v114, v34
	global_store_dwordx4 v[42:43], v[38:41], off offset:256 sc1
	s_waitcnt lgkmcnt(0)
	v_add_f32_e32 v34, v34, v35
	ds_bpermute_b32 v35, v115, v34
	s_and_saveexec_b64 s[50:51], s[38:39]
	s_cbranch_execz .LBB0_195
	v_lshlrev_b64 v[36:37], 7, v[94:95]
	v_lshl_add_u64 v[36:37], s[2:3], 0, v[36:37]
	v_lshl_add_u64 v[36:37], s[46:47], 2, v[36:37]
	s_lshl_b32 s52, s11, 2
	v_lshl_add_u64 v[36:37], v[36:37], 0, s[52:53]
	s_waitcnt lgkmcnt(0)
	v_add_f32_e32 v34, v34, v35
	global_store_dword v[36:37], v34, off sc1
; __device__ __forceinline__ unsigned cvt_pk_bf16(float lo, float hi) { unsigned r; asm volatile("v_cvt_pk_bf16_f32 %0, %1, %2" : "=v"(r) : "v"(lo), "v"(hi)); return r; }
;     __device__ __forceinline__ void operator()(const f32x4 (&acc)[2][2][4][2], const Unit& u, int wr, int wc, int fr, int fq) const {
;     ...
;             for (int m = 0; m < 4; ++m) { const int row = u.pm * BM + ai * HALF + wr * 64 + m * 16 + fr; const size_t off = (size_t)row * ldc + col0; float ss = 0.f;
; #pragma unroll
;                 for (int bj = 0; bj < 2; ++bj) { const u32x4 pb = pre[m][bj]; const f32x4 a0 = acc[ai][bj][m][0], a1 = acc[ai][bj][m][1];
;                     u32x4 w; w.x = cvt_pk_bf16(__uint_as_float(pb.x << 16) + a0[0], __uint_as_float(pb.x & 0xffff0000u) + a0[1]); w.y = cvt_pk_bf16(__uint_as_float(pb.y << 16) + a0[2], __uint_as_float(pb.y & 0xffff0000u) + a0[3]);
;                     w.z = cvt_pk_bf16(__uint_as_float(pb.z << 16) + a1[0], __uint_as_float(pb.z & 0xffff0000u) + a1[1]); w.w = cvt_pk_bf16(__uint_as_float(pb.w << 16) + a1[2], __uint_as_float(pb.w & 0xffff0000u) + a1[3]);
; #pragma unroll
;                     for (int q = 0; q < 4; ++q) { const float r0 = __uint_as_float(w[q] << 16), r1 = __uint_as_float(w[q] & 0xffff0000u); ss += r0 * r0 + r1 * r1; }
;                     *(u32x4*)(xb + off + bj * HALF) = w; }
;                 ss += __shfl_xor(ss, 16); ss += __shfl_xor(ss, 32);
;                 if (fq == 0) rowsq[(size_t)row * 32 + u.pn * 4 + wc] = ss; }
.LBB0_195:
	s_or_b64 exec, exec, s[50:51]
	s_waitcnt vmcnt(7)
	v_lshlrev_b32_e32 v36, 16, v78
	v_add_f32_e32 v30, v30, v36
	v_and_b32_e32 v36, 0xffff0000, v78
	v_add_f32_e32 v31, v31, v36
	v_cvt_pk_bf16_f32 v30, v30, v31
	v_lshlrev_b32_e32 v31, 16, v79
	v_add_f32_e32 v31, v32, v31
	v_and_b32_e32 v32, 0xffff0000, v79
	v_add_f32_e32 v32, v33, v32
	v_cvt_pk_bf16_f32 v31, v31, v32
	v_lshlrev_b32_e32 v32, 16, v80
	v_add_f32_e32 v26, v26, v32
	v_and_b32_e32 v32, 0xffff0000, v80
	v_add_f32_e32 v27, v27, v32
	v_cvt_pk_bf16_f32 v32, v26, v27
	v_and_b32_e32 v27, 0xffff0000, v81
	v_lshlrev_b32_e32 v26, 16, v81
	v_add_f32_e32 v27, v29, v27
	v_add_f32_e32 v26, v28, v26
	v_cvt_pk_bf16_f32 v33, v26, v27
	v_and_b32_e32 v27, 0xffff0000, v30
	v_lshlrev_b32_e32 v26, 16, v30
	v_mul_f32_e32 v27, v27, v27
	v_and_b32_e32 v28, 0xffff0000, v31
	v_fmac_f32_e32 v27, v26, v26
	v_lshlrev_b32_e32 v26, 16, v31
	v_mul_f32_e32 v28, v28, v28
	v_fmac_f32_e32 v28, v26, v26
	v_add_f32_e32 v26, v27, v28
	v_and_b32_e32 v28, 0xffff0000, v32
	v_lshlrev_b32_e32 v27, 16, v32
	v_mul_f32_e32 v28, v28, v28
	v_fmac_f32_e32 v28, v27, v27
	v_add_f32_e32 v26, v26, v28
	v_and_b32_e32 v28, 0xffff0000, v33
	v_lshlrev_b32_e32 v27, 16, v33
	v_mul_f32_e32 v28, v28, v28
	s_waitcnt lgkmcnt(0)
	v_lshlrev_b64 v[34:35], 11, v[92:93]
	v_fmac_f32_e32 v28, v27, v27
	s_waitcnt vmcnt(6)
	v_lshlrev_b32_e32 v29, 16, v74
	v_add_f32_e32 v28, v26, v28
	v_lshl_add_u64 v[26:27], v[34:35], 1, s[30:31]
	v_add_f32_e32 v22, v22, v29
	v_and_b32_e32 v29, 0xffff0000, v74
	v_lshl_add_u64 v[26:27], v[164:165], 1, v[26:27]
	v_add_f32_e32 v23, v23, v29
	global_store_dwordx4 v[26:27], v[30:33], off sc1
	v_cvt_pk_bf16_f32 v22, v22, v23
	v_lshlrev_b32_e32 v23, 16, v75
	v_add_f32_e32 v23, v24, v23
	v_and_b32_e32 v24, 0xffff0000, v75
	v_add_f32_e32 v24, v25, v24
	v_cvt_pk_bf16_f32 v23, v23, v24
	v_lshlrev_b32_e32 v24, 16, v76
	v_add_f32_e32 v18, v18, v24
	v_and_b32_e32 v24, 0xffff0000, v76
	v_add_f32_e32 v19, v19, v24
	v_cvt_pk_bf16_f32 v24, v18, v19
	v_and_b32_e32 v19, 0xffff0000, v77
	v_lshlrev_b32_e32 v18, 16, v77
	v_add_f32_e32 v19, v21, v19
	v_add_f32_e32 v18, v20, v18
	v_cvt_pk_bf16_f32 v25, v18, v19
	v_and_b32_e32 v19, 0xffff0000, v22
	v_lshlrev_b32_e32 v18, 16, v22
	v_mul_f32_e32 v19, v19, v19
	v_fmac_f32_e32 v19, v18, v18
	v_and_b32_e32 v20, 0xffff0000, v23
	v_add_f32_e32 v18, v28, v19
	v_lshlrev_b32_e32 v19, 16, v23
	v_mul_f32_e32 v20, v20, v20
	v_fmac_f32_e32 v20, v19, v19
	v_add_f32_e32 v18, v18, v20
	v_and_b32_e32 v20, 0xffff0000, v24
	v_lshlrev_b32_e32 v19, 16, v24
	v_mul_f32_e32 v20, v20, v20
	v_fmac_f32_e32 v20, v19, v19
	v_add_f32_e32 v18, v18, v20
	v_and_b32_e32 v20, 0xffff0000, v25
	v_lshlrev_b32_e32 v19, 16, v25
	v_mul_f32_e32 v20, v20, v20
	v_fmac_f32_e32 v20, v19, v19
	v_add_f32_e32 v18, v18, v20
	ds_bpermute_b32 v19, v114, v18
	global_store_dwordx4 v[26:27], v[22:25], off offset:256 sc1
	s_waitcnt lgkmcnt(0)
	v_add_f32_e32 v18, v18, v19
	ds_bpermute_b32 v19, v115, v18
	s_and_saveexec_b64 s[50:51], s[38:39]
	s_cbranch_execz .LBB0_197
	v_lshlrev_b64 v[20:21], 7, v[92:93]
	v_lshl_add_u64 v[20:21], s[2:3], 0, v[20:21]
	v_lshl_add_u64 v[20:21], s[46:47], 2, v[20:21]
	s_lshl_b32 s52, s11, 2
	v_lshl_add_u64 v[20:21], v[20:21], 0, s[52:53]
	s_waitcnt lgkmcnt(0)
	v_add_f32_e32 v18, v18, v19
	global_store_dword v[20:21], v18, off sc1
.LBB0_197:
	s_or_b64 exec, exec, s[50:51]
	s_waitcnt vmcnt(7)
	v_lshlrev_b32_e32 v20, 16, v70
	v_add_f32_e32 v14, v14, v20
	v_and_b32_e32 v20, 0xffff0000, v70
	v_add_f32_e32 v15, v15, v20
	v_cvt_pk_bf16_f32 v14, v14, v15
	v_lshlrev_b32_e32 v15, 16, v71
	v_add_f32_e32 v15, v16, v15
	v_and_b32_e32 v16, 0xffff0000, v71
	v_add_f32_e32 v16, v17, v16
	v_cvt_pk_bf16_f32 v15, v15, v16
	v_lshlrev_b32_e32 v16, 16, v72
	v_add_f32_e32 v10, v10, v16
	v_and_b32_e32 v16, 0xffff0000, v72
	v_add_f32_e32 v11, v11, v16
	v_cvt_pk_bf16_f32 v16, v10, v11
	v_and_b32_e32 v11, 0xffff0000, v73
	v_lshlrev_b32_e32 v10, 16, v73
	v_add_f32_e32 v11, v13, v11
	v_add_f32_e32 v10, v12, v10
	v_cvt_pk_bf16_f32 v17, v10, v11
	v_and_b32_e32 v11, 0xffff0000, v14
	v_lshlrev_b32_e32 v10, 16, v14
	v_mul_f32_e32 v11, v11, v11
	v_and_b32_e32 v12, 0xffff0000, v15
	v_fmac_f32_e32 v11, v10, v10
	v_lshlrev_b32_e32 v10, 16, v15
	v_mul_f32_e32 v12, v12, v12
	v_fmac_f32_e32 v12, v10, v10
	v_add_f32_e32 v10, v11, v12
	v_and_b32_e32 v12, 0xffff0000, v16
	v_lshlrev_b32_e32 v11, 16, v16
	v_mul_f32_e32 v12, v12, v12
	v_fmac_f32_e32 v12, v11, v11
	v_add_f32_e32 v10, v10, v12
	v_and_b32_e32 v12, 0xffff0000, v17
	v_lshlrev_b32_e32 v11, 16, v17
	v_mul_f32_e32 v12, v12, v12
	s_waitcnt lgkmcnt(0)
	v_lshlrev_b64 v[18:19], 11, v[90:91]
	v_fmac_f32_e32 v12, v11, v11
	s_waitcnt vmcnt(6)
	v_lshlrev_b32_e32 v13, 16, v66
	v_add_f32_e32 v12, v10, v12
	v_lshl_add_u64 v[10:11], v[18:19], 1, s[30:31]
	v_add_f32_e32 v6, v6, v13
	v_and_b32_e32 v13, 0xffff0000, v66
	v_lshl_add_u64 v[10:11], v[164:165], 1, v[10:11]
	v_add_f32_e32 v7, v7, v13
	global_store_dwordx4 v[10:11], v[14:17], off sc1
	v_cvt_pk_bf16_f32 v6, v6, v7
	v_lshlrev_b32_e32 v7, 16, v67
	v_add_f32_e32 v7, v8, v7
	v_and_b32_e32 v8, 0xffff0000, v67
	v_add_f32_e32 v8, v9, v8
	v_cvt_pk_bf16_f32 v7, v7, v8
	v_lshlrev_b32_e32 v8, 16, v68
	v_add_f32_e32 v2, v2, v8
	v_and_b32_e32 v8, 0xffff0000, v68
	v_add_f32_e32 v3, v3, v8
	v_cvt_pk_bf16_f32 v8, v2, v3
	v_and_b32_e32 v3, 0xffff0000, v69
	v_lshlrev_b32_e32 v2, 16, v69
	v_add_f32_e32 v3, v5, v3
	v_add_f32_e32 v2, v4, v2
	v_cvt_pk_bf16_f32 v9, v2, v3
	v_and_b32_e32 v3, 0xffff0000, v6
	v_lshlrev_b32_e32 v2, 16, v6
	v_mul_f32_e32 v3, v3, v3
	v_fmac_f32_e32 v3, v2, v2
	v_and_b32_e32 v4, 0xffff0000, v7
	v_add_f32_e32 v2, v12, v3
	v_lshlrev_b32_e32 v3, 16, v7
	v_mul_f32_e32 v4, v4, v4
	v_fmac_f32_e32 v4, v3, v3
	v_add_f32_e32 v2, v2, v4
	v_and_b32_e32 v4, 0xffff0000, v8
	v_lshlrev_b32_e32 v3, 16, v8
	v_mul_f32_e32 v4, v4, v4
	v_fmac_f32_e32 v4, v3, v3
	v_add_f32_e32 v2, v2, v4
	v_and_b32_e32 v4, 0xffff0000, v9
	v_lshlrev_b32_e32 v3, 16, v9
	v_mul_f32_e32 v4, v4, v4
	v_fmac_f32_e32 v4, v3, v3
	v_add_f32_e32 v2, v2, v4
	ds_bpermute_b32 v3, v114, v2
	global_store_dwordx4 v[10:11], v[6:9], off offset:256 sc1
	s_waitcnt lgkmcnt(0)
	v_add_f32_e32 v2, v2, v3
	ds_bpermute_b32 v3, v115, v2
	s_and_saveexec_b64 s[50:51], s[38:39]
	s_cbranch_execz .LBB0_199
	v_lshlrev_b64 v[4:5], 7, v[90:91]
	v_lshl_add_u64 v[4:5], s[2:3], 0, v[4:5]
	v_lshl_add_u64 v[4:5], s[46:47], 2, v[4:5]
	s_lshl_b32 s52, s11, 2
	v_lshl_add_u64 v[4:5], v[4:5], 0, s[52:53]
	s_waitcnt lgkmcnt(0)
	v_add_f32_e32 v2, v2, v3
	global_store_dword v[4:5], v2, off sc1

; __device__ __forceinline__ unsigned cvt_pk_bf16(float lo, float hi) { unsigned r; asm volatile("v_cvt_pk_bf16_f32 %0, %1, %2" : "=v"(r) : "v"(lo), "v"(hi)); return r; }
;     __device__ __forceinline__ void operator()(const f32x4 (&acc)[2][2][4][2], const Unit& u, int wr, int wc, int fr, int fq) const {
;         const int row0 = u.pm * BM + wr * 64 + fr, col0 = wc * 32 + 8 * fq;
; #pragma unroll
;         for (int ai = 0; ai < 2; ++ai) {
;             f32x4 pa[4], pb[4];
; #pragma unroll
;             for (int m = 0; m < 4; ++m) { const f32x4* pp = (const f32x4*)(rowsq + (size_t)(row0 + ai * HALF + m * 16) * 32 + 8 * fq); pa[m] = pp[0]; pb[m] = pp[1]; }
; #pragma unroll
;             for (int m = 0; m < 4; ++m) { const int row = row0 + ai * HALF + m * 16; const f32x4 a = pa[m], b = pb[m];
;                 float sq = ((a[0] + a[1]) + (a[2] + a[3])) + ((b[0] + b[1]) + (b[2] + b[3])); sq += __shfl_xor(sq, 16); sq += __shfl_xor(sq, 32);
;                 const float rs = __builtin_amdgcn_rsqf(sq * inv_k + eps);
; #pragma unroll
;                 for (int bj = 0; bj < 2; ++bj) { const f32x4 v0 = acc[ai][bj][m][0] * rs, v1 = acc[ai][bj][m][1] * rs;
;                     u32x4 w; w.x = cvt_pk_bf16(v0[0], v0[1]); w.y = cvt_pk_bf16(v0[2], v0[3]); w.z = cvt_pk_bf16(v1[0], v1[1]); w.w = cvt_pk_bf16(v1[2], v1[3]);
;                     *(u32x4*)(O + ((size_t)(u.pn * 2 + bj) * Mrows + row) * HALF + col0) = w; } }
;             asm volatile("" ::: "memory"); }
.LBB0_217:
	v_cmp_lt_i32_e32 vcc, v224, v219
	v_lshl_add_u32 v168, s36, 8, v176
	v_ashrrev_i32_e32 v169, 31, v168
	v_cndmask_b32_e32 v114, v218, v224, vcc
	v_cmp_lt_i32_e32 vcc, v225, v219
	v_lshlrev_b32_e32 v180, 2, v114
	v_or_b32_e32 v174, 16, v168
	v_cndmask_b32_e32 v114, v218, v225, vcc
	v_lshlrev_b32_e32 v179, 2, v114
	v_lshlrev_b64 v[114:115], 7, v[168:169]
	v_lshl_add_u64 v[114:115], v[162:163], 0, v[114:115]
	global_load_dwordx4 v[182:185], v[114:115], off
	global_load_dwordx4 v[186:189], v[114:115], off offset:16
	v_ashrrev_i32_e32 v175, 31, v174
	v_lshlrev_b64 v[114:115], 7, v[174:175]
	v_lshl_add_u64 v[114:115], v[162:163], 0, v[114:115]
	global_load_dwordx4 v[146:149], v[114:115], off
	global_load_dwordx4 v[150:153], v[114:115], off offset:16
	v_or_b32_e32 v172, 32, v168
	v_ashrrev_i32_e32 v173, 31, v172
	v_lshlrev_b64 v[114:115], 7, v[172:173]
	v_lshl_add_u64 v[114:115], v[162:163], 0, v[114:115]
	global_load_dwordx4 v[134:137], v[114:115], off
	global_load_dwordx4 v[130:133], v[114:115], off offset:16
	v_or_b32_e32 v170, 48, v168
	v_ashrrev_i32_e32 v171, 31, v170
	v_lshlrev_b64 v[114:115], 7, v[170:171]
	v_lshl_add_u64 v[114:115], v[162:163], 0, v[114:115]
	global_load_dwordx4 v[118:121], v[114:115], off
	s_nop 0
	global_load_dwordx4 v[114:117], v[114:115], off offset:16
	s_lshl_b32 s14, s14, 1
	s_ashr_i32 s15, s14, 31
	s_lshl_b64 s[34:35], s[14:15], 14
	s_or_b32 s14, s14, 1
	s_ashr_i32 s15, s14, 31
	s_lshl_b64 s[36:37], s[14:15], 14
	s_andn2_b64 vcc, exec, s[38:39]
	s_waitcnt vmcnt(0)
	v_mov_b32_e32 v190, v182
	v_mov_b32_e32 v191, v186
	v_mov_b32_e32 v186, v183
	v_pk_add_f32 v[182:183], v[190:191], v[186:187]
	v_mov_b32_e32 v186, v184
	v_mov_b32_e32 v187, v188
	v_mov_b32_e32 v188, v185
	v_pk_add_f32 v[184:185], v[186:187], v[188:189]
	s_nop 0
	v_pk_add_f32 v[182:183], v[182:183], v[184:185]
	s_nop 0
	v_add_f32_e32 v181, v182, v183
	ds_bpermute_b32 v182, v180, v181
	s_waitcnt lgkmcnt(0)
	v_add_f32_e32 v181, v181, v182
	ds_bpermute_b32 v182, v179, v181
	s_waitcnt lgkmcnt(0)
	v_add_f32_e32 v181, v181, v182
	v_fmamk_f32 v181, v181, 0x3a000000, v215
	v_rsq_f32_e32 v182, v181
	s_nop 0
	v_pk_mul_f32 v[142:143], v[142:143], v[182:183] op_sel_hi:[1,0]
	v_pk_mul_f32 v[184:185], v[140:141], v[182:183] op_sel_hi:[1,0]
	v_pk_mul_f32 v[140:141], v[138:139], v[182:183] op_sel_hi:[1,0]
	v_cvt_pk_bf16_f32 v138, v142, v143
	v_lshl_add_u64 v[142:143], s[34:35], 0, v[168:169]
	v_lshlrev_b64 v[142:143], 8, v[142:143]
	v_pk_mul_f32 v[144:145], v[144:145], v[182:183] op_sel_hi:[1,0]
	v_lshl_add_u64 v[142:143], v[160:161], 0, v[142:143]
	v_cvt_pk_bf16_f32 v139, v144, v145
	v_pk_mul_f32 v[126:127], v[126:127], v[182:183] op_sel_hi:[1,0]
	v_cvt_pk_bf16_f32 v140, v140, v141
	v_cvt_pk_bf16_f32 v141, v184, v185
	global_store_dwordx4 v[142:143], v[138:141], off sc1
	v_pk_mul_f32 v[128:129], v[128:129], v[182:183] op_sel_hi:[1,0]
	s_nop 0
	v_pk_mul_f32 v[138:139], v[124:125], v[182:183] op_sel_hi:[1,0]
	v_pk_mul_f32 v[124:125], v[122:123], v[182:183] op_sel_hi:[1,0]
	v_cvt_pk_bf16_f32 v122, v126, v127
	v_lshl_add_u64 v[126:127], s[36:37], 0, v[168:169]
	v_lshlrev_b64 v[126:127], 8, v[126:127]
	v_cvt_pk_bf16_f32 v123, v128, v129
	v_cvt_pk_bf16_f32 v124, v124, v125
	v_cvt_pk_bf16_f32 v125, v138, v139
	v_lshl_add_u64 v[126:127], v[160:161], 0, v[126:127]
	global_store_dwordx4 v[126:127], v[122:125], off sc1
	s_nop 1
	v_mov_b32_e32 v122, v146
	v_mov_b32_e32 v123, v150
	v_mov_b32_e32 v150, v147
	v_mov_b32_e32 v124, v148
	v_mov_b32_e32 v125, v152
	v_mov_b32_e32 v152, v149
	v_pk_add_f32 v[122:123], v[122:123], v[150:151]
	v_pk_add_f32 v[124:125], v[124:125], v[152:153]
	s_nop 0
	v_pk_add_f32 v[122:123], v[122:123], v[124:125]
	s_nop 0
	v_add_f32_e32 v122, v122, v123
	ds_bpermute_b32 v123, v180, v122
	s_waitcnt lgkmcnt(0)
	v_add_f32_e32 v122, v122, v123
	ds_bpermute_b32 v123, v179, v122
	s_waitcnt lgkmcnt(0)
	v_add_f32_e32 v122, v122, v123
	v_fmamk_f32 v122, v122, 0x3a000000, v215
	v_rsq_f32_e32 v122, v122
	s_nop 0
	v_pk_mul_f32 v[110:111], v[110:111], v[122:123] op_sel_hi:[1,0]
	v_pk_mul_f32 v[124:125], v[108:109], v[122:123] op_sel_hi:[1,0]
	v_pk_mul_f32 v[108:109], v[106:107], v[122:123] op_sel_hi:[1,0]
	v_cvt_pk_bf16_f32 v106, v110, v111
	v_lshl_add_u64 v[110:111], s[34:35], 0, v[174:175]
	v_lshlrev_b64 v[110:111], 8, v[110:111]
	v_pk_mul_f32 v[112:113], v[112:113], v[122:123] op_sel_hi:[1,0]
	v_lshl_add_u64 v[110:111], v[160:161], 0, v[110:111]
	v_cvt_pk_bf16_f32 v107, v112, v113
	v_pk_mul_f32 v[102:103], v[102:103], v[122:123] op_sel_hi:[1,0]
	v_cvt_pk_bf16_f32 v108, v108, v109
	v_cvt_pk_bf16_f32 v109, v124, v125
	global_store_dwordx4 v[110:111], v[106:109], off sc1
	v_pk_mul_f32 v[104:105], v[104:105], v[122:123] op_sel_hi:[1,0]
	s_nop 0
	v_pk_mul_f32 v[106:107], v[100:101], v[122:123] op_sel_hi:[1,0]
	v_pk_mul_f32 v[100:101], v[98:99], v[122:123] op_sel_hi:[1,0]
	v_cvt_pk_bf16_f32 v98, v102, v103
	v_lshl_add_u64 v[102:103], s[36:37], 0, v[174:175]
	v_lshlrev_b64 v[102:103], 8, v[102:103]
	v_cvt_pk_bf16_f32 v99, v104, v105
	v_cvt_pk_bf16_f32 v100, v100, v101
	v_cvt_pk_bf16_f32 v101, v106, v107
	v_lshl_add_u64 v[102:103], v[160:161], 0, v[102:103]
	global_store_dwordx4 v[102:103], v[98:101], off sc1
	v_add_u32_e32 v104, 0x80, v168
	v_ashrrev_i32_e32 v105, 31, v104
	v_mov_b32_e32 v98, v134
	v_mov_b32_e32 v99, v130
	v_mov_b32_e32 v130, v135
	v_mov_b32_e32 v100, v136
	v_mov_b32_e32 v101, v132
	v_mov_b32_e32 v132, v137
	v_pk_add_f32 v[98:99], v[98:99], v[130:131]
	v_pk_add_f32 v[100:101], v[100:101], v[132:133]
	s_nop 0
	v_pk_add_f32 v[98:99], v[98:99], v[100:101]
	s_nop 0
	v_add_f32_e32 v98, v98, v99
	ds_bpermute_b32 v99, v180, v98
	s_waitcnt lgkmcnt(0)
; __device__ __forceinline__ unsigned cvt_pk_bf16(float lo, float hi) { unsigned r; asm volatile("v_cvt_pk_bf16_f32 %0, %1, %2" : "=v"(r) : "v"(lo), "v"(hi)); return r; }
;     __device__ __forceinline__ void operator()(const f32x4 (&acc)[2][2][4][2], const Unit& u, int wr, int wc, int fr, int fq) const {
;         const int row0 = u.pm * BM + wr * 64 + fr, col0 = wc * 32 + 8 * fq;
; #pragma unroll
;         for (int ai = 0; ai < 2; ++ai) {
;             f32x4 pa[4], pb[4];
; #pragma unroll
;             for (int m = 0; m < 4; ++m) { const f32x4* pp = (const f32x4*)(rowsq + (size_t)(row0 + ai * HALF + m * 16) * 32 + 8 * fq); pa[m] = pp[0]; pb[m] = pp[1]; }
; #pragma unroll
;             for (int m = 0; m < 4; ++m) { const int row = row0 + ai * HALF + m * 16; const f32x4 a = pa[m], b = pb[m];
;                 float sq = ((a[0] + a[1]) + (a[2] + a[3])) + ((b[0] + b[1]) + (b[2] + b[3])); sq += __shfl_xor(sq, 16); sq += __shfl_xor(sq, 32);
;                 const float rs = __builtin_amdgcn_rsqf(sq * inv_k + eps);
; #pragma unroll
;                 for (int bj = 0; bj < 2; ++bj) { const f32x4 v0 = acc[ai][bj][m][0] * rs, v1 = acc[ai][bj][m][1] * rs;
;                     u32x4 w; w.x = cvt_pk_bf16(v0[0], v0[1]); w.y = cvt_pk_bf16(v0[2], v0[3]); w.z = cvt_pk_bf16(v1[0], v1[1]); w.w = cvt_pk_bf16(v1[2], v1[3]);
;                     *(u32x4*)(O + ((size_t)(u.pn * 2 + bj) * Mrows + row) * HALF + col0) = w; } }
;             asm volatile("" ::: "memory"); }
	v_add_f32_e32 v98, v98, v99
	ds_bpermute_b32 v99, v179, v98
	s_waitcnt lgkmcnt(0)
	v_add_f32_e32 v98, v98, v99
	v_fmamk_f32 v98, v98, 0x3a000000, v215
	v_rsq_f32_e32 v98, v98
	s_nop 0
	v_pk_mul_f32 v[94:95], v[94:95], v[98:99] op_sel_hi:[1,0]
	v_pk_mul_f32 v[100:101], v[92:93], v[98:99] op_sel_hi:[1,0]
	v_pk_mul_f32 v[92:93], v[90:91], v[98:99] op_sel_hi:[1,0]
	v_cvt_pk_bf16_f32 v90, v94, v95
	v_lshl_add_u64 v[94:95], s[34:35], 0, v[172:173]
	v_lshlrev_b64 v[94:95], 8, v[94:95]
	v_pk_mul_f32 v[96:97], v[96:97], v[98:99] op_sel_hi:[1,0]
	v_lshl_add_u64 v[94:95], v[160:161], 0, v[94:95]
	v_cvt_pk_bf16_f32 v91, v96, v97
	v_pk_mul_f32 v[86:87], v[86:87], v[98:99] op_sel_hi:[1,0]
	v_cvt_pk_bf16_f32 v92, v92, v93
	v_cvt_pk_bf16_f32 v93, v100, v101
	global_store_dwordx4 v[94:95], v[90:93], off sc1
	v_pk_mul_f32 v[88:89], v[88:89], v[98:99] op_sel_hi:[1,0]
	s_nop 0
	v_pk_mul_f32 v[90:91], v[84:85], v[98:99] op_sel_hi:[1,0]
	v_pk_mul_f32 v[84:85], v[82:83], v[98:99] op_sel_hi:[1,0]
	v_cvt_pk_bf16_f32 v82, v86, v87
	v_lshl_add_u64 v[86:87], s[36:37], 0, v[172:173]
	v_lshlrev_b64 v[86:87], 8, v[86:87]
	v_cvt_pk_bf16_f32 v83, v88, v89
	v_cvt_pk_bf16_f32 v84, v84, v85
	v_cvt_pk_bf16_f32 v85, v90, v91
	v_lshl_add_u64 v[86:87], v[160:161], 0, v[86:87]
	global_store_dwordx4 v[86:87], v[82:85], off sc1
	v_add_u32_e32 v86, 0x90, v168
	v_ashrrev_i32_e32 v87, 31, v86
	v_mov_b32_e32 v82, v118
	v_mov_b32_e32 v83, v114
	v_mov_b32_e32 v114, v119
	v_mov_b32_e32 v84, v120
	v_mov_b32_e32 v85, v116
	v_mov_b32_e32 v116, v121
	v_pk_add_f32 v[82:83], v[82:83], v[114:115]
	v_pk_add_f32 v[84:85], v[84:85], v[116:117]
	s_nop 0
	v_pk_add_f32 v[82:83], v[82:83], v[84:85]
	s_nop 0
	v_add_f32_e32 v82, v82, v83
	ds_bpermute_b32 v83, v180, v82
	s_waitcnt lgkmcnt(0)
	v_add_f32_e32 v82, v82, v83
	ds_bpermute_b32 v83, v179, v82
	s_waitcnt lgkmcnt(0)
	v_add_f32_e32 v82, v82, v83
	v_fmamk_f32 v82, v82, 0x3a000000, v215
	v_rsq_f32_e32 v82, v82
	s_nop 0
	v_pk_mul_f32 v[78:79], v[78:79], v[82:83] op_sel_hi:[1,0]
	v_pk_mul_f32 v[84:85], v[76:77], v[82:83] op_sel_hi:[1,0]
	v_pk_mul_f32 v[76:77], v[74:75], v[82:83] op_sel_hi:[1,0]
	v_cvt_pk_bf16_f32 v74, v78, v79
	v_lshl_add_u64 v[78:79], s[34:35], 0, v[170:171]
	v_lshlrev_b64 v[78:79], 8, v[78:79]
	v_pk_mul_f32 v[80:81], v[80:81], v[82:83] op_sel_hi:[1,0]
	v_lshl_add_u64 v[78:79], v[160:161], 0, v[78:79]
	v_cvt_pk_bf16_f32 v75, v80, v81
	v_pk_mul_f32 v[70:71], v[70:71], v[82:83] op_sel_hi:[1,0]
	v_cvt_pk_bf16_f32 v76, v76, v77
	v_cvt_pk_bf16_f32 v77, v84, v85
	global_store_dwordx4 v[78:79], v[74:77], off sc1
	v_pk_mul_f32 v[72:73], v[72:73], v[82:83] op_sel_hi:[1,0]
	v_add_u32_e32 v84, 0xa0, v168
	v_pk_mul_f32 v[74:75], v[68:69], v[82:83] op_sel_hi:[1,0]
	v_pk_mul_f32 v[68:69], v[66:67], v[82:83] op_sel_hi:[1,0]
	v_cvt_pk_bf16_f32 v66, v70, v71
	v_lshl_add_u64 v[70:71], s[36:37], 0, v[170:171]
	v_lshlrev_b64 v[70:71], 8, v[70:71]
	v_cvt_pk_bf16_f32 v67, v72, v73
	v_lshl_add_u64 v[70:71], v[160:161], 0, v[70:71]
	v_cvt_pk_bf16_f32 v68, v68, v69
	v_cvt_pk_bf16_f32 v69, v74, v75
	global_store_dwordx4 v[70:71], v[66:69], off sc1
	v_ashrrev_i32_e32 v85, 31, v84
	v_add_u32_e32 v82, 0xb0, v168
	v_lshlrev_b64 v[66:67], 7, v[104:105]
	v_lshl_add_u64 v[66:67], v[162:163], 0, v[66:67]
	global_load_dwordx4 v[88:91], v[66:67], off
	global_load_dwordx4 v[92:95], v[66:67], off offset:16
	v_lshlrev_b64 v[66:67], 7, v[86:87]
	v_lshl_add_u64 v[66:67], v[162:163], 0, v[66:67]
	global_load_dwordx4 v[96:99], v[66:67], off
	global_load_dwordx4 v[100:103], v[66:67], off offset:16
	v_lshlrev_b64 v[66:67], 7, v[84:85]
	v_lshl_add_u64 v[66:67], v[162:163], 0, v[66:67]
	global_load_dwordx4 v[78:81], v[66:67], off
	global_load_dwordx4 v[74:77], v[66:67], off offset:16
	v_ashrrev_i32_e32 v83, 31, v82
	v_lshlrev_b64 v[66:67], 7, v[82:83]
	v_lshl_add_u64 v[66:67], v[162:163], 0, v[66:67]
	global_load_dwordx4 v[70:73], v[66:67], off
	s_nop 0
	global_load_dwordx4 v[66:69], v[66:67], off offset:16
	s_waitcnt vmcnt(7)
	v_mov_b32_e32 v106, v88
	s_waitcnt vmcnt(6)
	v_mov_b32_e32 v107, v92
	v_mov_b32_e32 v92, v89
	v_pk_add_f32 v[88:89], v[106:107], v[92:93]
	v_mov_b32_e32 v92, v90
	v_mov_b32_e32 v93, v94
	v_mov_b32_e32 v94, v91
	v_pk_add_f32 v[90:91], v[92:93], v[94:95]
	s_nop 0
	v_pk_add_f32 v[88:89], v[88:89], v[90:91]
	s_nop 0
	v_add_f32_e32 v88, v88, v89
	ds_bpermute_b32 v89, v180, v88
	s_waitcnt lgkmcnt(0)
	v_add_f32_e32 v88, v88, v89
	ds_bpermute_b32 v89, v179, v88
	s_waitcnt lgkmcnt(0)
	v_add_f32_e32 v88, v88, v89
	v_fmamk_f32 v88, v88, 0x3a000000, v215
	v_rsq_f32_e32 v88, v88
	s_nop 0
	v_pk_mul_f32 v[62:63], v[62:63], v[88:89] op_sel_hi:[1,0]
	v_pk_mul_f32 v[90:91], v[60:61], v[88:89] op_sel_hi:[1,0]
	v_pk_mul_f32 v[60:61], v[58:59], v[88:89] op_sel_hi:[1,0]
	v_cvt_pk_bf16_f32 v58, v62, v63
	v_lshl_add_u64 v[62:63], s[34:35], 0, v[104:105]
	v_lshlrev_b64 v[62:63], 8, v[62:63]
	v_pk_mul_f32 v[64:65], v[64:65], v[88:89] op_sel_hi:[1,0]
	v_lshl_add_u64 v[62:63], v[160:161], 0, v[62:63]
	v_cvt_pk_bf16_f32 v59, v64, v65
	v_pk_mul_f32 v[54:55], v[54:55], v[88:89] op_sel_hi:[1,0]
	v_cvt_pk_bf16_f32 v60, v60, v61
	v_cvt_pk_bf16_f32 v61, v90, v91
	global_store_dwordx4 v[62:63], v[58:61], off sc1
	v_pk_mul_f32 v[56:57], v[56:57], v[88:89] op_sel_hi:[1,0]
	s_nop 0
	v_pk_mul_f32 v[58:59], v[52:53], v[88:89] op_sel_hi:[1,0]
	v_pk_mul_f32 v[52:53], v[50:51], v[88:89] op_sel_hi:[1,0]
	v_cvt_pk_bf16_f32 v50, v54, v55
	v_lshl_add_u64 v[54:55], s[36:37], 0, v[104:105]
	v_lshlrev_b64 v[54:55], 8, v[54:55]
	v_cvt_pk_bf16_f32 v51, v56, v57
	v_cvt_pk_bf16_f32 v52, v52, v53
	v_cvt_pk_bf16_f32 v53, v58, v59
	v_lshl_add_u64 v[54:55], v[160:161], 0, v[54:55]
	global_store_dwordx4 v[54:55], v[50:53], off sc1
	s_waitcnt vmcnt(7)
; __device__ __forceinline__ unsigned cvt_pk_bf16(float lo, float hi) { unsigned r; asm volatile("v_cvt_pk_bf16_f32 %0, %1, %2" : "=v"(r) : "v"(lo), "v"(hi)); return r; }
; #define PG8_BAR __builtin_amdgcn_s_barrier()
;     __device__ __forceinline__ void operator()(const f32x4 (&acc)[2][2][4][2], const Unit& u, int wr, int wc, int fr, int fq) const {
;     ...
;             for (int m = 0; m < 4; ++m) { const int row = row0 + ai * HALF + m * 16; const f32x4 a = pa[m], b = pb[m];
;                 float sq = ((a[0] + a[1]) + (a[2] + a[3])) + ((b[0] + b[1]) + (b[2] + b[3])); sq += __shfl_xor(sq, 16); sq += __shfl_xor(sq, 32);
;                 const float rs = __builtin_amdgcn_rsqf(sq * inv_k + eps);
; #pragma unroll
;                 for (int bj = 0; bj < 2; ++bj) { const f32x4 v0 = acc[ai][bj][m][0] * rs, v1 = acc[ai][bj][m][1] * rs;
;                     u32x4 w; w.x = cvt_pk_bf16(v0[0], v0[1]); w.y = cvt_pk_bf16(v0[2], v0[3]); w.z = cvt_pk_bf16(v1[0], v1[1]); w.w = cvt_pk_bf16(v1[2], v1[3]);
;                     *(u32x4*)(O + ((size_t)(u.pn * 2 + bj) * Mrows + row) * HALF + col0) = w; } }
;             asm volatile("" ::: "memory"); }
; template <class Epi, class Sched, bool ALIGN_EPI = false, bool SP2 = false>
; __device__ __forceinline__ void gemm_phase(PG8_LAS unsigned char* lds, const Gemm g, const Sched& S, const Epi& E) {
;     ...
;         if constexpr (ALIGN_EPI) { if (wr == 0) PG8_BAR; }
;         if constexpr (!Epi::AFTER_DRAIN) { E(acc, cur, wr, wc, fr, fq); S.done(cur); }
;         if (!has_next) break;
; #pragma unroll
;         for (int a = 0; a < 2; ++a)
; #pragma unroll
;             for (int b = 0; b < 2; ++b)
; #pragma unroll
;                 for (int m = 0; m < 4; ++m)
; #pragma unroll
;                     for (int n = 0; n < 2; ++n) acc[a][b][m][n] = (f32x4){0.f, 0.f, 0.f, 0.f};
;         cur = nxt; cA = nA; cB = nB; ++ui;
;         if constexpr (ALIGN_EPI) { if (wr == 1) PG8_BAR; }
	s_nop 0
	v_mov_b32_e32 v50, v96
	s_waitcnt vmcnt(6)
	v_mov_b32_e32 v51, v100
	v_mov_b32_e32 v100, v97
	v_mov_b32_e32 v52, v98
	v_mov_b32_e32 v53, v102
	v_mov_b32_e32 v102, v99
	v_pk_add_f32 v[50:51], v[50:51], v[100:101]
	v_pk_add_f32 v[52:53], v[52:53], v[102:103]
	s_nop 0
	v_pk_add_f32 v[50:51], v[50:51], v[52:53]
	s_nop 0
	v_add_f32_e32 v50, v50, v51
	ds_bpermute_b32 v51, v180, v50
	s_waitcnt lgkmcnt(0)
	v_add_f32_e32 v50, v50, v51
	ds_bpermute_b32 v51, v179, v50
	s_waitcnt lgkmcnt(0)
	v_add_f32_e32 v50, v50, v51
	v_fmamk_f32 v50, v50, 0x3a000000, v215
	v_rsq_f32_e32 v50, v50
	s_nop 0
	v_pk_mul_f32 v[46:47], v[46:47], v[50:51] op_sel_hi:[1,0]
	v_pk_mul_f32 v[52:53], v[44:45], v[50:51] op_sel_hi:[1,0]
	v_pk_mul_f32 v[44:45], v[42:43], v[50:51] op_sel_hi:[1,0]
	v_cvt_pk_bf16_f32 v42, v46, v47
	v_lshl_add_u64 v[46:47], s[34:35], 0, v[86:87]
	v_lshlrev_b64 v[46:47], 8, v[46:47]
	v_pk_mul_f32 v[48:49], v[48:49], v[50:51] op_sel_hi:[1,0]
	v_lshl_add_u64 v[46:47], v[160:161], 0, v[46:47]
	v_cvt_pk_bf16_f32 v43, v48, v49
	v_pk_mul_f32 v[38:39], v[38:39], v[50:51] op_sel_hi:[1,0]
	v_cvt_pk_bf16_f32 v44, v44, v45
	v_cvt_pk_bf16_f32 v45, v52, v53
	global_store_dwordx4 v[46:47], v[42:45], off sc1
	v_pk_mul_f32 v[40:41], v[40:41], v[50:51] op_sel_hi:[1,0]
	s_nop 0
	v_pk_mul_f32 v[42:43], v[36:37], v[50:51] op_sel_hi:[1,0]
	v_pk_mul_f32 v[36:37], v[34:35], v[50:51] op_sel_hi:[1,0]
	v_cvt_pk_bf16_f32 v34, v38, v39
	v_lshl_add_u64 v[38:39], s[36:37], 0, v[86:87]
	v_lshlrev_b64 v[38:39], 8, v[38:39]
	v_cvt_pk_bf16_f32 v35, v40, v41
	v_cvt_pk_bf16_f32 v36, v36, v37
	v_cvt_pk_bf16_f32 v37, v42, v43
	v_lshl_add_u64 v[38:39], v[160:161], 0, v[38:39]
	global_store_dwordx4 v[38:39], v[34:37], off sc1
	s_waitcnt vmcnt(7)
	s_nop 0
	v_mov_b32_e32 v34, v78
	s_waitcnt vmcnt(6)
	v_mov_b32_e32 v35, v74
	v_mov_b32_e32 v74, v79
	v_mov_b32_e32 v36, v80
	v_mov_b32_e32 v37, v76
	v_mov_b32_e32 v76, v81
	v_pk_add_f32 v[34:35], v[34:35], v[74:75]
	v_pk_add_f32 v[36:37], v[36:37], v[76:77]
	s_nop 0
	v_pk_add_f32 v[34:35], v[34:35], v[36:37]
	s_nop 0
	v_add_f32_e32 v34, v34, v35
	ds_bpermute_b32 v35, v180, v34
	s_waitcnt lgkmcnt(0)
	v_add_f32_e32 v34, v34, v35
	ds_bpermute_b32 v35, v179, v34
	s_waitcnt lgkmcnt(0)
	v_add_f32_e32 v34, v34, v35
	v_fmamk_f32 v34, v34, 0x3a000000, v215
	v_rsq_f32_e32 v34, v34
	s_nop 0
	v_pk_mul_f32 v[30:31], v[30:31], v[34:35] op_sel_hi:[1,0]
	v_pk_mul_f32 v[36:37], v[28:29], v[34:35] op_sel_hi:[1,0]
	v_pk_mul_f32 v[28:29], v[26:27], v[34:35] op_sel_hi:[1,0]
	v_cvt_pk_bf16_f32 v26, v30, v31
	v_lshl_add_u64 v[30:31], s[34:35], 0, v[84:85]
	v_lshlrev_b64 v[30:31], 8, v[30:31]
	v_pk_mul_f32 v[32:33], v[32:33], v[34:35] op_sel_hi:[1,0]
	v_lshl_add_u64 v[30:31], v[160:161], 0, v[30:31]
	v_cvt_pk_bf16_f32 v27, v32, v33
	v_pk_mul_f32 v[22:23], v[22:23], v[34:35] op_sel_hi:[1,0]
	v_cvt_pk_bf16_f32 v28, v28, v29
	v_cvt_pk_bf16_f32 v29, v36, v37
	global_store_dwordx4 v[30:31], v[26:29], off sc1
	v_pk_mul_f32 v[24:25], v[24:25], v[34:35] op_sel_hi:[1,0]
	s_nop 0
	v_pk_mul_f32 v[26:27], v[20:21], v[34:35] op_sel_hi:[1,0]
	v_pk_mul_f32 v[20:21], v[18:19], v[34:35] op_sel_hi:[1,0]
	v_cvt_pk_bf16_f32 v18, v22, v23
	v_lshl_add_u64 v[22:23], s[36:37], 0, v[84:85]
	v_lshlrev_b64 v[22:23], 8, v[22:23]
	v_cvt_pk_bf16_f32 v19, v24, v25
	v_cvt_pk_bf16_f32 v20, v20, v21
	v_cvt_pk_bf16_f32 v21, v26, v27
	v_lshl_add_u64 v[22:23], v[160:161], 0, v[22:23]
	global_store_dwordx4 v[22:23], v[18:21], off sc1
	s_waitcnt vmcnt(7)
	s_nop 0
	v_mov_b32_e32 v18, v70
	s_waitcnt vmcnt(6)
	v_mov_b32_e32 v19, v66
	v_mov_b32_e32 v66, v71
	v_mov_b32_e32 v20, v72
	v_mov_b32_e32 v21, v68
	v_mov_b32_e32 v68, v73
	v_pk_add_f32 v[18:19], v[18:19], v[66:67]
	v_pk_add_f32 v[20:21], v[20:21], v[68:69]
	s_nop 0
	v_pk_add_f32 v[18:19], v[18:19], v[20:21]
	s_nop 0
	v_add_f32_e32 v18, v18, v19
	ds_bpermute_b32 v19, v180, v18
	s_waitcnt lgkmcnt(0)
	v_add_f32_e32 v18, v18, v19
	ds_bpermute_b32 v19, v179, v18
	s_waitcnt lgkmcnt(0)
	v_add_f32_e32 v18, v18, v19
	v_fmamk_f32 v18, v18, 0x3a000000, v215
	v_rsq_f32_e32 v18, v18
	s_nop 0
	v_pk_mul_f32 v[14:15], v[14:15], v[18:19] op_sel_hi:[1,0]
	v_pk_mul_f32 v[20:21], v[12:13], v[18:19] op_sel_hi:[1,0]
	v_pk_mul_f32 v[12:13], v[10:11], v[18:19] op_sel_hi:[1,0]
	v_cvt_pk_bf16_f32 v10, v14, v15
	v_lshl_add_u64 v[14:15], s[34:35], 0, v[82:83]
	v_lshlrev_b64 v[14:15], 8, v[14:15]
	v_pk_mul_f32 v[16:17], v[16:17], v[18:19] op_sel_hi:[1,0]
	v_lshl_add_u64 v[14:15], v[160:161], 0, v[14:15]
	v_cvt_pk_bf16_f32 v11, v16, v17
	v_pk_mul_f32 v[6:7], v[6:7], v[18:19] op_sel_hi:[1,0]
	v_cvt_pk_bf16_f32 v12, v12, v13
	v_cvt_pk_bf16_f32 v13, v20, v21
	global_store_dwordx4 v[14:15], v[10:13], off sc1
	v_pk_mul_f32 v[8:9], v[8:9], v[18:19] op_sel_hi:[1,0]
	s_mov_b64 s[34:35], -1
	v_pk_mul_f32 v[10:11], v[4:5], v[18:19] op_sel_hi:[1,0]
	v_pk_mul_f32 v[4:5], v[2:3], v[18:19] op_sel_hi:[1,0]
	v_cvt_pk_bf16_f32 v2, v6, v7
	v_lshl_add_u64 v[6:7], s[36:37], 0, v[82:83]
	v_lshlrev_b64 v[6:7], 8, v[6:7]
	v_lshl_add_u64 v[6:7], v[160:161], 0, v[6:7]
	v_cvt_pk_bf16_f32 v3, v8, v9
	v_cvt_pk_bf16_f32 v4, v4, v5
	v_cvt_pk_bf16_f32 v5, v10, v11
	global_store_dwordx4 v[6:7], v[2:5], off sc1
	s_cbranch_vccnz .LBB0_210
	s_andn2_b64 vcc, exec, s[0:1]
	s_cbranch_vccnz .LBB0_209
	s_barrier
	s_branch .LBB0_209

; #define LAS __attribute__((address_space(3)))
; #define LDS_WAIT() asm volatile("s_waitcnt lgkmcnt(0)" ::: "memory")
; __device__ __forceinline__ unsigned pk2(float lo, float hi) { unsigned r; asm("v_cvt_pk_bf16_f32 %0, %1, %2" : "=v"(r) : "v"(lo), "v"(hi)); return r; }
; __device__ __forceinline__ void p0_transpose_item(const float* W, int K, int N, bf16_t* WT, LAS float* scr, int item, int lane, const float* kscale) {
;     const int nblk = N / 32, kb = item / nblk, nb = item % nblk, k0 = 64 * kb, n0 = 32 * nb;
; #pragma unroll 8
;     for (int i = 0; i < 32; ++i) { const int kk = 2 * i + (lane >> 5); scr[kk * 33 + (lane & 31)] = W[(size_t)(k0 + kk) * N + n0 + (lane & 31)] * (kscale ? kscale[k0 + kk] : 1.0f); }
;     LDS_WAIT(); asm volatile("" ::: "memory");
;     const int c = lane & 7;
; #pragma unroll
;     for (int j = 0; j < 4; ++j) { const int n = (lane >> 3) + 8 * j; const LAS float* s = scr + (8 * c) * 33 + n;
;         v4u o; o.x = pk2(s[0 * 33], s[1 * 33]); o.y = pk2(s[2 * 33], s[3 * 33]); o.z = pk2(s[4 * 33], s[5 * 33]); o.w = pk2(s[6 * 33], s[7 * 33]);
;         *(v4u*)(WT + (size_t)(n0 + n) * K + k0 + 8 * c) = o; }
;     LDS_WAIT(); asm volatile("" ::: "memory");
; }
.LBB0_224:
	s_mul_i32 s1, s2, 0x1a00000
	s_waitcnt lgkmcnt(0)
	s_mul_hi_i32 s0, s2, 0x1a00000
	s_add_u32 s2, s94, s1
	s_addc_u32 s3, s95, s0
	s_lshl_b64 s[0:1], s[20:21], 1
	ds_read2_b32 v[18:19], v9 offset0:33 offset1:41
	ds_read2_b32 v[20:21], v9 offset1:8
	ds_read2_b32 v[22:23], v9 offset0:66 offset1:74
	ds_read2_b32 v[24:25], v9 offset0:99 offset1:107
	ds_read2_b32 v[26:27], v9 offset0:132 offset1:140
	ds_read2_b32 v[28:29], v9 offset0:165 offset1:173
	ds_read2_b32 v[30:31], v9 offset0:198 offset1:206
	ds_read2_b32 v[32:33], v9 offset0:231 offset1:239
	s_add_u32 s0, s2, s0
	v_or_b32_e32 v48, s16, v7
	s_addc_u32 s1, s3, s1
	v_lshlrev_b32_e32 v0, 1, v8
	v_ashrrev_i32_e32 v49, 31, v48
	v_lshl_add_u64 v[34:35], s[0:1], 0, v[0:1]
	v_lshlrev_b64 v[48:49], 12, v[48:49]
	s_waitcnt lgkmcnt(6)
	v_cvt_pk_bf16_f32 v14, v20, v18
	v_lshl_add_u64 v[48:49], v[34:35], 0, v[48:49]
	v_or_b32_e32 v18, s16, v36
	s_waitcnt lgkmcnt(4)
	v_cvt_pk_bf16_f32 v15, v22, v24
	s_waitcnt lgkmcnt(2)
	v_cvt_pk_bf16_f32 v16, v26, v28
	s_waitcnt lgkmcnt(0)
	v_cvt_pk_bf16_f32 v17, v30, v32
	global_store_dwordx4 v[48:49], v[14:17], off sc1
	s_nop 1
	v_cvt_pk_bf16_f32 v14, v21, v19
	v_ashrrev_i32_e32 v19, 31, v18
	v_lshlrev_b64 v[18:19], 12, v[18:19]
	v_cvt_pk_bf16_f32 v15, v23, v25
	v_cvt_pk_bf16_f32 v16, v27, v29
	v_cvt_pk_bf16_f32 v17, v31, v33
	v_lshl_add_u64 v[18:19], v[34:35], 0, v[18:19]
	ds_read2_b32 v[20:21], v9 offset0:16 offset1:24
	ds_read2_b32 v[22:23], v9 offset0:49 offset1:57
	ds_read2_b32 v[24:25], v9 offset0:82 offset1:90
	ds_read2_b32 v[26:27], v9 offset0:115 offset1:123
	ds_read2_b32 v[28:29], v9 offset0:148 offset1:156
	ds_read2_b32 v[30:31], v9 offset0:181 offset1:189
	ds_read2_b32 v[32:33], v9 offset0:214 offset1:222
	ds_read2_b32 v[48:49], v9 offset0:247 offset1:255
	global_store_dwordx4 v[18:19], v[14:17], off sc1
	v_or_b32_e32 v18, s16, v37
	v_ashrrev_i32_e32 v19, 31, v18
	v_lshlrev_b64 v[18:19], 12, v[18:19]
	v_lshl_add_u64 v[18:19], v[34:35], 0, v[18:19]
	s_waitcnt lgkmcnt(6)
	v_cvt_pk_bf16_f32 v14, v20, v22
	s_waitcnt lgkmcnt(4)
	v_cvt_pk_bf16_f32 v15, v24, v26
	s_waitcnt lgkmcnt(2)
	v_cvt_pk_bf16_f32 v16, v28, v30
	s_waitcnt lgkmcnt(0)
	v_cvt_pk_bf16_f32 v17, v32, v48
	global_store_dwordx4 v[18:19], v[14:17], off sc1
	v_or_b32_e32 v18, s16, v38
	v_ashrrev_i32_e32 v19, 31, v18
	v_lshlrev_b64 v[18:19], 12, v[18:19]
	v_lshl_add_u64 v[18:19], v[34:35], 0, v[18:19]
	v_cvt_pk_bf16_f32 v14, v21, v23
	v_cvt_pk_bf16_f32 v15, v25, v27
	v_cvt_pk_bf16_f32 v16, v29, v31
	v_cvt_pk_bf16_f32 v17, v33, v49
	global_store_dwordx4 v[18:19], v[14:17], off sc1
	s_waitcnt lgkmcnt(0)

; __device__ __forceinline__ void p0_transpose_item(const float* W, int K, int N, bf16_t* WT, LAS float* scr, int item, int lane, const float* kscale) {
;     const int nblk = N / 32, kb = item / nblk, nb = item % nblk, k0 = 64 * kb, n0 = 32 * nb;
; #pragma unroll 8
;     for (int i = 0; i < 32; ++i) { const int kk = 2 * i + (lane >> 5); scr[kk * 33 + (lane & 31)] = W[(size_t)(k0 + kk) * N + n0 + (lane & 31)] * (kscale ? kscale[k0 + kk] : 1.0f); }
; __global__ void __launch_bounds__(512, 2) mk_fwd(Params p) {
;     ...
;                 const int l = it / IL, r = it % IL;
;                 if (r < I1) p0_transpose_item(p.w_in + (size_t)l * DM * DIN, DM, DIN, W1T + (size_t)l * DIN * DM, scr, r, lane, p.norm_w + (size_t)l * DM);
;                 else p0_transpose_item(p.w_out + (size_t)l * DM * DM, DM, DM, W2T + (size_t)l * DM * DM, scr, r - I1, lane, nullptr);
.LBB0_226:
	s_mul_hi_i32 s0, s4, 0x78787879
	s_lshr_b32 s1, s0, 31
	s_ashr_i32 s0, s0, 12
	s_add_i32 s2, s0, s1
	s_mul_i32 s0, s2, 0x2200
	s_sub_i32 s5, s4, s0
	s_ashr_i32 s3, s2, 31
	s_cmpk_gt_i32 s5, 0x19ff
	s_mov_b64 s[0:1], -1
	s_cbranch_scc0 .LBB0_230
	s_lshl_b64 s[0:1], s[2:3], 22
	s_lshl_b64 s[6:7], s[2:3], 24
	s_add_u32 s8, s66, s6
	s_addc_u32 s9, s67, s7
	s_add_i32 s6, s5, 0xe600
	s_and_b32 s7, s6, 0xffc0
	s_lshl_b32 s6, s5, 5
	s_and_b32 s6, s6, 0x7e0
	s_lshl_b32 s10, s6, 2
	s_add_u32 s8, s8, s10
	s_addc_u32 s9, s9, 0
	v_mov_b32_e32 v13, v1
	v_lshl_add_u64 v[14:15], s[8:9], 0, v[12:13]
	v_or_b32_e32 v5, s7, v3
	v_or_b32_e32 v16, s7, v4
	s_lshl_b32 s10, s7, 13
	s_add_u32 s8, s8, s10
	s_addc_u32 s9, s9, 0
	v_lshlrev_b32_e32 v47, 13, v4
	v_add_u32_e32 v47, v47, v12
	global_load_dword v100, v47, s[8:9]
	s_add_u32 s8, s8, 0x4000
	s_addc_u32 s9, s9, 0
	global_load_dword v101, v47, s[8:9]
	s_add_u32 s8, s8, 0x4000
	s_addc_u32 s9, s9, 0
	global_load_dword v102, v47, s[8:9]
	s_add_u32 s8, s8, 0x4000
	s_addc_u32 s9, s9, 0
	global_load_dword v103, v47, s[8:9]
	s_add_u32 s8, s8, 0x4000
	s_addc_u32 s9, s9, 0
	global_load_dword v104, v47, s[8:9]
	s_add_u32 s8, s8, 0x4000
	s_addc_u32 s9, s9, 0
	global_load_dword v105, v47, s[8:9]
	s_add_u32 s8, s8, 0x4000
	s_addc_u32 s9, s9, 0
	global_load_dword v106, v47, s[8:9]
	s_add_u32 s8, s8, 0x4000
	s_addc_u32 s9, s9, 0
	global_load_dword v107, v47, s[8:9]
	s_add_u32 s8, s8, 0x4000
	s_addc_u32 s9, s9, 0
	global_load_dword v108, v47, s[8:9]
	s_add_u32 s8, s8, 0x4000
	s_addc_u32 s9, s9, 0
	global_load_dword v109, v47, s[8:9]
	s_add_u32 s8, s8, 0x4000
	s_addc_u32 s9, s9, 0
	global_load_dword v110, v47, s[8:9]
	s_add_u32 s8, s8, 0x4000
	s_addc_u32 s9, s9, 0
	global_load_dword v111, v47, s[8:9]
	s_add_u32 s8, s8, 0x4000
	s_addc_u32 s9, s9, 0
	global_load_dword v112, v47, s[8:9]
	s_add_u32 s8, s8, 0x4000
	s_addc_u32 s9, s9, 0
	global_load_dword v113, v47, s[8:9]
	s_add_u32 s8, s8, 0x4000
	s_addc_u32 s9, s9, 0
	global_load_dword v114, v47, s[8:9]
	s_add_u32 s8, s8, 0x4000
	s_addc_u32 s9, s9, 0
	global_load_dword v115, v47, s[8:9]
	s_add_u32 s8, s8, 0x4000
	s_addc_u32 s9, s9, 0
	global_load_dword v116, v47, s[8:9]
	s_add_u32 s8, s8, 0x4000
	s_addc_u32 s9, s9, 0
	global_load_dword v117, v47, s[8:9]
	s_add_u32 s8, s8, 0x4000
	s_addc_u32 s9, s9, 0
	global_load_dword v118, v47, s[8:9]
	s_add_u32 s8, s8, 0x4000
	s_addc_u32 s9, s9, 0
	global_load_dword v119, v47, s[8:9]
	s_add_u32 s8, s8, 0x4000
	s_addc_u32 s9, s9, 0
	global_load_dword v120, v47, s[8:9]
	s_add_u32 s8, s8, 0x4000
	s_addc_u32 s9, s9, 0
	global_load_dword v121, v47, s[8:9]
	s_add_u32 s8, s8, 0x4000
	s_addc_u32 s9, s9, 0
	global_load_dword v122, v47, s[8:9]
	s_add_u32 s8, s8, 0x4000
	s_addc_u32 s9, s9, 0
	global_load_dword v123, v47, s[8:9]
	s_add_u32 s8, s8, 0x4000
	s_addc_u32 s9, s9, 0
	global_load_dword v124, v47, s[8:9]
	s_add_u32 s8, s8, 0x4000
	s_addc_u32 s9, s9, 0
	global_load_dword v125, v47, s[8:9]
	s_add_u32 s8, s8, 0x4000
	s_addc_u32 s9, s9, 0
	global_load_dword v126, v47, s[8:9]
	s_add_u32 s8, s8, 0x4000
	s_addc_u32 s9, s9, 0
	global_load_dword v127, v47, s[8:9]
	s_add_u32 s8, s8, 0x4000
	s_addc_u32 s9, s9, 0
	global_load_dword v128, v47, s[8:9]
	s_add_u32 s8, s8, 0x4000
	s_addc_u32 s9, s9, 0
	global_load_dword v129, v47, s[8:9]
	s_add_u32 s8, s8, 0x4000
	s_addc_u32 s9, s9, 0
	global_load_dword v130, v47, s[8:9]
	s_add_u32 s8, s8, 0x4000
	s_addc_u32 s9, s9, 0
	global_load_dword v131, v47, s[8:9]
	s_waitcnt vmcnt(31)
	ds_write_b32 v39, v100 offset:0
	s_waitcnt vmcnt(30)
	ds_write_b32 v39, v101 offset:264
	s_waitcnt vmcnt(29)
	ds_write_b32 v39, v102 offset:528
	s_waitcnt vmcnt(28)
	ds_write_b32 v39, v103 offset:792
	s_waitcnt vmcnt(27)
	ds_write_b32 v39, v104 offset:1056
	s_waitcnt vmcnt(26)
	ds_write_b32 v39, v105 offset:1320
	s_waitcnt vmcnt(25)
; #define LAS __attribute__((address_space(3)))
; #define LDS_WAIT() asm volatile("s_waitcnt lgkmcnt(0)" ::: "memory")
; __device__ __forceinline__ unsigned pk2(float lo, float hi) { unsigned r; asm("v_cvt_pk_bf16_f32 %0, %1, %2" : "=v"(r) : "v"(lo), "v"(hi)); return r; }
; __device__ __forceinline__ void p0_transpose_item(const float* W, int K, int N, bf16_t* WT, LAS float* scr, int item, int lane, const float* kscale) {
;     ...
;     for (int i = 0; i < 32; ++i) { const int kk = 2 * i + (lane >> 5); scr[kk * 33 + (lane & 31)] = W[(size_t)(k0 + kk) * N + n0 + (lane & 31)] * (kscale ? kscale[k0 + kk] : 1.0f); }
;     LDS_WAIT(); asm volatile("" ::: "memory");
;     const int c = lane & 7;
; #pragma unroll
;     for (int j = 0; j < 4; ++j) { const int n = (lane >> 3) + 8 * j; const LAS float* s = scr + (8 * c) * 33 + n;
;         v4u o; o.x = pk2(s[0 * 33], s[1 * 33]); o.y = pk2(s[2 * 33], s[3 * 33]); o.z = pk2(s[4 * 33], s[5 * 33]); o.w = pk2(s[6 * 33], s[7 * 33]);
;         *(v4u*)(WT + (size_t)(n0 + n) * K + k0 + 8 * c) = o; }
;     LDS_WAIT(); asm volatile("" ::: "memory");
	ds_write_b32 v39, v106 offset:1584
	s_waitcnt vmcnt(24)
	ds_write_b32 v39, v107 offset:1848
	s_waitcnt vmcnt(23)
	ds_write_b32 v39, v108 offset:2112
	s_waitcnt vmcnt(22)
	ds_write_b32 v39, v109 offset:2376
	s_waitcnt vmcnt(21)
	ds_write_b32 v39, v110 offset:2640
	s_waitcnt vmcnt(20)
	ds_write_b32 v39, v111 offset:2904
	s_waitcnt vmcnt(19)
	ds_write_b32 v39, v112 offset:3168
	s_waitcnt vmcnt(18)
	ds_write_b32 v39, v113 offset:3432
	s_waitcnt vmcnt(17)
	ds_write_b32 v39, v114 offset:3696
	s_waitcnt vmcnt(16)
	ds_write_b32 v39, v115 offset:3960
	s_waitcnt vmcnt(15)
	ds_write_b32 v39, v116 offset:4224
	s_waitcnt vmcnt(14)
	ds_write_b32 v39, v117 offset:4488
	s_waitcnt vmcnt(13)
	ds_write_b32 v39, v118 offset:4752
	s_waitcnt vmcnt(12)
	ds_write_b32 v39, v119 offset:5016
	s_waitcnt vmcnt(11)
	ds_write_b32 v39, v120 offset:5280
	s_waitcnt vmcnt(10)
	ds_write_b32 v39, v121 offset:5544
	s_waitcnt vmcnt(9)
	ds_write_b32 v39, v122 offset:5808
	s_waitcnt vmcnt(8)
	ds_write_b32 v39, v123 offset:6072
	s_waitcnt vmcnt(7)
	ds_write_b32 v39, v124 offset:6336
	s_waitcnt vmcnt(6)
	ds_write_b32 v39, v125 offset:6600
	s_waitcnt vmcnt(5)
	ds_write_b32 v39, v126 offset:6864
	s_waitcnt vmcnt(4)
	ds_write_b32 v39, v127 offset:7128
	s_waitcnt vmcnt(3)
	ds_write_b32 v39, v128 offset:7392
	s_waitcnt vmcnt(2)
	ds_write_b32 v39, v129 offset:7656
	s_waitcnt vmcnt(1)
	ds_write_b32 v39, v130 offset:7920
	s_waitcnt vmcnt(0)
	ds_write_b32 v39, v131 offset:8184
	s_lshl_b64 s[0:1], s[0:1], 1
	s_add_u32 s0, s96, s0
	s_waitcnt lgkmcnt(0)
	s_addc_u32 s1, s97, s1
	s_lshl_b32 s7, s7, 1
	s_add_u32 s0, s0, s7
	ds_read2_b32 v[18:19], v9 offset0:33 offset1:41
	ds_read2_b32 v[20:21], v9 offset1:8
	ds_read2_b32 v[22:23], v9 offset0:66 offset1:74
	ds_read2_b32 v[24:25], v9 offset0:99 offset1:107
	ds_read2_b32 v[26:27], v9 offset0:132 offset1:140
	ds_read2_b32 v[28:29], v9 offset0:165 offset1:173
	ds_read2_b32 v[30:31], v9 offset0:198 offset1:206
	ds_read2_b32 v[32:33], v9 offset0:231 offset1:239
	s_addc_u32 s1, s1, 0
	v_lshlrev_b32_e32 v0, 1, v8
	v_lshl_add_u64 v[34:35], s[0:1], 0, v[0:1]
	v_or_b32_e32 v0, s6, v7
	v_lshlrev_b32_e32 v0, 12, v0
	v_lshl_add_u64 v[48:49], v[34:35], 0, v[0:1]
	s_waitcnt lgkmcnt(6)
	v_cvt_pk_bf16_f32 v14, v20, v18
	s_waitcnt lgkmcnt(4)
	v_cvt_pk_bf16_f32 v15, v22, v24
	s_waitcnt lgkmcnt(2)
	v_cvt_pk_bf16_f32 v16, v26, v28
	s_waitcnt lgkmcnt(0)
	v_cvt_pk_bf16_f32 v17, v30, v32
	global_store_dwordx4 v[48:49], v[14:17], off sc1
	v_or_b32_e32 v0, s6, v36
	v_lshlrev_b32_e32 v0, 12, v0
	v_cvt_pk_bf16_f32 v14, v21, v19
	v_cvt_pk_bf16_f32 v15, v23, v25
	v_cvt_pk_bf16_f32 v16, v27, v29
	v_cvt_pk_bf16_f32 v17, v31, v33
	ds_read2_b32 v[20:21], v9 offset0:16 offset1:24
	ds_read2_b32 v[22:23], v9 offset0:49 offset1:57
	ds_read2_b32 v[24:25], v9 offset0:82 offset1:90
	ds_read2_b32 v[26:27], v9 offset0:115 offset1:123
	ds_read2_b32 v[28:29], v9 offset0:148 offset1:156
	ds_read2_b32 v[30:31], v9 offset0:181 offset1:189
	ds_read2_b32 v[32:33], v9 offset0:214 offset1:222
	ds_read2_b32 v[48:49], v9 offset0:247 offset1:255
	v_lshl_add_u64 v[18:19], v[34:35], 0, v[0:1]
	v_or_b32_e32 v0, s6, v37
	v_lshlrev_b32_e32 v0, 12, v0
	global_store_dwordx4 v[18:19], v[14:17], off sc1
	v_lshl_add_u64 v[18:19], v[34:35], 0, v[0:1]
	v_or_b32_e32 v0, s6, v38
	v_lshlrev_b32_e32 v0, 12, v0
	s_waitcnt lgkmcnt(6)
	v_cvt_pk_bf16_f32 v14, v20, v22
	s_waitcnt lgkmcnt(4)
	v_cvt_pk_bf16_f32 v15, v24, v26
	s_waitcnt lgkmcnt(2)
	v_cvt_pk_bf16_f32 v16, v28, v30
	s_waitcnt lgkmcnt(0)
	v_cvt_pk_bf16_f32 v17, v32, v48
	global_store_dwordx4 v[18:19], v[14:17], off sc1
	v_lshl_add_u64 v[18:19], v[34:35], 0, v[0:1]
	s_nop 0
	v_cvt_pk_bf16_f32 v14, v21, v23
	v_cvt_pk_bf16_f32 v15, v25, v27
	v_cvt_pk_bf16_f32 v16, v29, v31
	v_cvt_pk_bf16_f32 v17, v33, v49
	global_store_dwordx4 v[18:19], v[14:17], off sc1
	s_waitcnt lgkmcnt(0)
	s_branch .LBB0_225

; __device__ __forceinline__ unsigned pk2(float lo, float hi) { unsigned r; asm("v_cvt_pk_bf16_f32 %0, %1, %2" : "=v"(r) : "v"(lo), "v"(hi)); return r; }
; __device__ __forceinline__ float bflo(unsigned w) { return __uint_as_float(w << 16); }
; __device__ __forceinline__ float bfhi(unsigned w) { return __uint_as_float(w & 0xffff0000u); }
; __global__ void __launch_bounds__(512, 2) mk_fwd(Params p) {
;     ...
;             for (int m = gw; m < M; m += NGW) {
;                 const f32x4* xr = (const f32x4*)(p.x + (size_t)m * DM) + lane; v2u* o8 = (v2u*)(XB + (size_t)m * DM) + lane; float sq = 0.f;
; #pragma unroll
;                 for (int j = 0; j < 8; ++j) { const f32x4 v = xr[64 * j]; v2u w; w.x = pk2(v.x, v.y); w.y = pk2(v.z, v.w); o8[64 * j] = w;
;                     const float r0 = bflo(w.x), r1 = bfhi(w.x), r2 = bflo(w.y), r3 = bfhi(w.y); sq += (r0 * r0 + r1 * r1) + (r2 * r2 + r3 * r3); }
;                 sq = wave_sum(sq); if (lane < 32) ROWSQ[(size_t)m * 32 + lane] = (lane == 0) ? sq : 0.f;
;             }
.LBB0_252:
	v_add_co_u32_e32 v12, vcc, 0xfffff000, v6
	s_nop 1
	v_addc_co_u32_e32 v13, vcc, -1, v7, vcc
	s_waitcnt lgkmcnt(0)
	global_load_dwordx4 v[8:11], v[12:13], off offset:-3072
	s_waitcnt vmcnt(0)
	v_cvt_pk_bf16_f32 v14, v8, v9
	v_cvt_pk_bf16_f32 v15, v10, v11
	global_store_dwordx2 v[2:3], v[14:15], off offset:-2048 sc1
	v_lshlrev_b32_e32 v26, 16, v14
	v_and_b32_e32 v14, 0xffff0000, v14
	v_lshlrev_b32_e32 v27, 16, v15
	v_and_b32_e32 v15, 0xffff0000, v15
	v_mul_f32_e32 v14, v14, v14
	v_mul_f32_e32 v15, v15, v15
	global_load_dwordx4 v[8:11], v[12:13], off offset:-2048
	s_waitcnt vmcnt(0)
	v_cvt_pk_bf16_f32 v16, v8, v9
	v_cvt_pk_bf16_f32 v17, v10, v11
	v_fmac_f32_e32 v14, v26, v26
	v_fmac_f32_e32 v15, v27, v27
	global_store_dwordx2 v[2:3], v[16:17], off offset:-1536 sc1
	v_add_f32_e32 v14, v14, v15
	v_lshlrev_b32_e32 v15, 16, v16
	v_and_b32_e32 v16, 0xffff0000, v16
	v_lshlrev_b32_e32 v26, 16, v17
	v_and_b32_e32 v17, 0xffff0000, v17
	v_mul_f32_e32 v16, v16, v16
	v_mul_f32_e32 v17, v17, v17
	v_fmac_f32_e32 v16, v15, v15
	v_fmac_f32_e32 v17, v26, v26
	global_load_dwordx4 v[8:11], v[12:13], off offset:-1024
	s_waitcnt vmcnt(0)
	v_cvt_pk_bf16_f32 v12, v8, v9
	v_cvt_pk_bf16_f32 v13, v10, v11
	v_add_f32_e32 v15, v16, v17
	global_store_dwordx2 v[2:3], v[12:13], off offset:-1024 sc1
	v_add_f32_e32 v14, v14, v15
	v_lshlrev_b32_e32 v15, 16, v12
	v_and_b32_e32 v12, 0xffff0000, v12
	v_lshlrev_b32_e32 v16, 16, v13
	v_and_b32_e32 v13, 0xffff0000, v13
	v_mul_f32_e32 v12, v12, v12
	v_mul_f32_e32 v13, v13, v13
	v_fmac_f32_e32 v12, v15, v15
	v_fmac_f32_e32 v13, v16, v16
	v_add_f32_e32 v12, v12, v13
	global_load_dwordx4 v[8:11], v[6:7], off offset:-4096
	s_waitcnt vmcnt(0)
	v_cvt_pk_bf16_f32 v18, v8, v9
	v_cvt_pk_bf16_f32 v19, v10, v11
	v_add_f32_e32 v12, v14, v12
	v_and_b32_e32 v14, 0xffff0000, v18
	v_and_b32_e32 v16, 0xffff0000, v19
	v_lshlrev_b32_e32 v13, 16, v18
	v_lshlrev_b32_e32 v15, 16, v19
	v_mul_f32_e32 v14, v14, v14
	v_mul_f32_e32 v16, v16, v16
	global_store_dwordx2 v[2:3], v[18:19], off offset:-512 sc1
	v_fmac_f32_e32 v14, v13, v13
	v_fmac_f32_e32 v16, v15, v15
	global_load_dwordx4 v[8:11], v[6:7], off offset:-3072
	s_waitcnt vmcnt(0)
	v_cvt_pk_bf16_f32 v20, v8, v9
	v_cvt_pk_bf16_f32 v21, v10, v11
	v_add_f32_e32 v13, v14, v16
	v_and_b32_e32 v14, 0xffff0000, v20
	v_and_b32_e32 v16, 0xffff0000, v21
	v_add_f32_e32 v12, v12, v13
	v_lshlrev_b32_e32 v13, 16, v20
	v_lshlrev_b32_e32 v15, 16, v21
	v_mul_f32_e32 v14, v14, v14
	v_mul_f32_e32 v16, v16, v16
	global_store_dwordx2 v[2:3], v[20:21], off sc1
	v_fmac_f32_e32 v14, v13, v13
	v_fmac_f32_e32 v16, v15, v15
	global_load_dwordx4 v[8:11], v[6:7], off offset:-2048
	s_waitcnt vmcnt(0)
	v_cvt_pk_bf16_f32 v22, v8, v9
	v_cvt_pk_bf16_f32 v23, v10, v11
	v_add_f32_e32 v13, v14, v16
	v_and_b32_e32 v14, 0xffff0000, v22
	v_and_b32_e32 v16, 0xffff0000, v23
	v_add_f32_e32 v12, v12, v13
	v_lshlrev_b32_e32 v13, 16, v22
	v_lshlrev_b32_e32 v15, 16, v23
	v_mul_f32_e32 v14, v14, v14
	v_mul_f32_e32 v16, v16, v16
	global_store_dwordx2 v[2:3], v[22:23], off offset:512 sc1
	v_fmac_f32_e32 v14, v13, v13
	v_fmac_f32_e32 v16, v15, v15
	global_load_dwordx4 v[8:11], v[6:7], off offset:-1024
	s_waitcnt vmcnt(0)
	v_cvt_pk_bf16_f32 v24, v8, v9
	v_cvt_pk_bf16_f32 v25, v10, v11
	v_add_f32_e32 v13, v14, v16
	v_and_b32_e32 v14, 0xffff0000, v24
	v_and_b32_e32 v16, 0xffff0000, v25
	v_add_f32_e32 v12, v12, v13
	v_lshlrev_b32_e32 v13, 16, v24
	v_lshlrev_b32_e32 v15, 16, v25
	v_mul_f32_e32 v14, v14, v14
	v_mul_f32_e32 v16, v16, v16
	global_store_dwordx2 v[2:3], v[24:25], off offset:1024 sc1
	v_fmac_f32_e32 v14, v13, v13
	v_fmac_f32_e32 v16, v15, v15
	global_load_dwordx4 v[8:11], v[6:7], off
	v_add_f32_e32 v13, v14, v16
	v_add_f32_e32 v14, v12, v13
	s_waitcnt vmcnt(0)
	v_cvt_pk_bf16_f32 v12, v8, v9
	v_cvt_pk_bf16_f32 v13, v10, v11
	v_cmp_lt_i32_e32 vcc, v220, v219
	v_and_b32_e32 v9, 0xffff0000, v12
	v_and_b32_e32 v11, 0xffff0000, v13
	v_lshlrev_b32_e32 v8, 16, v12
	v_lshlrev_b32_e32 v10, 16, v13
	v_mul_f32_e32 v9, v9, v9
	v_mul_f32_e32 v11, v11, v11
	v_fmac_f32_e32 v9, v8, v8
	v_fmac_f32_e32 v11, v10, v10
	v_cndmask_b32_e32 v0, v218, v220, vcc
	v_add_f32_e32 v8, v9, v11
	v_lshlrev_b32_e32 v0, 2, v0
	v_add_f32_e32 v8, v14, v8
	ds_bpermute_b32 v0, v0, v8
	v_cmp_lt_i32_e32 vcc, v221, v219
	global_store_dwordx2 v[2:3], v[12:13], off offset:1536 sc1
	s_waitcnt lgkmcnt(0)
	v_add_f32_e32 v0, v8, v0
	v_cndmask_b32_e32 v9, v218, v221, vcc
	v_lshlrev_b32_e32 v9, 2, v9
	ds_bpermute_b32 v8, v9, v0
	v_cmp_lt_i32_e32 vcc, v222, v219
	s_waitcnt lgkmcnt(0)
	v_add_f32_e32 v0, v0, v8
	v_cndmask_b32_e32 v9, v218, v222, vcc
	v_lshlrev_b32_e32 v9, 2, v9
	ds_bpermute_b32 v8, v9, v0
	v_cmp_lt_i32_e32 vcc, v223, v219
	s_waitcnt lgkmcnt(0)
	v_add_f32_e32 v0, v0, v8
	v_cndmask_b32_e32 v9, v218, v223, vcc
	v_lshlrev_b32_e32 v9, 2, v9
	ds_bpermute_b32 v8, v9, v0
	v_cmp_lt_i32_e32 vcc, v224, v219
	s_waitcnt lgkmcnt(0)
	v_add_f32_e32 v0, v0, v8
	v_cndmask_b32_e32 v9, v218, v224, vcc
	v_lshlrev_b32_e32 v9, 2, v9
	ds_bpermute_b32 v8, v9, v0
	v_cmp_lt_i32_e32 vcc, v225, v219
	s_waitcnt lgkmcnt(0)
	v_add_f32_e32 v0, v0, v8
	v_cndmask_b32_e32 v9, v218, v225, vcc
	v_lshlrev_b32_e32 v8, 2, v9
	ds_bpermute_b32 v8, v8, v0
	s_and_saveexec_b64 s[18:19], s[38:39]
	s_cbranch_execz .LBB0_251
	s_waitcnt lgkmcnt(0)
	v_add_f32_e32 v0, v0, v8
	v_cndmask_b32_e64 v0, 0, v0, s[40:41]
	global_store_dword v[4:5], v0, off sc1
	s_branch .LBB0_251
